# GEMM K-loops: first K-iteration after an epilogue peeled with its first two DMA waits relaxed vmcnt(8)->vmcnt(24) (no stall on the previous tile's store drain)
# baseline (speedup 1.0000x reference)
.LBB0_257:
	s_add_u32 s10, s94, 0x12800000
	s_addc_u32 s11, s95, 0
	s_add_u32 s12, s94, 0x14800000
	s_addc_u32 s13, s95, 0
	s_add_u32 s14, s94, 0x16800000
	s_addc_u32 s15, s95, 0
	s_add_u32 s16, s94, 0x1a800000
	s_addc_u32 s17, s95, 0
	s_add_u32 s18, s94, 0x26800000
	s_addc_u32 s19, s95, 0
	v_writelane_b32 v238, s18, 6
	s_mov_b64 s[26:27], 0x80
	v_lshl_add_u64 v[6:7], v[6:7], 0, s[26:27]
	v_writelane_b32 v238, s19, 7
	s_add_u32 s18, s94, 0x2a800000
	s_addc_u32 s19, s95, 0
	s_add_u32 s22, s94, 0x2e800000
	s_addc_u32 s23, s95, 0
	s_add_u32 s24, s94, 0x100000
	s_addc_u32 s25, s95, 0
	s_and_b32 s20, s30, 3
	s_add_i32 m0, s49, 0x18000
	s_lshl_b32 s21, s29, 13
	s_lshl_b32 s31, s20, 5
	s_lshl_b32 s36, s20, 12
	s_waitcnt vmcnt(2)
	s_barrier
	global_load_lds_dwordx4 v[6:7], off
	v_lshl_add_u64 v[4:5], v[4:5], 0, s[26:27]
	s_add_i32 m0, s49, 0x1a000
	s_add_i32 s68, s49, 0x8000
	s_add_i32 s69, s49, 0xa000
	global_load_lds_dwordx4 v[4:5], off
	v_lshl_add_u64 v[2:3], v[2:3], 0, s[26:27]
	s_mov_b32 m0, s68
	s_add_u32 s34, s54, 0x40080
	global_load_lds_dwordx4 v[2:3], off
	v_lshl_add_u64 v[0:1], v[0:1], 0, s[26:27]
	s_mov_b32 m0, s69
	s_addc_u32 s35, s55, 0
	global_load_lds_dwordx4 v[0:1], off
	s_add_i32 m0, s49, 0x1c000
	v_lshl_add_u64 v[0:1], s[34:35], 0, v[194:195]
	global_load_lds_dwordx4 v[0:1], off
	v_lshl_add_u64 v[0:1], s[34:35], 0, v[198:199]
	s_add_i32 m0, s49, 0x1e000
	s_cmpk_lt_u32 s28, 0x100
	global_load_lds_dwordx4 v[0:1], off
	v_lshrrev_b32_e32 v1, 1, v8
	v_and_b32_e32 v1, 24, v1
	v_and_b32_e32 v0, 15, v8
	v_lshlrev_b32_e32 v2, 1, v1
	v_lshl_or_b32 v203, s29, 6, v0
	v_lshl_or_b32 v0, v0, 6, v2
	v_lshlrev_b32_e32 v2, 2, v8
	v_and_b32_e32 v2, 32, v2
	v_bitop3_b32 v3, v0, s21, v2 bitop3:0xde
	v_bitop3_b32 v209, v0, s36, v2 bitop3:0xde
	v_lshlrev_b32_e32 v0, 14, v9
	v_and_b32_e32 v0, 0xffff8000, v0
	v_or_b32_e32 v224, s31, v1
	v_and_or_b32 v202, s31, 32, v1
	v_lshlrev_b32_e32 v200, 2, v1
	v_lshl_add_u32 v0, v10, 11, v0
	v_and_b32_e32 v1, 1, v9
	v_lshl_or_b32 v0, v1, 6, v0
	s_cselect_b64 s[28:29], -1, 0
	s_lshl_b32 s21, s30, 6
	v_lshl_add_u32 v206, v11, 1, v0
	v_lshlrev_b32_e32 v0, 14, v12
	s_and_b32 s74, s21, 0x80
	v_and_b32_e32 v0, 0xffff8000, v0
	s_waitcnt vmcnt(6)
	s_cmp_eq_u32 s20, 0
	v_lshl_add_u32 v0, v13, 11, v0
	v_and_b32_e32 v1, 1, v12
	s_cselect_b64 s[30:31], -1, 0
	v_lshl_or_b32 v0, v1, 6, v0
	s_add_i32 s84, 0, 0x10000
	s_add_i32 s85, 0, 0x14000
	v_writelane_b32 v238, s18, 8
	s_ashr_i32 s75, s90, 31
	s_mov_b32 s76, s90
	s_ashr_i32 s77, s2, 31
	v_lshl_add_u64 v[204:205], s[0:1], 0, v[200:201]
	v_mov_b32_e32 v207, v201
	v_lshl_add_u32 v210, v14, 1, v0
	v_mov_b32_e32 v211, v201
	v_mov_b64_e32 v[212:213], 0x1000
	v_mov_b64_e32 v[214:215], 0xfff
	v_add_u32_e32 v225, s84, v209
	v_add_u32_e32 v226, s85, v209
	v_add_u32_e32 v227, 0, v3
	s_mov_b32 s86, 0x3f3c0
	s_mov_b64 s[34:35], 0x2000
	s_mov_b64 s[36:37], 0x4000
	s_mov_b64 s[38:39], 0x6000
	v_mov_b32_e32 v228, 0x100
	v_writelane_b32 v238, s19, 9
	s_barrier
	s_mov_b32 s100, 0
	s_branch .LBB0_260

.LBB0_266:
	s_ashr_i32 s43, s42, 31
	s_lshl_b64 s[44:45], s[42:43], 19
	s_add_u32 s44, s6, s44
	s_addc_u32 s45, s7, s45
	s_and_b64 s[46:47], s[0:1], exec
	s_cselect_b32 s43, s45, s53
	s_cselect_b32 s51, s44, s52
	s_ashr_i32 s41, s40, 31
	s_lshl_b64 s[46:47], s[40:41], 19
	s_add_u32 s46, s33, s46
	s_addc_u32 s47, s58, s47
	s_and_b64 s[56:57], s[0:1], exec
	s_cselect_b32 s41, s47, s55
	s_cselect_b32 s87, s46, s54
	s_add_u32 s52, s52, 0x40080
	s_addc_u32 s53, s53, 0
	s_add_u32 s96, s54, 0x100
	v_mov_b32_e32 v32, 0
	s_addc_u32 s97, s55, 0
	s_mov_b32 vcc_lo, -2
	v_mov_b32_e32 v33, v32
	v_mov_b32_e32 v34, v32
	v_mov_b32_e32 v35, v32
	v_mov_b32_e32 v36, v32
	v_mov_b32_e32 v37, v32
	v_mov_b32_e32 v38, v32
	v_mov_b32_e32 v39, v32
	v_mov_b32_e32 v64, v32
	v_mov_b32_e32 v65, v32
	v_mov_b32_e32 v66, v32
	v_mov_b32_e32 v67, v32
	v_mov_b32_e32 v72, v32
	v_mov_b32_e32 v73, v32
	v_mov_b32_e32 v74, v32
	v_mov_b32_e32 v75, v32
	v_mov_b32_e32 v80, v32
	v_mov_b32_e32 v81, v32
	v_mov_b32_e32 v82, v32
	v_mov_b32_e32 v83, v32
	v_mov_b32_e32 v84, v32
	v_mov_b32_e32 v85, v32
	v_mov_b32_e32 v86, v32
	v_mov_b32_e32 v87, v32
	v_mov_b32_e32 v88, v32
	v_mov_b32_e32 v89, v32
	v_mov_b32_e32 v90, v32
	v_mov_b32_e32 v91, v32
	v_mov_b32_e32 v92, v32
	v_mov_b32_e32 v93, v32
	v_mov_b32_e32 v94, v32
	v_mov_b32_e32 v95, v32
	v_mov_b32_e32 v0, v32
	v_mov_b32_e32 v1, v32
	v_mov_b32_e32 v2, v32
	v_mov_b32_e32 v3, v32
	v_mov_b32_e32 v4, v32
	v_mov_b32_e32 v5, v32
	v_mov_b32_e32 v6, v32
	v_mov_b32_e32 v7, v32
	v_mov_b32_e32 v8, v32
	v_mov_b32_e32 v9, v32
	v_mov_b32_e32 v10, v32
	v_mov_b32_e32 v11, v32
	v_mov_b32_e32 v12, v32
	v_mov_b32_e32 v13, v32
	v_mov_b32_e32 v14, v32
	v_mov_b32_e32 v15, v32
	v_mov_b32_e32 v16, v32
	v_mov_b32_e32 v17, v32
	v_mov_b32_e32 v18, v32
	v_mov_b32_e32 v19, v32
	v_mov_b32_e32 v20, v32
	v_mov_b32_e32 v21, v32
	v_mov_b32_e32 v22, v32
	v_mov_b32_e32 v23, v32
	v_mov_b32_e32 v24, v32
	v_mov_b32_e32 v25, v32
	v_mov_b32_e32 v26, v32
	v_mov_b32_e32 v27, v32
	v_mov_b32_e32 v28, v32
	v_mov_b32_e32 v29, v32
	v_mov_b32_e32 v30, v32
	v_mov_b32_e32 v31, v32
	v_mov_b32_e32 v96, v32
	v_mov_b32_e32 v97, v32
	v_mov_b32_e32 v98, v32
	v_mov_b32_e32 v99, v32
	v_mov_b32_e32 v100, v32
	v_mov_b32_e32 v101, v32
	v_mov_b32_e32 v102, v32
	v_mov_b32_e32 v103, v32
	v_mov_b32_e32 v104, v32
	v_mov_b32_e32 v105, v32
	v_mov_b32_e32 v106, v32
	v_mov_b32_e32 v107, v32
	v_mov_b32_e32 v108, v32
	v_mov_b32_e32 v109, v32
	v_mov_b32_e32 v110, v32
	v_mov_b32_e32 v111, v32
	v_mov_b32_e32 v112, v32
	v_mov_b32_e32 v113, v32
	v_mov_b32_e32 v114, v32
	v_mov_b32_e32 v115, v32
	v_mov_b32_e32 v116, v32
	v_mov_b32_e32 v117, v32
	v_mov_b32_e32 v118, v32
	v_mov_b32_e32 v119, v32
	v_mov_b32_e32 v120, v32
	v_mov_b32_e32 v121, v32
	v_mov_b32_e32 v122, v32
	v_mov_b32_e32 v123, v32
	v_mov_b32_e32 v124, v32
	v_mov_b32_e32 v125, v32
	v_mov_b32_e32 v126, v32
	v_mov_b32_e32 v127, v32
	v_mov_b32_e32 v40, v32
	v_mov_b32_e32 v41, v32
	v_mov_b32_e32 v42, v32
	v_mov_b32_e32 v43, v32
	v_mov_b32_e32 v44, v32
	v_mov_b32_e32 v45, v32
	v_mov_b32_e32 v46, v32
	v_mov_b32_e32 v47, v32
	v_mov_b32_e32 v48, v32
	v_mov_b32_e32 v49, v32
	v_mov_b32_e32 v50, v32
	v_mov_b32_e32 v51, v32
	v_mov_b32_e32 v52, v32
	v_mov_b32_e32 v53, v32
	v_mov_b32_e32 v54, v32
	v_mov_b32_e32 v55, v32
	v_mov_b32_e32 v56, v32
	v_mov_b32_e32 v57, v32
	v_mov_b32_e32 v58, v32
	v_mov_b32_e32 v59, v32
	v_mov_b32_e32 v60, v32
	v_mov_b32_e32 v61, v32
	v_mov_b32_e32 v62, v32
	v_mov_b32_e32 v63, v32
	v_mov_b32_e32 v68, v32
	v_mov_b32_e32 v69, v32
	v_mov_b32_e32 v70, v32
	v_mov_b32_e32 v71, v32
	v_mov_b32_e32 v76, v32
	v_mov_b32_e32 v77, v32
	v_mov_b32_e32 v78, v32
	v_mov_b32_e32 v79, v32
	s_cmp_eq_u32 s100, 0
	s_cbranch_scc1 .LBB0_267
	ds_read_b128 v[128:131], v225
	ds_read_b128 v[132:135], v225 offset:1024
	ds_read_b128 v[136:139], v225 offset:2048
	ds_read_b128 v[140:143], v225 offset:3072
	ds_read_b128 v[144:147], v226
	ds_read_b128 v[148:151], v226 offset:1024
	ds_read_b128 v[152:155], v226 offset:2048
	ds_read_b128 v[156:159], v226 offset:3072
	s_add_u32 s20, s52, 0xfffc0080
	s_addc_u32 s21, s53, -1
	s_cmp_eq_u32 vcc_lo, 12
	s_cselect_b32 s57, s43, s21
	s_cselect_b32 s56, s51, s20
	s_cselect_b32 s55, s41, s97
	s_cselect_b32 s54, s87, s96
	v_lshl_add_u64 v[216:217], s[52:53], 0, v[206:207]
	s_add_i32 m0, s49, 0xc000
	ds_read_b128 v[160:163], v227
	ds_read_b128 v[164:167], v227 offset:1024
	ds_read_b128 v[168:171], v227 offset:2048
	ds_read_b128 v[172:175], v227 offset:3072
	ds_read_b128 v[176:179], v227 offset:4096
	ds_read_b128 v[180:183], v227 offset:5120
	ds_read_b128 v[184:187], v227 offset:6144
	ds_read_b128 v[188:191], v227 offset:7168
	global_load_lds_dwordx4 v[216:217], off
	v_lshl_add_u64 v[216:217], s[52:53], 0, v[210:211]
	s_add_i32 m0, s49, 0xe000
	s_nop 0
	global_load_lds_dwordx4 v[216:217], off
	s_waitcnt vmcnt(24)
	s_waitcnt lgkmcnt(0)
	s_barrier
	s_setprio 1
	s_waitcnt lgkmcnt(0)
	v_mfma_f32_16x16x32_bf16 v[76:79], v[128:131], v[160:163], v[76:79]
	v_mfma_f32_16x16x32_bf16 v[68:71], v[136:139], v[160:163], v[68:71]
	v_mfma_f32_16x16x32_bf16 v[60:63], v[128:131], v[168:171], v[60:63]
	v_mfma_f32_16x16x32_bf16 v[56:59], v[136:139], v[168:171], v[56:59]
	v_mfma_f32_16x16x32_bf16 v[52:55], v[128:131], v[176:179], v[52:55]
	v_mfma_f32_16x16x32_bf16 v[48:51], v[136:139], v[176:179], v[48:51]
	v_mfma_f32_16x16x32_bf16 v[44:47], v[128:131], v[184:187], v[44:47]
	v_mfma_f32_16x16x32_bf16 v[40:43], v[136:139], v[184:187], v[40:43]
	v_mfma_f32_16x16x32_bf16 v[76:79], v[132:135], v[164:167], v[76:79]
	v_mfma_f32_16x16x32_bf16 v[68:71], v[140:143], v[164:167], v[68:71]
	v_mfma_f32_16x16x32_bf16 v[60:63], v[132:135], v[172:175], v[60:63]
	v_mfma_f32_16x16x32_bf16 v[56:59], v[140:143], v[172:175], v[56:59]
	v_mfma_f32_16x16x32_bf16 v[52:55], v[132:135], v[180:183], v[52:55]
	v_mfma_f32_16x16x32_bf16 v[48:51], v[140:143], v[180:183], v[48:51]
	v_mfma_f32_16x16x32_bf16 v[44:47], v[132:135], v[188:191], v[44:47]
	v_mfma_f32_16x16x32_bf16 v[40:43], v[140:143], v[188:191], v[40:43]
	s_setprio 0
	s_setprio 1
	v_mfma_f32_16x16x32_bf16 v[124:127], v[144:147], v[160:163], v[124:127]
	v_mfma_f32_16x16x32_bf16 v[120:123], v[152:155], v[160:163], v[120:123]
	v_mfma_f32_16x16x32_bf16 v[116:119], v[144:147], v[168:171], v[116:119]
	v_mfma_f32_16x16x32_bf16 v[112:115], v[152:155], v[168:171], v[112:115]
	v_mfma_f32_16x16x32_bf16 v[108:111], v[144:147], v[176:179], v[108:111]
	v_mfma_f32_16x16x32_bf16 v[104:107], v[152:155], v[176:179], v[104:107]
	v_mfma_f32_16x16x32_bf16 v[100:103], v[144:147], v[184:187], v[100:103]
	v_mfma_f32_16x16x32_bf16 v[96:99], v[152:155], v[184:187], v[96:99]
	v_mfma_f32_16x16x32_bf16 v[124:127], v[148:151], v[164:167], v[124:127]
	v_mfma_f32_16x16x32_bf16 v[120:123], v[156:159], v[164:167], v[120:123]
	v_mfma_f32_16x16x32_bf16 v[116:119], v[148:151], v[172:175], v[116:119]
	v_mfma_f32_16x16x32_bf16 v[112:115], v[156:159], v[172:175], v[112:115]
	v_mfma_f32_16x16x32_bf16 v[108:111], v[148:151], v[180:183], v[108:111]
	v_mfma_f32_16x16x32_bf16 v[104:107], v[156:159], v[180:183], v[104:107]
	v_mfma_f32_16x16x32_bf16 v[100:103], v[148:151], v[188:191], v[100:103]
	v_mfma_f32_16x16x32_bf16 v[96:99], v[156:159], v[188:191], v[96:99]
	s_setprio 0
	s_barrier
	s_add_i32 s20, s84, s3
	v_lshl_add_u64 v[216:217], s[54:55], 0, v[194:195]
	s_mov_b32 m0, s20
	ds_read_b128 v[160:163], v227 offset:16384
	ds_read_b128 v[164:167], v227 offset:17408
	ds_read_b128 v[168:171], v227 offset:18432
	ds_read_b128 v[172:175], v227 offset:19456
	ds_read_b128 v[176:179], v227 offset:20480
	ds_read_b128 v[180:183], v227 offset:21504
	ds_read_b128 v[184:187], v227 offset:22528
	ds_read_b128 v[188:191], v227 offset:23552
	global_load_lds_dwordx4 v[216:217], off
	s_add_i32 m0, s20, 0x2000
	s_add_u32 s20, s54, 0x40000
	v_lshl_add_u64 v[218:219], s[54:55], 0, v[198:199]
	s_addc_u32 s21, s55, 0
	s_add_i32 vcc_hi, s85, s3
	global_load_lds_dwordx4 v[218:219], off
	v_lshl_add_u64 v[220:221], s[20:21], 0, v[194:195]
	s_mov_b32 m0, vcc_hi
	v_lshl_add_u64 v[222:223], s[56:57], 0, v[196:197]
	global_load_lds_dwordx4 v[220:221], off
	v_lshl_add_u64 v[220:221], s[20:21], 0, v[198:199]
	s_add_i32 m0, vcc_hi, 0x2000
	s_nop 0
	global_load_lds_dwordx4 v[220:221], off
	v_lshl_add_u64 v[220:221], s[56:57], 0, v[192:193]
	s_mov_b32 m0, s49
	s_nop 0
	global_load_lds_dwordx4 v[220:221], off
	s_mov_b32 m0, s59
	s_nop 0
	global_load_lds_dwordx4 v[222:223], off
	s_waitcnt vmcnt(24)
	s_waitcnt lgkmcnt(0)
	s_barrier
	s_setprio 1
	s_waitcnt lgkmcnt(0)
	v_mfma_f32_16x16x32_bf16 v[28:31], v[128:131], v[160:163], v[28:31]
	v_mfma_f32_16x16x32_bf16 v[24:27], v[136:139], v[160:163], v[24:27]
	v_mfma_f32_16x16x32_bf16 v[20:23], v[128:131], v[168:171], v[20:23]
	v_mfma_f32_16x16x32_bf16 v[16:19], v[136:139], v[168:171], v[16:19]
	v_mfma_f32_16x16x32_bf16 v[12:15], v[128:131], v[176:179], v[12:15]
	v_mfma_f32_16x16x32_bf16 v[8:11], v[136:139], v[176:179], v[8:11]
	v_mfma_f32_16x16x32_bf16 v[4:7], v[128:131], v[184:187], v[4:7]
	v_mfma_f32_16x16x32_bf16 v[0:3], v[136:139], v[184:187], v[0:3]
	v_mfma_f32_16x16x32_bf16 v[28:31], v[132:135], v[164:167], v[28:31]
	v_mfma_f32_16x16x32_bf16 v[24:27], v[140:143], v[164:167], v[24:27]
	v_mfma_f32_16x16x32_bf16 v[20:23], v[132:135], v[172:175], v[20:23]
	v_mfma_f32_16x16x32_bf16 v[16:19], v[140:143], v[172:175], v[16:19]
	v_mfma_f32_16x16x32_bf16 v[12:15], v[132:135], v[180:183], v[12:15]
	v_mfma_f32_16x16x32_bf16 v[8:11], v[140:143], v[180:183], v[8:11]
	v_mfma_f32_16x16x32_bf16 v[4:7], v[132:135], v[188:191], v[4:7]
	v_mfma_f32_16x16x32_bf16 v[0:3], v[140:143], v[188:191], v[0:3]
	s_setprio 0
	s_setprio 1
	v_mfma_f32_16x16x32_bf16 v[92:95], v[144:147], v[160:163], v[92:95]
	v_mfma_f32_16x16x32_bf16 v[88:91], v[152:155], v[160:163], v[88:91]
	v_mfma_f32_16x16x32_bf16 v[84:87], v[144:147], v[168:171], v[84:87]
	v_mfma_f32_16x16x32_bf16 v[80:83], v[152:155], v[168:171], v[80:83]
	v_mfma_f32_16x16x32_bf16 v[72:75], v[144:147], v[176:179], v[72:75]
	v_mfma_f32_16x16x32_bf16 v[64:67], v[152:155], v[176:179], v[64:67]
	v_mfma_f32_16x16x32_bf16 v[36:39], v[144:147], v[184:187], v[36:39]
	v_mfma_f32_16x16x32_bf16 v[32:35], v[152:155], v[184:187], v[32:35]
	v_mfma_f32_16x16x32_bf16 v[92:95], v[148:151], v[164:167], v[92:95]
	v_mfma_f32_16x16x32_bf16 v[88:91], v[156:159], v[164:167], v[88:91]
	v_mfma_f32_16x16x32_bf16 v[84:87], v[148:151], v[172:175], v[84:87]
	v_mfma_f32_16x16x32_bf16 v[80:83], v[156:159], v[172:175], v[80:83]
	v_mfma_f32_16x16x32_bf16 v[72:75], v[148:151], v[180:183], v[72:75]
	v_mfma_f32_16x16x32_bf16 v[64:67], v[156:159], v[180:183], v[64:67]
	v_mfma_f32_16x16x32_bf16 v[36:39], v[148:151], v[188:191], v[36:39]
	v_mfma_f32_16x16x32_bf16 v[32:35], v[156:159], v[188:191], v[32:35]
	s_setprio 0
	s_barrier
	s_add_i32 vcc_hi, 0, 0x18000
	s_add_i32 s18, 0, 0x1c000
	v_add_u32_e32 v140, vcc_hi, v209
	v_add_u32_e32 v156, s18, v209
	ds_read_b128 v[128:131], v140
	ds_read_b128 v[132:135], v140 offset:1024
	ds_read_b128 v[136:139], v140 offset:2048
	ds_read_b128 v[140:143], v140 offset:3072
	ds_read_b128 v[144:147], v156
	ds_read_b128 v[148:151], v156 offset:1024
	ds_read_b128 v[152:155], v156 offset:2048
	ds_read_b128 v[156:159], v156 offset:3072
	s_add_u32 s20, s56, 0x40000
	s_addc_u32 s21, s57, 0
	s_mov_b32 m0, s62
	v_lshl_add_u64 v[230:231], s[20:21], 0, v[192:193]
	ds_read_b128 v[160:163], v227 offset:32768
	ds_read_b128 v[164:167], v227 offset:33792
	ds_read_b128 v[168:171], v227 offset:34816
	ds_read_b128 v[172:175], v227 offset:35840
	ds_read_b128 v[176:179], v227 offset:36864
	ds_read_b128 v[180:183], v227 offset:37888
	ds_read_b128 v[184:187], v227 offset:38912
	ds_read_b128 v[188:191], v227 offset:39936
	global_load_lds_dwordx4 v[230:231], off
	v_lshl_add_u64 v[230:231], s[20:21], 0, v[196:197]
	s_mov_b32 m0, s63
	s_nop 0
	global_load_lds_dwordx4 v[230:231], off
	s_waitcnt vmcnt(8)
	s_waitcnt lgkmcnt(0)
	s_barrier
	s_setprio 1
	s_waitcnt lgkmcnt(0)
	v_mfma_f32_16x16x32_bf16 v[76:79], v[128:131], v[160:163], v[76:79]
	v_mfma_f32_16x16x32_bf16 v[68:71], v[136:139], v[160:163], v[68:71]
	v_mfma_f32_16x16x32_bf16 v[60:63], v[128:131], v[168:171], v[60:63]
	v_mfma_f32_16x16x32_bf16 v[56:59], v[136:139], v[168:171], v[56:59]
	v_mfma_f32_16x16x32_bf16 v[52:55], v[128:131], v[176:179], v[52:55]
	v_mfma_f32_16x16x32_bf16 v[48:51], v[136:139], v[176:179], v[48:51]
	v_mfma_f32_16x16x32_bf16 v[44:47], v[128:131], v[184:187], v[44:47]
	v_mfma_f32_16x16x32_bf16 v[40:43], v[136:139], v[184:187], v[40:43]
	v_mfma_f32_16x16x32_bf16 v[76:79], v[132:135], v[164:167], v[76:79]
	v_mfma_f32_16x16x32_bf16 v[68:71], v[140:143], v[164:167], v[68:71]
	v_mfma_f32_16x16x32_bf16 v[60:63], v[132:135], v[172:175], v[60:63]
	v_mfma_f32_16x16x32_bf16 v[56:59], v[140:143], v[172:175], v[56:59]
	v_mfma_f32_16x16x32_bf16 v[52:55], v[132:135], v[180:183], v[52:55]
	v_mfma_f32_16x16x32_bf16 v[48:51], v[140:143], v[180:183], v[48:51]
	v_mfma_f32_16x16x32_bf16 v[44:47], v[132:135], v[188:191], v[44:47]
	v_mfma_f32_16x16x32_bf16 v[40:43], v[140:143], v[188:191], v[40:43]
	s_setprio 0
	s_setprio 1
	v_mfma_f32_16x16x32_bf16 v[124:127], v[144:147], v[160:163], v[124:127]
	v_mfma_f32_16x16x32_bf16 v[120:123], v[152:155], v[160:163], v[120:123]
	v_mfma_f32_16x16x32_bf16 v[116:119], v[144:147], v[168:171], v[116:119]
	v_mfma_f32_16x16x32_bf16 v[112:115], v[152:155], v[168:171], v[112:115]
	v_mfma_f32_16x16x32_bf16 v[108:111], v[144:147], v[176:179], v[108:111]
	v_mfma_f32_16x16x32_bf16 v[104:107], v[152:155], v[176:179], v[104:107]
	v_mfma_f32_16x16x32_bf16 v[100:103], v[144:147], v[184:187], v[100:103]
	v_mfma_f32_16x16x32_bf16 v[96:99], v[152:155], v[184:187], v[96:99]
	v_mfma_f32_16x16x32_bf16 v[124:127], v[148:151], v[164:167], v[124:127]
	v_mfma_f32_16x16x32_bf16 v[120:123], v[156:159], v[164:167], v[120:123]
	v_mfma_f32_16x16x32_bf16 v[116:119], v[148:151], v[172:175], v[116:119]
	v_mfma_f32_16x16x32_bf16 v[112:115], v[156:159], v[172:175], v[112:115]
	v_mfma_f32_16x16x32_bf16 v[108:111], v[148:151], v[180:183], v[108:111]
	v_mfma_f32_16x16x32_bf16 v[104:107], v[156:159], v[180:183], v[104:107]
	v_mfma_f32_16x16x32_bf16 v[100:103], v[148:151], v[188:191], v[100:103]
	v_mfma_f32_16x16x32_bf16 v[96:99], v[156:159], v[188:191], v[96:99]
	s_setprio 0
	s_barrier
	s_add_i32 s19, vcc_hi, s3
	v_lshl_add_u64 v[216:217], v[216:217], 0, s[26:27]
	s_mov_b32 m0, s19
	ds_read_b128 v[160:163], v227 offset:49152
	ds_read_b128 v[164:167], v227 offset:50176
	ds_read_b128 v[168:171], v227 offset:51200
	ds_read_b128 v[172:175], v227 offset:52224
	ds_read_b128 v[176:179], v227 offset:53248
	ds_read_b128 v[180:183], v227 offset:54272
	ds_read_b128 v[184:187], v227 offset:55296
	ds_read_b128 v[188:191], v227 offset:56320
	global_load_lds_dwordx4 v[216:217], off
	s_add_i32 m0, s19, 0x2000
	s_add_u32 s20, s54, 0x40080
	v_lshl_add_u64 v[216:217], v[218:219], 0, s[26:27]
	s_addc_u32 s21, s55, 0
	s_add_i32 s18, s18, s3
	global_load_lds_dwordx4 v[216:217], off
	v_lshl_add_u64 v[216:217], s[20:21], 0, v[194:195]
	s_mov_b32 m0, s18
	s_nop 0
	global_load_lds_dwordx4 v[216:217], off
	v_lshl_add_u64 v[216:217], s[20:21], 0, v[198:199]
	s_add_i32 m0, s18, 0x2000
	s_nop 0
	global_load_lds_dwordx4 v[216:217], off
	v_lshl_add_u64 v[216:217], v[220:221], 0, s[26:27]
	s_mov_b32 m0, s68
	s_nop 0
	global_load_lds_dwordx4 v[216:217], off
	v_lshl_add_u64 v[216:217], v[222:223], 0, s[26:27]
	s_mov_b32 m0, s69
	s_nop 0
	global_load_lds_dwordx4 v[216:217], off
	s_waitcnt vmcnt(8)
	s_waitcnt lgkmcnt(0)
	s_barrier
	s_setprio 1
	s_waitcnt lgkmcnt(0)
	v_mfma_f32_16x16x32_bf16 v[28:31], v[128:131], v[160:163], v[28:31]
	v_mfma_f32_16x16x32_bf16 v[24:27], v[136:139], v[160:163], v[24:27]
	v_mfma_f32_16x16x32_bf16 v[20:23], v[128:131], v[168:171], v[20:23]
	v_mfma_f32_16x16x32_bf16 v[16:19], v[136:139], v[168:171], v[16:19]
	v_mfma_f32_16x16x32_bf16 v[12:15], v[128:131], v[176:179], v[12:15]
	v_mfma_f32_16x16x32_bf16 v[8:11], v[136:139], v[176:179], v[8:11]
	v_mfma_f32_16x16x32_bf16 v[4:7], v[128:131], v[184:187], v[4:7]
	v_mfma_f32_16x16x32_bf16 v[0:3], v[136:139], v[184:187], v[0:3]
	v_mfma_f32_16x16x32_bf16 v[28:31], v[132:135], v[164:167], v[28:31]
	v_mfma_f32_16x16x32_bf16 v[24:27], v[140:143], v[164:167], v[24:27]
	v_mfma_f32_16x16x32_bf16 v[20:23], v[132:135], v[172:175], v[20:23]
	v_mfma_f32_16x16x32_bf16 v[16:19], v[140:143], v[172:175], v[16:19]
	v_mfma_f32_16x16x32_bf16 v[12:15], v[132:135], v[180:183], v[12:15]
	v_mfma_f32_16x16x32_bf16 v[8:11], v[140:143], v[180:183], v[8:11]
	v_mfma_f32_16x16x32_bf16 v[4:7], v[132:135], v[188:191], v[4:7]
	v_mfma_f32_16x16x32_bf16 v[0:3], v[140:143], v[188:191], v[0:3]
	s_setprio 0
	s_setprio 1
	v_mfma_f32_16x16x32_bf16 v[92:95], v[144:147], v[160:163], v[92:95]
	v_mfma_f32_16x16x32_bf16 v[88:91], v[152:155], v[160:163], v[88:91]
	v_mfma_f32_16x16x32_bf16 v[84:87], v[144:147], v[168:171], v[84:87]
	v_mfma_f32_16x16x32_bf16 v[80:83], v[152:155], v[168:171], v[80:83]
	v_mfma_f32_16x16x32_bf16 v[72:75], v[144:147], v[176:179], v[72:75]
	v_mfma_f32_16x16x32_bf16 v[64:67], v[152:155], v[176:179], v[64:67]
	v_mfma_f32_16x16x32_bf16 v[36:39], v[144:147], v[184:187], v[36:39]
	v_mfma_f32_16x16x32_bf16 v[32:35], v[152:155], v[184:187], v[32:35]
	v_mfma_f32_16x16x32_bf16 v[92:95], v[148:151], v[164:167], v[92:95]
	v_mfma_f32_16x16x32_bf16 v[88:91], v[156:159], v[164:167], v[88:91]
	v_mfma_f32_16x16x32_bf16 v[84:87], v[148:151], v[172:175], v[84:87]
	v_mfma_f32_16x16x32_bf16 v[80:83], v[156:159], v[172:175], v[80:83]
	v_mfma_f32_16x16x32_bf16 v[72:75], v[148:151], v[180:183], v[72:75]
	v_mfma_f32_16x16x32_bf16 v[64:67], v[156:159], v[180:183], v[64:67]
	v_mfma_f32_16x16x32_bf16 v[36:39], v[148:151], v[188:191], v[36:39]
	v_mfma_f32_16x16x32_bf16 v[32:35], v[156:159], v[188:191], v[32:35]
	s_setprio 0
	s_barrier
	s_add_i32 vcc_lo, vcc_lo, 2
	s_add_u32 s52, s52, 0x100
	s_addc_u32 s53, s53, 0
	s_add_u32 s96, s96, 0x100
	s_addc_u32 s97, s97, 0
	s_cmp_gt_u32 vcc_lo, 13
	s_cbranch_scc0 .LBB0_267
.LBB0_267:
	ds_read_b128 v[128:131], v225
	ds_read_b128 v[132:135], v225 offset:1024
	ds_read_b128 v[136:139], v225 offset:2048
	ds_read_b128 v[140:143], v225 offset:3072
	ds_read_b128 v[144:147], v226
	ds_read_b128 v[148:151], v226 offset:1024
	ds_read_b128 v[152:155], v226 offset:2048
	ds_read_b128 v[156:159], v226 offset:3072
	s_add_u32 s20, s52, 0xfffc0080
	s_addc_u32 s21, s53, -1
	s_cmp_eq_u32 vcc_lo, 12
	s_cselect_b32 s57, s43, s21
	s_cselect_b32 s56, s51, s20
	s_cselect_b32 s55, s41, s97
	s_cselect_b32 s54, s87, s96
	v_lshl_add_u64 v[216:217], s[52:53], 0, v[206:207]
	s_add_i32 m0, s49, 0xc000
	ds_read_b128 v[160:163], v227
	ds_read_b128 v[164:167], v227 offset:1024
	ds_read_b128 v[168:171], v227 offset:2048
	ds_read_b128 v[172:175], v227 offset:3072
	ds_read_b128 v[176:179], v227 offset:4096
	ds_read_b128 v[180:183], v227 offset:5120
	ds_read_b128 v[184:187], v227 offset:6144
	ds_read_b128 v[188:191], v227 offset:7168
	global_load_lds_dwordx4 v[216:217], off
	v_lshl_add_u64 v[216:217], s[52:53], 0, v[210:211]
	s_add_i32 m0, s49, 0xe000
	s_nop 0
	global_load_lds_dwordx4 v[216:217], off
	s_waitcnt vmcnt(8)
	s_waitcnt lgkmcnt(0)
	s_barrier
	s_setprio 1
	s_waitcnt lgkmcnt(0)
	v_mfma_f32_16x16x32_bf16 v[76:79], v[128:131], v[160:163], v[76:79]
	v_mfma_f32_16x16x32_bf16 v[68:71], v[136:139], v[160:163], v[68:71]
	v_mfma_f32_16x16x32_bf16 v[60:63], v[128:131], v[168:171], v[60:63]
	v_mfma_f32_16x16x32_bf16 v[56:59], v[136:139], v[168:171], v[56:59]
	v_mfma_f32_16x16x32_bf16 v[52:55], v[128:131], v[176:179], v[52:55]
	v_mfma_f32_16x16x32_bf16 v[48:51], v[136:139], v[176:179], v[48:51]
	v_mfma_f32_16x16x32_bf16 v[44:47], v[128:131], v[184:187], v[44:47]
	v_mfma_f32_16x16x32_bf16 v[40:43], v[136:139], v[184:187], v[40:43]
	v_mfma_f32_16x16x32_bf16 v[76:79], v[132:135], v[164:167], v[76:79]
	v_mfma_f32_16x16x32_bf16 v[68:71], v[140:143], v[164:167], v[68:71]
	v_mfma_f32_16x16x32_bf16 v[60:63], v[132:135], v[172:175], v[60:63]
	v_mfma_f32_16x16x32_bf16 v[56:59], v[140:143], v[172:175], v[56:59]
	v_mfma_f32_16x16x32_bf16 v[52:55], v[132:135], v[180:183], v[52:55]
	v_mfma_f32_16x16x32_bf16 v[48:51], v[140:143], v[180:183], v[48:51]
	v_mfma_f32_16x16x32_bf16 v[44:47], v[132:135], v[188:191], v[44:47]
	v_mfma_f32_16x16x32_bf16 v[40:43], v[140:143], v[188:191], v[40:43]
	s_setprio 0
	s_setprio 1
	v_mfma_f32_16x16x32_bf16 v[124:127], v[144:147], v[160:163], v[124:127]
	v_mfma_f32_16x16x32_bf16 v[120:123], v[152:155], v[160:163], v[120:123]
	v_mfma_f32_16x16x32_bf16 v[116:119], v[144:147], v[168:171], v[116:119]
	v_mfma_f32_16x16x32_bf16 v[112:115], v[152:155], v[168:171], v[112:115]
	v_mfma_f32_16x16x32_bf16 v[108:111], v[144:147], v[176:179], v[108:111]
	v_mfma_f32_16x16x32_bf16 v[104:107], v[152:155], v[176:179], v[104:107]
	v_mfma_f32_16x16x32_bf16 v[100:103], v[144:147], v[184:187], v[100:103]
	v_mfma_f32_16x16x32_bf16 v[96:99], v[152:155], v[184:187], v[96:99]
	v_mfma_f32_16x16x32_bf16 v[124:127], v[148:151], v[164:167], v[124:127]
	v_mfma_f32_16x16x32_bf16 v[120:123], v[156:159], v[164:167], v[120:123]
	v_mfma_f32_16x16x32_bf16 v[116:119], v[148:151], v[172:175], v[116:119]
	v_mfma_f32_16x16x32_bf16 v[112:115], v[156:159], v[172:175], v[112:115]
	v_mfma_f32_16x16x32_bf16 v[108:111], v[148:151], v[180:183], v[108:111]
	v_mfma_f32_16x16x32_bf16 v[104:107], v[156:159], v[180:183], v[104:107]
	v_mfma_f32_16x16x32_bf16 v[100:103], v[148:151], v[188:191], v[100:103]
	v_mfma_f32_16x16x32_bf16 v[96:99], v[156:159], v[188:191], v[96:99]
	s_setprio 0
	s_barrier
	s_add_i32 s20, s84, s3
	v_lshl_add_u64 v[216:217], s[54:55], 0, v[194:195]
	s_mov_b32 m0, s20
	ds_read_b128 v[160:163], v227 offset:16384
	ds_read_b128 v[164:167], v227 offset:17408
	ds_read_b128 v[168:171], v227 offset:18432
	ds_read_b128 v[172:175], v227 offset:19456
	ds_read_b128 v[176:179], v227 offset:20480
	ds_read_b128 v[180:183], v227 offset:21504
	ds_read_b128 v[184:187], v227 offset:22528
	ds_read_b128 v[188:191], v227 offset:23552
	global_load_lds_dwordx4 v[216:217], off
	s_add_i32 m0, s20, 0x2000
	s_add_u32 s20, s54, 0x40000
	v_lshl_add_u64 v[218:219], s[54:55], 0, v[198:199]
	s_addc_u32 s21, s55, 0
	s_add_i32 vcc_hi, s85, s3
	global_load_lds_dwordx4 v[218:219], off
	v_lshl_add_u64 v[220:221], s[20:21], 0, v[194:195]
	s_mov_b32 m0, vcc_hi
	v_lshl_add_u64 v[222:223], s[56:57], 0, v[196:197]
	global_load_lds_dwordx4 v[220:221], off
	v_lshl_add_u64 v[220:221], s[20:21], 0, v[198:199]
	s_add_i32 m0, vcc_hi, 0x2000
	s_nop 0
	global_load_lds_dwordx4 v[220:221], off
	v_lshl_add_u64 v[220:221], s[56:57], 0, v[192:193]
	s_mov_b32 m0, s49
	s_nop 0
	global_load_lds_dwordx4 v[220:221], off
	s_mov_b32 m0, s59
	s_nop 0
	global_load_lds_dwordx4 v[222:223], off
	s_waitcnt vmcnt(8)
	s_waitcnt lgkmcnt(0)
	s_barrier
	s_setprio 1
	s_waitcnt lgkmcnt(0)
	v_mfma_f32_16x16x32_bf16 v[28:31], v[128:131], v[160:163], v[28:31]
	v_mfma_f32_16x16x32_bf16 v[24:27], v[136:139], v[160:163], v[24:27]
	v_mfma_f32_16x16x32_bf16 v[20:23], v[128:131], v[168:171], v[20:23]
	v_mfma_f32_16x16x32_bf16 v[16:19], v[136:139], v[168:171], v[16:19]
	v_mfma_f32_16x16x32_bf16 v[12:15], v[128:131], v[176:179], v[12:15]
	v_mfma_f32_16x16x32_bf16 v[8:11], v[136:139], v[176:179], v[8:11]
	v_mfma_f32_16x16x32_bf16 v[4:7], v[128:131], v[184:187], v[4:7]
	v_mfma_f32_16x16x32_bf16 v[0:3], v[136:139], v[184:187], v[0:3]
	v_mfma_f32_16x16x32_bf16 v[28:31], v[132:135], v[164:167], v[28:31]
	v_mfma_f32_16x16x32_bf16 v[24:27], v[140:143], v[164:167], v[24:27]
	v_mfma_f32_16x16x32_bf16 v[20:23], v[132:135], v[172:175], v[20:23]
	v_mfma_f32_16x16x32_bf16 v[16:19], v[140:143], v[172:175], v[16:19]
	v_mfma_f32_16x16x32_bf16 v[12:15], v[132:135], v[180:183], v[12:15]
	v_mfma_f32_16x16x32_bf16 v[8:11], v[140:143], v[180:183], v[8:11]
	v_mfma_f32_16x16x32_bf16 v[4:7], v[132:135], v[188:191], v[4:7]
	v_mfma_f32_16x16x32_bf16 v[0:3], v[140:143], v[188:191], v[0:3]
	s_setprio 0
	s_setprio 1
	v_mfma_f32_16x16x32_bf16 v[92:95], v[144:147], v[160:163], v[92:95]
	v_mfma_f32_16x16x32_bf16 v[88:91], v[152:155], v[160:163], v[88:91]
	v_mfma_f32_16x16x32_bf16 v[84:87], v[144:147], v[168:171], v[84:87]
	v_mfma_f32_16x16x32_bf16 v[80:83], v[152:155], v[168:171], v[80:83]
	v_mfma_f32_16x16x32_bf16 v[72:75], v[144:147], v[176:179], v[72:75]
	v_mfma_f32_16x16x32_bf16 v[64:67], v[152:155], v[176:179], v[64:67]
	v_mfma_f32_16x16x32_bf16 v[36:39], v[144:147], v[184:187], v[36:39]
	v_mfma_f32_16x16x32_bf16 v[32:35], v[152:155], v[184:187], v[32:35]
	v_mfma_f32_16x16x32_bf16 v[92:95], v[148:151], v[164:167], v[92:95]
	v_mfma_f32_16x16x32_bf16 v[88:91], v[156:159], v[164:167], v[88:91]
	v_mfma_f32_16x16x32_bf16 v[84:87], v[148:151], v[172:175], v[84:87]
	v_mfma_f32_16x16x32_bf16 v[80:83], v[156:159], v[172:175], v[80:83]
	v_mfma_f32_16x16x32_bf16 v[72:75], v[148:151], v[180:183], v[72:75]
	v_mfma_f32_16x16x32_bf16 v[64:67], v[156:159], v[180:183], v[64:67]
	v_mfma_f32_16x16x32_bf16 v[36:39], v[148:151], v[188:191], v[36:39]
	v_mfma_f32_16x16x32_bf16 v[32:35], v[156:159], v[188:191], v[32:35]
	s_setprio 0
	s_barrier
	s_add_i32 vcc_hi, 0, 0x18000
	s_add_i32 s18, 0, 0x1c000
	v_add_u32_e32 v140, vcc_hi, v209
	v_add_u32_e32 v156, s18, v209
	ds_read_b128 v[128:131], v140
	ds_read_b128 v[132:135], v140 offset:1024
	ds_read_b128 v[136:139], v140 offset:2048
	ds_read_b128 v[140:143], v140 offset:3072
	ds_read_b128 v[144:147], v156
	ds_read_b128 v[148:151], v156 offset:1024
	ds_read_b128 v[152:155], v156 offset:2048
	ds_read_b128 v[156:159], v156 offset:3072
	s_add_u32 s20, s56, 0x40000
	s_addc_u32 s21, s57, 0
	s_mov_b32 m0, s62
	v_lshl_add_u64 v[230:231], s[20:21], 0, v[192:193]
	ds_read_b128 v[160:163], v227 offset:32768
	ds_read_b128 v[164:167], v227 offset:33792
	ds_read_b128 v[168:171], v227 offset:34816
	ds_read_b128 v[172:175], v227 offset:35840
	ds_read_b128 v[176:179], v227 offset:36864
	ds_read_b128 v[180:183], v227 offset:37888
	ds_read_b128 v[184:187], v227 offset:38912
	ds_read_b128 v[188:191], v227 offset:39936
	global_load_lds_dwordx4 v[230:231], off
	v_lshl_add_u64 v[230:231], s[20:21], 0, v[196:197]
	s_mov_b32 m0, s63
	s_nop 0
	global_load_lds_dwordx4 v[230:231], off
	s_waitcnt vmcnt(8)
	s_waitcnt lgkmcnt(0)
	s_barrier
	s_setprio 1
	s_waitcnt lgkmcnt(0)
	v_mfma_f32_16x16x32_bf16 v[76:79], v[128:131], v[160:163], v[76:79]
	v_mfma_f32_16x16x32_bf16 v[68:71], v[136:139], v[160:163], v[68:71]
	v_mfma_f32_16x16x32_bf16 v[60:63], v[128:131], v[168:171], v[60:63]
	v_mfma_f32_16x16x32_bf16 v[56:59], v[136:139], v[168:171], v[56:59]
	v_mfma_f32_16x16x32_bf16 v[52:55], v[128:131], v[176:179], v[52:55]
	v_mfma_f32_16x16x32_bf16 v[48:51], v[136:139], v[176:179], v[48:51]
	v_mfma_f32_16x16x32_bf16 v[44:47], v[128:131], v[184:187], v[44:47]
	v_mfma_f32_16x16x32_bf16 v[40:43], v[136:139], v[184:187], v[40:43]
	v_mfma_f32_16x16x32_bf16 v[76:79], v[132:135], v[164:167], v[76:79]
	v_mfma_f32_16x16x32_bf16 v[68:71], v[140:143], v[164:167], v[68:71]
	v_mfma_f32_16x16x32_bf16 v[60:63], v[132:135], v[172:175], v[60:63]
	v_mfma_f32_16x16x32_bf16 v[56:59], v[140:143], v[172:175], v[56:59]
	v_mfma_f32_16x16x32_bf16 v[52:55], v[132:135], v[180:183], v[52:55]
	v_mfma_f32_16x16x32_bf16 v[48:51], v[140:143], v[180:183], v[48:51]
	v_mfma_f32_16x16x32_bf16 v[44:47], v[132:135], v[188:191], v[44:47]
	v_mfma_f32_16x16x32_bf16 v[40:43], v[140:143], v[188:191], v[40:43]
	s_setprio 0
	s_setprio 1
	v_mfma_f32_16x16x32_bf16 v[124:127], v[144:147], v[160:163], v[124:127]
	v_mfma_f32_16x16x32_bf16 v[120:123], v[152:155], v[160:163], v[120:123]
	v_mfma_f32_16x16x32_bf16 v[116:119], v[144:147], v[168:171], v[116:119]
	v_mfma_f32_16x16x32_bf16 v[112:115], v[152:155], v[168:171], v[112:115]
	v_mfma_f32_16x16x32_bf16 v[108:111], v[144:147], v[176:179], v[108:111]
	v_mfma_f32_16x16x32_bf16 v[104:107], v[152:155], v[176:179], v[104:107]
	v_mfma_f32_16x16x32_bf16 v[100:103], v[144:147], v[184:187], v[100:103]
	v_mfma_f32_16x16x32_bf16 v[96:99], v[152:155], v[184:187], v[96:99]
	v_mfma_f32_16x16x32_bf16 v[124:127], v[148:151], v[164:167], v[124:127]
	v_mfma_f32_16x16x32_bf16 v[120:123], v[156:159], v[164:167], v[120:123]
	v_mfma_f32_16x16x32_bf16 v[116:119], v[148:151], v[172:175], v[116:119]
	v_mfma_f32_16x16x32_bf16 v[112:115], v[156:159], v[172:175], v[112:115]
	v_mfma_f32_16x16x32_bf16 v[108:111], v[148:151], v[180:183], v[108:111]
	v_mfma_f32_16x16x32_bf16 v[104:107], v[156:159], v[180:183], v[104:107]
	v_mfma_f32_16x16x32_bf16 v[100:103], v[148:151], v[188:191], v[100:103]
	v_mfma_f32_16x16x32_bf16 v[96:99], v[156:159], v[188:191], v[96:99]
	s_setprio 0
	s_barrier
	s_add_i32 s19, vcc_hi, s3
	v_lshl_add_u64 v[216:217], v[216:217], 0, s[26:27]
	s_mov_b32 m0, s19
	ds_read_b128 v[160:163], v227 offset:49152
	ds_read_b128 v[164:167], v227 offset:50176
	ds_read_b128 v[168:171], v227 offset:51200
	ds_read_b128 v[172:175], v227 offset:52224
	ds_read_b128 v[176:179], v227 offset:53248
	ds_read_b128 v[180:183], v227 offset:54272
	ds_read_b128 v[184:187], v227 offset:55296
	ds_read_b128 v[188:191], v227 offset:56320
	global_load_lds_dwordx4 v[216:217], off
	s_add_i32 m0, s19, 0x2000
	s_add_u32 s20, s54, 0x40080
	v_lshl_add_u64 v[216:217], v[218:219], 0, s[26:27]
	s_addc_u32 s21, s55, 0
	s_add_i32 s18, s18, s3
	global_load_lds_dwordx4 v[216:217], off
	v_lshl_add_u64 v[216:217], s[20:21], 0, v[194:195]
	s_mov_b32 m0, s18
	s_nop 0
	global_load_lds_dwordx4 v[216:217], off
	v_lshl_add_u64 v[216:217], s[20:21], 0, v[198:199]
	s_add_i32 m0, s18, 0x2000
	s_nop 0
	global_load_lds_dwordx4 v[216:217], off
	v_lshl_add_u64 v[216:217], v[220:221], 0, s[26:27]
	s_mov_b32 m0, s68
	s_nop 0
	global_load_lds_dwordx4 v[216:217], off
	v_lshl_add_u64 v[216:217], v[222:223], 0, s[26:27]
	s_mov_b32 m0, s69
	s_nop 0
	global_load_lds_dwordx4 v[216:217], off
	s_waitcnt vmcnt(8)
	s_waitcnt lgkmcnt(0)
	s_barrier
	s_setprio 1
	s_waitcnt lgkmcnt(0)
	v_mfma_f32_16x16x32_bf16 v[28:31], v[128:131], v[160:163], v[28:31]
	v_mfma_f32_16x16x32_bf16 v[24:27], v[136:139], v[160:163], v[24:27]
	v_mfma_f32_16x16x32_bf16 v[20:23], v[128:131], v[168:171], v[20:23]
	v_mfma_f32_16x16x32_bf16 v[16:19], v[136:139], v[168:171], v[16:19]
	v_mfma_f32_16x16x32_bf16 v[12:15], v[128:131], v[176:179], v[12:15]
	v_mfma_f32_16x16x32_bf16 v[8:11], v[136:139], v[176:179], v[8:11]
	v_mfma_f32_16x16x32_bf16 v[4:7], v[128:131], v[184:187], v[4:7]
	v_mfma_f32_16x16x32_bf16 v[0:3], v[136:139], v[184:187], v[0:3]
	v_mfma_f32_16x16x32_bf16 v[28:31], v[132:135], v[164:167], v[28:31]
	v_mfma_f32_16x16x32_bf16 v[24:27], v[140:143], v[164:167], v[24:27]
	v_mfma_f32_16x16x32_bf16 v[20:23], v[132:135], v[172:175], v[20:23]
	v_mfma_f32_16x16x32_bf16 v[16:19], v[140:143], v[172:175], v[16:19]
	v_mfma_f32_16x16x32_bf16 v[12:15], v[132:135], v[180:183], v[12:15]
	v_mfma_f32_16x16x32_bf16 v[8:11], v[140:143], v[180:183], v[8:11]
	v_mfma_f32_16x16x32_bf16 v[4:7], v[132:135], v[188:191], v[4:7]
	v_mfma_f32_16x16x32_bf16 v[0:3], v[140:143], v[188:191], v[0:3]
	s_setprio 0
	s_setprio 1
	v_mfma_f32_16x16x32_bf16 v[92:95], v[144:147], v[160:163], v[92:95]
	v_mfma_f32_16x16x32_bf16 v[88:91], v[152:155], v[160:163], v[88:91]
	v_mfma_f32_16x16x32_bf16 v[84:87], v[144:147], v[168:171], v[84:87]
	v_mfma_f32_16x16x32_bf16 v[80:83], v[152:155], v[168:171], v[80:83]
	v_mfma_f32_16x16x32_bf16 v[72:75], v[144:147], v[176:179], v[72:75]
	v_mfma_f32_16x16x32_bf16 v[64:67], v[152:155], v[176:179], v[64:67]
	v_mfma_f32_16x16x32_bf16 v[36:39], v[144:147], v[184:187], v[36:39]
	v_mfma_f32_16x16x32_bf16 v[32:35], v[152:155], v[184:187], v[32:35]
	v_mfma_f32_16x16x32_bf16 v[92:95], v[148:151], v[164:167], v[92:95]
	v_mfma_f32_16x16x32_bf16 v[88:91], v[156:159], v[164:167], v[88:91]
	v_mfma_f32_16x16x32_bf16 v[84:87], v[148:151], v[172:175], v[84:87]
	v_mfma_f32_16x16x32_bf16 v[80:83], v[156:159], v[172:175], v[80:83]
	v_mfma_f32_16x16x32_bf16 v[72:75], v[148:151], v[180:183], v[72:75]
	v_mfma_f32_16x16x32_bf16 v[64:67], v[156:159], v[180:183], v[64:67]
	v_mfma_f32_16x16x32_bf16 v[36:39], v[148:151], v[188:191], v[36:39]
	v_mfma_f32_16x16x32_bf16 v[32:35], v[156:159], v[188:191], v[32:35]
	s_setprio 0
	s_barrier
	s_add_i32 vcc_lo, vcc_lo, 2
	s_add_u32 s52, s52, 0x100
	s_addc_u32 s53, s53, 0
	s_add_u32 s96, s96, 0x100
	s_addc_u32 s97, s97, 0
	s_cmp_gt_u32 vcc_lo, 13
	s_cbranch_scc0 .LBB0_267
	s_mov_b32 s100, 1
	s_and_b64 vcc, exec, s[28:29]
	s_cbranch_vccnz .LBB0_271
	v_lshl_add_u32 v216, s50, 8, v203
	s_cmp_lg_u32 s48, 32
	s_mov_b64 s[50:51], -1
	s_cbranch_scc1 .LBB0_272

.LBB0_1036:
	s_add_u32 s10, s94, 0x12800000
	s_addc_u32 s11, s95, 0
	s_add_u32 s12, s94, 0x1000
	s_addc_u32 s13, s95, 0
	s_lshl_b32 s1, s1, 5
	s_mov_b64 s[14:15], 0x80
	s_and_b32 s18, s1, 0x60
	s_add_i32 m0, s29, 0x18000
	v_lshl_add_u64 v[6:7], v[6:7], 0, s[14:15]
	s_lshl_b32 s17, s0, 13
	s_lshl_b32 s1, s18, 7
	s_waitcnt vmcnt(2)
	s_barrier
	global_load_lds_dwordx4 v[6:7], off
	v_lshl_add_u64 v[4:5], v[4:5], 0, s[14:15]
	s_add_i32 m0, s29, 0x1a000
	s_add_i32 s45, s29, 0x8000
	s_add_i32 s46, s29, 0xa000
	global_load_lds_dwordx4 v[4:5], off
	v_lshl_add_u64 v[0:1], v[0:1], 0, s[14:15]
	s_mov_b32 m0, s45
	s_add_u32 s4, s34, 0x40080
	global_load_lds_dwordx4 v[0:1], off
	v_lshl_add_u64 v[0:1], v[2:3], 0, s[14:15]
	s_mov_b32 m0, s46
	s_addc_u32 s5, s35, 0
	global_load_lds_dwordx4 v[0:1], off
	s_add_i32 m0, s29, 0x1c000
	v_lshl_add_u64 v[0:1], s[4:5], 0, v[178:179]
	global_load_lds_dwordx4 v[0:1], off
	v_lshl_add_u64 v[0:1], s[4:5], 0, v[182:183]
	s_add_i32 m0, s29, 0x1e000
	s_cmpk_lt_u32 s16, 0x100
	global_load_lds_dwordx4 v[0:1], off
	v_bfe_u32 v1, v8, 4, 2
	v_and_b32_e32 v0, 15, v8
	v_lshlrev_b32_e32 v2, 4, v1
	s_waitcnt vmcnt(0)
	v_lshl_or_b32 v204, s0, 6, v0
	v_lshl_or_b32 v0, v0, 6, v2
	v_lshlrev_b32_e32 v2, 2, v8
	v_and_b32_e32 v2, 32, v2
	v_bitop3_b32 v3, v0, s17, v2 bitop3:0xde
	v_bitop3_b32 v205, v0, s1, v2 bitop3:0xde
	v_lshlrev_b32_e32 v0, 14, v9
	v_and_b32_e32 v0, 0xffff8000, v0
	v_cmp_eq_u32_e64 s[0:1], 0, v1
	v_lshl_or_b32 v206, v1, 3, s18
	v_lshl_add_u32 v0, v10, 11, v0
	v_and_b32_e32 v1, 1, v9
	v_lshl_or_b32 v0, v1, 6, v0
	v_lshl_add_u32 v184, v11, 1, v0
	v_lshlrev_b32_e32 v0, 14, v12
	v_and_b32_e32 v0, 0xffff8000, v0
	v_lshl_add_u32 v0, v13, 11, v0
	v_and_b32_e32 v1, 1, v12
	s_waitcnt vmcnt(6)
	v_lshl_or_b32 v0, v1, 6, v0
	s_cselect_b64 s[16:17], -1, 0
	v_lshl_add_u32 v186, v14, 1, v0
	s_add_i32 s50, 0, 0x10000
	s_add_i32 s51, 0, 0x14000
	v_mbcnt_lo_u32_b32 v0, -1, 0
	s_ashr_i32 s47, s90, 31
	s_mov_b32 s48, s90
	s_ashr_i32 s49, s2, 31
	v_mov_b32_e32 v185, v179
	v_mov_b32_e32 v187, v179
	v_mov_b64_e32 v[188:189], 0x400
	v_mov_b64_e32 v[190:191], 0x3ff
	v_add_u32_e32 v207, s50, v205
	v_add_u32_e32 v209, s51, v205
	v_add_u32_e32 v210, 0, v3
	v_mbcnt_hi_u32_b32 v211, -1, v0
	s_barrier
	s_mov_b32 s100, 0
	s_branch .LBB0_1039

.LBB0_1045:
	s_ashr_i32 s21, s20, 31
	s_lshl_b64 s[22:23], s[20:21], 19
	s_add_u32 s22, s3, s22
	s_addc_u32 s23, s33, s23
	s_and_b64 s[24:25], s[4:5], exec
	s_cselect_b32 s21, s23, s31
	s_cselect_b32 s27, s22, s30
	s_ashr_i32 s19, s18, 31
	s_lshl_b64 s[24:25], s[18:19], 19
	s_add_u32 s24, s38, s24
	s_addc_u32 s25, s39, s25
	s_and_b64 s[36:37], s[4:5], exec
	s_cselect_b32 s19, s25, s35
	s_cselect_b32 s52, s24, s34
	s_add_u32 s30, s30, 0x40080
	s_addc_u32 s31, s31, 0
	s_add_u32 s53, s34, 0x100
	v_mov_b32_e32 v0, 0
	s_addc_u32 s54, s35, 0
	s_mov_b32 s55, -2
	s_waitcnt lgkmcnt(0)
	v_mov_b32_e32 v1, v0
	v_mov_b32_e32 v2, v0
	v_mov_b32_e32 v3, v0
	v_mov_b32_e32 v4, v0
	v_mov_b32_e32 v5, v0
	v_mov_b32_e32 v6, v0
	v_mov_b32_e32 v7, v0
	v_mov_b32_e32 v16, v0
	v_mov_b32_e32 v17, v0
	v_mov_b32_e32 v18, v0
	v_mov_b32_e32 v19, v0
	v_mov_b32_e32 v20, v0
	v_mov_b32_e32 v21, v0
	v_mov_b32_e32 v22, v0
	v_mov_b32_e32 v23, v0
	v_mov_b32_e32 v32, v0
	v_mov_b32_e32 v33, v0
	v_mov_b32_e32 v34, v0
	v_mov_b32_e32 v35, v0
	v_mov_b32_e32 v36, v0
	v_mov_b32_e32 v37, v0
	v_mov_b32_e32 v38, v0
	v_mov_b32_e32 v39, v0
	v_mov_b32_e32 v48, v0
	v_mov_b32_e32 v49, v0
	v_mov_b32_e32 v50, v0
	v_mov_b32_e32 v51, v0
	v_mov_b32_e32 v52, v0
	v_mov_b32_e32 v53, v0
	v_mov_b32_e32 v54, v0
	v_mov_b32_e32 v55, v0
	v_mov_b32_e32 v8, v0
	v_mov_b32_e32 v9, v0
	v_mov_b32_e32 v10, v0
	v_mov_b32_e32 v11, v0
	v_mov_b32_e32 v12, v0
	v_mov_b32_e32 v13, v0
	v_mov_b32_e32 v14, v0
	v_mov_b32_e32 v15, v0
	v_mov_b32_e32 v24, v0
	v_mov_b32_e32 v25, v0
	v_mov_b32_e32 v26, v0
	v_mov_b32_e32 v27, v0
	v_mov_b32_e32 v28, v0
	v_mov_b32_e32 v29, v0
	v_mov_b32_e32 v30, v0
	v_mov_b32_e32 v31, v0
	v_mov_b32_e32 v40, v0
	v_mov_b32_e32 v41, v0
	v_mov_b32_e32 v42, v0
	v_mov_b32_e32 v43, v0
	v_mov_b32_e32 v44, v0
	v_mov_b32_e32 v45, v0
	v_mov_b32_e32 v46, v0
	v_mov_b32_e32 v47, v0
	v_mov_b32_e32 v56, v0
	v_mov_b32_e32 v57, v0
	v_mov_b32_e32 v58, v0
	v_mov_b32_e32 v59, v0
	v_mov_b32_e32 v60, v0
	v_mov_b32_e32 v61, v0
	v_mov_b32_e32 v62, v0
	v_mov_b32_e32 v63, v0
	v_mov_b32_e32 v64, v0
	v_mov_b32_e32 v65, v0
	v_mov_b32_e32 v66, v0
	v_mov_b32_e32 v67, v0
	v_mov_b32_e32 v68, v0
	v_mov_b32_e32 v69, v0
	v_mov_b32_e32 v70, v0
	v_mov_b32_e32 v71, v0
	v_mov_b32_e32 v80, v0
	v_mov_b32_e32 v81, v0
	v_mov_b32_e32 v82, v0
	v_mov_b32_e32 v83, v0
	v_mov_b32_e32 v84, v0
	v_mov_b32_e32 v85, v0
	v_mov_b32_e32 v86, v0
	v_mov_b32_e32 v87, v0
	v_mov_b32_e32 v96, v0
	v_mov_b32_e32 v97, v0
	v_mov_b32_e32 v98, v0
	v_mov_b32_e32 v99, v0
	v_mov_b32_e32 v100, v0
	v_mov_b32_e32 v101, v0
	v_mov_b32_e32 v102, v0
	v_mov_b32_e32 v103, v0
	v_mov_b32_e32 v112, v0
	v_mov_b32_e32 v113, v0
	v_mov_b32_e32 v114, v0
	v_mov_b32_e32 v115, v0
	v_mov_b32_e32 v116, v0
	v_mov_b32_e32 v117, v0
	v_mov_b32_e32 v118, v0
	v_mov_b32_e32 v119, v0
	v_mov_b32_e32 v72, v0
	v_mov_b32_e32 v73, v0
	v_mov_b32_e32 v74, v0
	v_mov_b32_e32 v75, v0
	v_mov_b32_e32 v76, v0
	v_mov_b32_e32 v77, v0
	v_mov_b32_e32 v78, v0
	v_mov_b32_e32 v79, v0
	v_mov_b32_e32 v88, v0
	v_mov_b32_e32 v89, v0
	v_mov_b32_e32 v90, v0
	v_mov_b32_e32 v91, v0
	v_mov_b32_e32 v92, v0
	v_mov_b32_e32 v93, v0
	v_mov_b32_e32 v94, v0
	v_mov_b32_e32 v95, v0
	v_mov_b32_e32 v104, v0
	v_mov_b32_e32 v105, v0
	v_mov_b32_e32 v106, v0
	v_mov_b32_e32 v107, v0
	v_mov_b32_e32 v108, v0
	v_mov_b32_e32 v109, v0
	v_mov_b32_e32 v110, v0
	v_mov_b32_e32 v111, v0
	v_mov_b32_e32 v120, v0
	v_mov_b32_e32 v121, v0
	v_mov_b32_e32 v122, v0
	v_mov_b32_e32 v123, v0
	v_mov_b32_e32 v124, v0
	v_mov_b32_e32 v125, v0
	v_mov_b32_e32 v126, v0
	v_mov_b32_e32 v127, v0
	s_cmp_eq_u32 s100, 0
	s_cbranch_scc1 .LBB0_1046
	ds_read_b128 v[128:131], v207
	ds_read_b128 v[132:135], v207 offset:1024
	ds_read_b128 v[136:139], v207 offset:2048
	ds_read_b128 v[140:143], v207 offset:3072
	ds_read_b128 v[144:147], v209
	ds_read_b128 v[148:151], v209 offset:1024
	ds_read_b128 v[152:155], v209 offset:2048
	ds_read_b128 v[156:159], v209 offset:3072
	s_add_u32 s34, s30, 0xfffc0080
	s_addc_u32 s35, s31, -1
	s_cmp_eq_u32 s55, 12
	s_cselect_b32 s37, s21, s35
	s_cselect_b32 s36, s27, s34
	s_cselect_b32 s35, s19, s54
	s_cselect_b32 s34, s52, s53
	v_lshl_add_u64 v[216:217], s[30:31], 0, v[184:185]
	s_add_i32 m0, s29, 0xc000
	ds_read_b128 v[160:163], v210
	ds_read_b128 v[164:167], v210 offset:1024
	ds_read_b128 v[168:171], v210 offset:2048
	ds_read_b128 v[172:175], v210 offset:3072
	ds_read_b128 v[192:195], v210 offset:4096
	ds_read_b128 v[196:199], v210 offset:5120
	ds_read_b128 v[200:203], v210 offset:6144
	ds_read_b128 v[212:215], v210 offset:7168
	global_load_lds_dwordx4 v[216:217], off
	v_lshl_add_u64 v[216:217], s[30:31], 0, v[186:187]
	s_add_i32 m0, s29, 0xe000
	s_nop 0
	global_load_lds_dwordx4 v[216:217], off
	s_waitcnt vmcnt(24)
	s_waitcnt lgkmcnt(0)
	s_barrier
	s_setprio 1
	s_waitcnt lgkmcnt(0)
	v_mfma_f32_16x16x32_bf16 v[124:127], v[128:131], v[160:163], v[124:127]
	v_mfma_f32_16x16x32_bf16 v[120:123], v[136:139], v[160:163], v[120:123]
	v_mfma_f32_16x16x32_bf16 v[108:111], v[128:131], v[168:171], v[108:111]
	v_mfma_f32_16x16x32_bf16 v[104:107], v[136:139], v[168:171], v[104:107]
	v_mfma_f32_16x16x32_bf16 v[92:95], v[128:131], v[192:195], v[92:95]
	v_mfma_f32_16x16x32_bf16 v[88:91], v[136:139], v[192:195], v[88:91]
	v_mfma_f32_16x16x32_bf16 v[76:79], v[128:131], v[200:203], v[76:79]
	v_mfma_f32_16x16x32_bf16 v[72:75], v[136:139], v[200:203], v[72:75]
	v_mfma_f32_16x16x32_bf16 v[124:127], v[132:135], v[164:167], v[124:127]
	v_mfma_f32_16x16x32_bf16 v[120:123], v[140:143], v[164:167], v[120:123]
	v_mfma_f32_16x16x32_bf16 v[108:111], v[132:135], v[172:175], v[108:111]
	v_mfma_f32_16x16x32_bf16 v[104:107], v[140:143], v[172:175], v[104:107]
	v_mfma_f32_16x16x32_bf16 v[92:95], v[132:135], v[196:199], v[92:95]
	v_mfma_f32_16x16x32_bf16 v[88:91], v[140:143], v[196:199], v[88:91]
	v_mfma_f32_16x16x32_bf16 v[76:79], v[132:135], v[212:215], v[76:79]
	v_mfma_f32_16x16x32_bf16 v[72:75], v[140:143], v[212:215], v[72:75]
	s_setprio 0
	s_setprio 1
	v_mfma_f32_16x16x32_bf16 v[116:119], v[144:147], v[160:163], v[116:119]
	v_mfma_f32_16x16x32_bf16 v[112:115], v[152:155], v[160:163], v[112:115]
	v_mfma_f32_16x16x32_bf16 v[100:103], v[144:147], v[168:171], v[100:103]
	v_mfma_f32_16x16x32_bf16 v[96:99], v[152:155], v[168:171], v[96:99]
	v_mfma_f32_16x16x32_bf16 v[84:87], v[144:147], v[192:195], v[84:87]
	v_mfma_f32_16x16x32_bf16 v[80:83], v[152:155], v[192:195], v[80:83]
	v_mfma_f32_16x16x32_bf16 v[68:71], v[144:147], v[200:203], v[68:71]
	v_mfma_f32_16x16x32_bf16 v[64:67], v[152:155], v[200:203], v[64:67]
	v_mfma_f32_16x16x32_bf16 v[116:119], v[148:151], v[164:167], v[116:119]
	v_mfma_f32_16x16x32_bf16 v[112:115], v[156:159], v[164:167], v[112:115]
	v_mfma_f32_16x16x32_bf16 v[100:103], v[148:151], v[172:175], v[100:103]
	v_mfma_f32_16x16x32_bf16 v[96:99], v[156:159], v[172:175], v[96:99]
	v_mfma_f32_16x16x32_bf16 v[84:87], v[148:151], v[196:199], v[84:87]
	v_mfma_f32_16x16x32_bf16 v[80:83], v[156:159], v[196:199], v[80:83]
	v_mfma_f32_16x16x32_bf16 v[68:71], v[148:151], v[212:215], v[68:71]
	v_mfma_f32_16x16x32_bf16 v[64:67], v[156:159], v[212:215], v[64:67]
	s_setprio 0
	s_barrier
	s_add_i32 s56, s50, s40
	v_lshl_add_u64 v[216:217], s[34:35], 0, v[178:179]
	s_mov_b32 m0, s56
	ds_read_b128 v[160:163], v210 offset:16384
	ds_read_b128 v[164:167], v210 offset:17408
	ds_read_b128 v[168:171], v210 offset:18432
	ds_read_b128 v[172:175], v210 offset:19456
	ds_read_b128 v[192:195], v210 offset:20480
	ds_read_b128 v[196:199], v210 offset:21504
	ds_read_b128 v[200:203], v210 offset:22528
	ds_read_b128 v[212:215], v210 offset:23552
	global_load_lds_dwordx4 v[216:217], off
	s_add_i32 m0, s56, 0x2000
	s_add_u32 s56, s34, 0x40000
	v_lshl_add_u64 v[218:219], s[34:35], 0, v[182:183]
	s_addc_u32 s57, s35, 0
	s_add_i32 s58, s51, s40
	global_load_lds_dwordx4 v[218:219], off
	v_lshl_add_u64 v[220:221], s[56:57], 0, v[178:179]
	s_mov_b32 m0, s58
	v_lshl_add_u64 v[222:223], s[36:37], 0, v[180:181]
	global_load_lds_dwordx4 v[220:221], off
	v_lshl_add_u64 v[220:221], s[56:57], 0, v[182:183]
	s_add_i32 m0, s58, 0x2000
	s_nop 0
	global_load_lds_dwordx4 v[220:221], off
	v_lshl_add_u64 v[220:221], s[36:37], 0, v[176:177]
	s_mov_b32 m0, s29
	s_nop 0
	global_load_lds_dwordx4 v[220:221], off
	s_mov_b32 m0, s41
	s_nop 0
	global_load_lds_dwordx4 v[222:223], off
	s_waitcnt vmcnt(24)
	s_waitcnt lgkmcnt(0)
	s_barrier
	s_setprio 1
	s_waitcnt lgkmcnt(0)
	v_mfma_f32_16x16x32_bf16 v[60:63], v[128:131], v[160:163], v[60:63]
	v_mfma_f32_16x16x32_bf16 v[56:59], v[136:139], v[160:163], v[56:59]
	v_mfma_f32_16x16x32_bf16 v[44:47], v[128:131], v[168:171], v[44:47]
	v_mfma_f32_16x16x32_bf16 v[40:43], v[136:139], v[168:171], v[40:43]
	v_mfma_f32_16x16x32_bf16 v[28:31], v[128:131], v[192:195], v[28:31]
	v_mfma_f32_16x16x32_bf16 v[24:27], v[136:139], v[192:195], v[24:27]
	v_mfma_f32_16x16x32_bf16 v[12:15], v[128:131], v[200:203], v[12:15]
	v_mfma_f32_16x16x32_bf16 v[8:11], v[136:139], v[200:203], v[8:11]
	v_mfma_f32_16x16x32_bf16 v[60:63], v[132:135], v[164:167], v[60:63]
	v_mfma_f32_16x16x32_bf16 v[56:59], v[140:143], v[164:167], v[56:59]
	v_mfma_f32_16x16x32_bf16 v[44:47], v[132:135], v[172:175], v[44:47]
	v_mfma_f32_16x16x32_bf16 v[40:43], v[140:143], v[172:175], v[40:43]
	v_mfma_f32_16x16x32_bf16 v[28:31], v[132:135], v[196:199], v[28:31]
	v_mfma_f32_16x16x32_bf16 v[24:27], v[140:143], v[196:199], v[24:27]
	v_mfma_f32_16x16x32_bf16 v[12:15], v[132:135], v[212:215], v[12:15]
	v_mfma_f32_16x16x32_bf16 v[8:11], v[140:143], v[212:215], v[8:11]
	s_setprio 0
	s_setprio 1
	v_mfma_f32_16x16x32_bf16 v[52:55], v[144:147], v[160:163], v[52:55]
	v_mfma_f32_16x16x32_bf16 v[48:51], v[152:155], v[160:163], v[48:51]
	v_mfma_f32_16x16x32_bf16 v[36:39], v[144:147], v[168:171], v[36:39]
	v_mfma_f32_16x16x32_bf16 v[32:35], v[152:155], v[168:171], v[32:35]
	v_mfma_f32_16x16x32_bf16 v[20:23], v[144:147], v[192:195], v[20:23]
	v_mfma_f32_16x16x32_bf16 v[16:19], v[152:155], v[192:195], v[16:19]
	v_mfma_f32_16x16x32_bf16 v[4:7], v[144:147], v[200:203], v[4:7]
	v_mfma_f32_16x16x32_bf16 v[0:3], v[152:155], v[200:203], v[0:3]
	v_mfma_f32_16x16x32_bf16 v[52:55], v[148:151], v[164:167], v[52:55]
	v_mfma_f32_16x16x32_bf16 v[48:51], v[156:159], v[164:167], v[48:51]
	v_mfma_f32_16x16x32_bf16 v[36:39], v[148:151], v[172:175], v[36:39]
	v_mfma_f32_16x16x32_bf16 v[32:35], v[156:159], v[172:175], v[32:35]
	v_mfma_f32_16x16x32_bf16 v[20:23], v[148:151], v[196:199], v[20:23]
	v_mfma_f32_16x16x32_bf16 v[16:19], v[156:159], v[196:199], v[16:19]
	v_mfma_f32_16x16x32_bf16 v[4:7], v[148:151], v[212:215], v[4:7]
	v_mfma_f32_16x16x32_bf16 v[0:3], v[156:159], v[212:215], v[0:3]
	s_setprio 0
	s_barrier
	s_add_i32 s56, 0, 0x18000
	s_add_i32 s57, 0, 0x1c000
	v_add_u32_e32 v140, s56, v205
	v_add_u32_e32 v156, s57, v205
	ds_read_b128 v[128:131], v140
	ds_read_b128 v[132:135], v140 offset:1024
	ds_read_b128 v[136:139], v140 offset:2048
	ds_read_b128 v[140:143], v140 offset:3072
	ds_read_b128 v[144:147], v156
	ds_read_b128 v[148:151], v156 offset:1024
	ds_read_b128 v[152:155], v156 offset:2048
	ds_read_b128 v[156:159], v156 offset:3072
	s_add_u32 s36, s36, 0x40000
	s_addc_u32 s37, s37, 0
	s_mov_b32 m0, s42
	v_lshl_add_u64 v[224:225], s[36:37], 0, v[176:177]
	ds_read_b128 v[160:163], v210 offset:32768
	ds_read_b128 v[164:167], v210 offset:33792
	ds_read_b128 v[168:171], v210 offset:34816
	ds_read_b128 v[172:175], v210 offset:35840
	ds_read_b128 v[192:195], v210 offset:36864
	ds_read_b128 v[196:199], v210 offset:37888
	ds_read_b128 v[200:203], v210 offset:38912
	ds_read_b128 v[212:215], v210 offset:39936
	global_load_lds_dwordx4 v[224:225], off
	v_lshl_add_u64 v[224:225], s[36:37], 0, v[180:181]
	s_mov_b32 m0, s43
	s_nop 0
	global_load_lds_dwordx4 v[224:225], off
	s_waitcnt vmcnt(8)
	s_waitcnt lgkmcnt(0)
	s_barrier
	s_setprio 1
	s_waitcnt lgkmcnt(0)
	v_mfma_f32_16x16x32_bf16 v[124:127], v[128:131], v[160:163], v[124:127]
	v_mfma_f32_16x16x32_bf16 v[120:123], v[136:139], v[160:163], v[120:123]
	v_mfma_f32_16x16x32_bf16 v[108:111], v[128:131], v[168:171], v[108:111]
	v_mfma_f32_16x16x32_bf16 v[104:107], v[136:139], v[168:171], v[104:107]
	v_mfma_f32_16x16x32_bf16 v[92:95], v[128:131], v[192:195], v[92:95]
	v_mfma_f32_16x16x32_bf16 v[88:91], v[136:139], v[192:195], v[88:91]
	v_mfma_f32_16x16x32_bf16 v[76:79], v[128:131], v[200:203], v[76:79]
	v_mfma_f32_16x16x32_bf16 v[72:75], v[136:139], v[200:203], v[72:75]
	v_mfma_f32_16x16x32_bf16 v[124:127], v[132:135], v[164:167], v[124:127]
	v_mfma_f32_16x16x32_bf16 v[120:123], v[140:143], v[164:167], v[120:123]
	v_mfma_f32_16x16x32_bf16 v[108:111], v[132:135], v[172:175], v[108:111]
	v_mfma_f32_16x16x32_bf16 v[104:107], v[140:143], v[172:175], v[104:107]
	v_mfma_f32_16x16x32_bf16 v[92:95], v[132:135], v[196:199], v[92:95]
	v_mfma_f32_16x16x32_bf16 v[88:91], v[140:143], v[196:199], v[88:91]
	v_mfma_f32_16x16x32_bf16 v[76:79], v[132:135], v[212:215], v[76:79]
	v_mfma_f32_16x16x32_bf16 v[72:75], v[140:143], v[212:215], v[72:75]
	s_setprio 0
	s_setprio 1
	v_mfma_f32_16x16x32_bf16 v[116:119], v[144:147], v[160:163], v[116:119]
	v_mfma_f32_16x16x32_bf16 v[112:115], v[152:155], v[160:163], v[112:115]
	v_mfma_f32_16x16x32_bf16 v[100:103], v[144:147], v[168:171], v[100:103]
	v_mfma_f32_16x16x32_bf16 v[96:99], v[152:155], v[168:171], v[96:99]
	v_mfma_f32_16x16x32_bf16 v[84:87], v[144:147], v[192:195], v[84:87]
	v_mfma_f32_16x16x32_bf16 v[80:83], v[152:155], v[192:195], v[80:83]
	v_mfma_f32_16x16x32_bf16 v[68:71], v[144:147], v[200:203], v[68:71]
	v_mfma_f32_16x16x32_bf16 v[64:67], v[152:155], v[200:203], v[64:67]
	v_mfma_f32_16x16x32_bf16 v[116:119], v[148:151], v[164:167], v[116:119]
	v_mfma_f32_16x16x32_bf16 v[112:115], v[156:159], v[164:167], v[112:115]
	v_mfma_f32_16x16x32_bf16 v[100:103], v[148:151], v[172:175], v[100:103]
	v_mfma_f32_16x16x32_bf16 v[96:99], v[156:159], v[172:175], v[96:99]
	v_mfma_f32_16x16x32_bf16 v[84:87], v[148:151], v[196:199], v[84:87]
	v_mfma_f32_16x16x32_bf16 v[80:83], v[156:159], v[196:199], v[80:83]
	v_mfma_f32_16x16x32_bf16 v[68:71], v[148:151], v[212:215], v[68:71]
	v_mfma_f32_16x16x32_bf16 v[64:67], v[156:159], v[212:215], v[64:67]
	s_setprio 0
	s_barrier
	s_add_i32 s36, s56, s40
	v_lshl_add_u64 v[216:217], v[216:217], 0, s[14:15]
	s_mov_b32 m0, s36
	ds_read_b128 v[160:163], v210 offset:49152
	ds_read_b128 v[164:167], v210 offset:50176
	ds_read_b128 v[168:171], v210 offset:51200
	ds_read_b128 v[172:175], v210 offset:52224
	ds_read_b128 v[192:195], v210 offset:53248
	ds_read_b128 v[196:199], v210 offset:54272
	ds_read_b128 v[200:203], v210 offset:55296
	ds_read_b128 v[212:215], v210 offset:56320
	global_load_lds_dwordx4 v[216:217], off
	s_add_i32 m0, s36, 0x2000
	s_add_u32 s34, s34, 0x40080
	v_lshl_add_u64 v[216:217], v[218:219], 0, s[14:15]
	s_addc_u32 s35, s35, 0
	s_add_i32 s36, s57, s40
	global_load_lds_dwordx4 v[216:217], off
	v_lshl_add_u64 v[216:217], s[34:35], 0, v[178:179]
	s_mov_b32 m0, s36
	s_nop 0
	global_load_lds_dwordx4 v[216:217], off
	v_lshl_add_u64 v[216:217], s[34:35], 0, v[182:183]
	s_add_i32 m0, s36, 0x2000
	s_nop 0
	global_load_lds_dwordx4 v[216:217], off
	v_lshl_add_u64 v[216:217], v[220:221], 0, s[14:15]
	s_mov_b32 m0, s45
	s_nop 0
	global_load_lds_dwordx4 v[216:217], off
	v_lshl_add_u64 v[216:217], v[222:223], 0, s[14:15]
	s_mov_b32 m0, s46
	s_nop 0
	global_load_lds_dwordx4 v[216:217], off
	s_waitcnt vmcnt(8)
	s_waitcnt lgkmcnt(0)
	s_barrier
	s_setprio 1
	s_waitcnt lgkmcnt(0)
	v_mfma_f32_16x16x32_bf16 v[60:63], v[128:131], v[160:163], v[60:63]
	v_mfma_f32_16x16x32_bf16 v[56:59], v[136:139], v[160:163], v[56:59]
	v_mfma_f32_16x16x32_bf16 v[44:47], v[128:131], v[168:171], v[44:47]
	v_mfma_f32_16x16x32_bf16 v[40:43], v[136:139], v[168:171], v[40:43]
	v_mfma_f32_16x16x32_bf16 v[28:31], v[128:131], v[192:195], v[28:31]
	v_mfma_f32_16x16x32_bf16 v[24:27], v[136:139], v[192:195], v[24:27]
	v_mfma_f32_16x16x32_bf16 v[12:15], v[128:131], v[200:203], v[12:15]
	v_mfma_f32_16x16x32_bf16 v[8:11], v[136:139], v[200:203], v[8:11]
	v_mfma_f32_16x16x32_bf16 v[60:63], v[132:135], v[164:167], v[60:63]
	v_mfma_f32_16x16x32_bf16 v[56:59], v[140:143], v[164:167], v[56:59]
	v_mfma_f32_16x16x32_bf16 v[44:47], v[132:135], v[172:175], v[44:47]
	v_mfma_f32_16x16x32_bf16 v[40:43], v[140:143], v[172:175], v[40:43]
	v_mfma_f32_16x16x32_bf16 v[28:31], v[132:135], v[196:199], v[28:31]
	v_mfma_f32_16x16x32_bf16 v[24:27], v[140:143], v[196:199], v[24:27]
	v_mfma_f32_16x16x32_bf16 v[12:15], v[132:135], v[212:215], v[12:15]
	v_mfma_f32_16x16x32_bf16 v[8:11], v[140:143], v[212:215], v[8:11]
	s_setprio 0
	s_setprio 1
	v_mfma_f32_16x16x32_bf16 v[52:55], v[144:147], v[160:163], v[52:55]
	v_mfma_f32_16x16x32_bf16 v[48:51], v[152:155], v[160:163], v[48:51]
	v_mfma_f32_16x16x32_bf16 v[36:39], v[144:147], v[168:171], v[36:39]
	v_mfma_f32_16x16x32_bf16 v[32:35], v[152:155], v[168:171], v[32:35]
	v_mfma_f32_16x16x32_bf16 v[20:23], v[144:147], v[192:195], v[20:23]
	v_mfma_f32_16x16x32_bf16 v[16:19], v[152:155], v[192:195], v[16:19]
	v_mfma_f32_16x16x32_bf16 v[4:7], v[144:147], v[200:203], v[4:7]
	v_mfma_f32_16x16x32_bf16 v[0:3], v[152:155], v[200:203], v[0:3]
	v_mfma_f32_16x16x32_bf16 v[52:55], v[148:151], v[164:167], v[52:55]
	v_mfma_f32_16x16x32_bf16 v[48:51], v[156:159], v[164:167], v[48:51]
	v_mfma_f32_16x16x32_bf16 v[36:39], v[148:151], v[172:175], v[36:39]
	v_mfma_f32_16x16x32_bf16 v[32:35], v[156:159], v[172:175], v[32:35]
	v_mfma_f32_16x16x32_bf16 v[20:23], v[148:151], v[196:199], v[20:23]
	v_mfma_f32_16x16x32_bf16 v[16:19], v[156:159], v[196:199], v[16:19]
	v_mfma_f32_16x16x32_bf16 v[4:7], v[148:151], v[212:215], v[4:7]
	v_mfma_f32_16x16x32_bf16 v[0:3], v[156:159], v[212:215], v[0:3]
	s_setprio 0
	s_barrier
	s_add_i32 s55, s55, 2
	s_add_u32 s30, s30, 0x100
	s_addc_u32 s31, s31, 0
	s_add_u32 s53, s53, 0x100
	s_addc_u32 s54, s54, 0
	s_cmp_gt_u32 s55, 13
	s_cbranch_scc0 .LBB0_1046
.LBB0_1046:
	ds_read_b128 v[128:131], v207
	ds_read_b128 v[132:135], v207 offset:1024
	ds_read_b128 v[136:139], v207 offset:2048
	ds_read_b128 v[140:143], v207 offset:3072
	ds_read_b128 v[144:147], v209
	ds_read_b128 v[148:151], v209 offset:1024
	ds_read_b128 v[152:155], v209 offset:2048
	ds_read_b128 v[156:159], v209 offset:3072
	s_add_u32 s34, s30, 0xfffc0080
	s_addc_u32 s35, s31, -1
	s_cmp_eq_u32 s55, 12
	s_cselect_b32 s37, s21, s35
	s_cselect_b32 s36, s27, s34
	s_cselect_b32 s35, s19, s54
	s_cselect_b32 s34, s52, s53
	v_lshl_add_u64 v[216:217], s[30:31], 0, v[184:185]
	s_add_i32 m0, s29, 0xc000
	ds_read_b128 v[160:163], v210
	ds_read_b128 v[164:167], v210 offset:1024
	ds_read_b128 v[168:171], v210 offset:2048
	ds_read_b128 v[172:175], v210 offset:3072
	ds_read_b128 v[192:195], v210 offset:4096
	ds_read_b128 v[196:199], v210 offset:5120
	ds_read_b128 v[200:203], v210 offset:6144
	ds_read_b128 v[212:215], v210 offset:7168
	global_load_lds_dwordx4 v[216:217], off
	v_lshl_add_u64 v[216:217], s[30:31], 0, v[186:187]
	s_add_i32 m0, s29, 0xe000
	s_nop 0
	global_load_lds_dwordx4 v[216:217], off
	s_waitcnt vmcnt(8)
	s_waitcnt lgkmcnt(0)
	s_barrier
	s_setprio 1
	s_waitcnt lgkmcnt(0)
	v_mfma_f32_16x16x32_bf16 v[124:127], v[128:131], v[160:163], v[124:127]
	v_mfma_f32_16x16x32_bf16 v[120:123], v[136:139], v[160:163], v[120:123]
	v_mfma_f32_16x16x32_bf16 v[108:111], v[128:131], v[168:171], v[108:111]
	v_mfma_f32_16x16x32_bf16 v[104:107], v[136:139], v[168:171], v[104:107]
	v_mfma_f32_16x16x32_bf16 v[92:95], v[128:131], v[192:195], v[92:95]
	v_mfma_f32_16x16x32_bf16 v[88:91], v[136:139], v[192:195], v[88:91]
	v_mfma_f32_16x16x32_bf16 v[76:79], v[128:131], v[200:203], v[76:79]
	v_mfma_f32_16x16x32_bf16 v[72:75], v[136:139], v[200:203], v[72:75]
	v_mfma_f32_16x16x32_bf16 v[124:127], v[132:135], v[164:167], v[124:127]
	v_mfma_f32_16x16x32_bf16 v[120:123], v[140:143], v[164:167], v[120:123]
	v_mfma_f32_16x16x32_bf16 v[108:111], v[132:135], v[172:175], v[108:111]
	v_mfma_f32_16x16x32_bf16 v[104:107], v[140:143], v[172:175], v[104:107]
	v_mfma_f32_16x16x32_bf16 v[92:95], v[132:135], v[196:199], v[92:95]
	v_mfma_f32_16x16x32_bf16 v[88:91], v[140:143], v[196:199], v[88:91]
	v_mfma_f32_16x16x32_bf16 v[76:79], v[132:135], v[212:215], v[76:79]
	v_mfma_f32_16x16x32_bf16 v[72:75], v[140:143], v[212:215], v[72:75]
	s_setprio 0
	s_setprio 1
	v_mfma_f32_16x16x32_bf16 v[116:119], v[144:147], v[160:163], v[116:119]
	v_mfma_f32_16x16x32_bf16 v[112:115], v[152:155], v[160:163], v[112:115]
	v_mfma_f32_16x16x32_bf16 v[100:103], v[144:147], v[168:171], v[100:103]
	v_mfma_f32_16x16x32_bf16 v[96:99], v[152:155], v[168:171], v[96:99]
	v_mfma_f32_16x16x32_bf16 v[84:87], v[144:147], v[192:195], v[84:87]
	v_mfma_f32_16x16x32_bf16 v[80:83], v[152:155], v[192:195], v[80:83]
	v_mfma_f32_16x16x32_bf16 v[68:71], v[144:147], v[200:203], v[68:71]
	v_mfma_f32_16x16x32_bf16 v[64:67], v[152:155], v[200:203], v[64:67]
	v_mfma_f32_16x16x32_bf16 v[116:119], v[148:151], v[164:167], v[116:119]
	v_mfma_f32_16x16x32_bf16 v[112:115], v[156:159], v[164:167], v[112:115]
	v_mfma_f32_16x16x32_bf16 v[100:103], v[148:151], v[172:175], v[100:103]
	v_mfma_f32_16x16x32_bf16 v[96:99], v[156:159], v[172:175], v[96:99]
	v_mfma_f32_16x16x32_bf16 v[84:87], v[148:151], v[196:199], v[84:87]
	v_mfma_f32_16x16x32_bf16 v[80:83], v[156:159], v[196:199], v[80:83]
	v_mfma_f32_16x16x32_bf16 v[68:71], v[148:151], v[212:215], v[68:71]
	v_mfma_f32_16x16x32_bf16 v[64:67], v[156:159], v[212:215], v[64:67]
	s_setprio 0
	s_barrier
	s_add_i32 s56, s50, s40
	v_lshl_add_u64 v[216:217], s[34:35], 0, v[178:179]
	s_mov_b32 m0, s56
	ds_read_b128 v[160:163], v210 offset:16384
	ds_read_b128 v[164:167], v210 offset:17408
	ds_read_b128 v[168:171], v210 offset:18432
	ds_read_b128 v[172:175], v210 offset:19456
	ds_read_b128 v[192:195], v210 offset:20480
	ds_read_b128 v[196:199], v210 offset:21504
	ds_read_b128 v[200:203], v210 offset:22528
	ds_read_b128 v[212:215], v210 offset:23552
	global_load_lds_dwordx4 v[216:217], off
	s_add_i32 m0, s56, 0x2000
	s_add_u32 s56, s34, 0x40000
	v_lshl_add_u64 v[218:219], s[34:35], 0, v[182:183]
	s_addc_u32 s57, s35, 0
	s_add_i32 s58, s51, s40
	global_load_lds_dwordx4 v[218:219], off
	v_lshl_add_u64 v[220:221], s[56:57], 0, v[178:179]
	s_mov_b32 m0, s58
	v_lshl_add_u64 v[222:223], s[36:37], 0, v[180:181]
	global_load_lds_dwordx4 v[220:221], off
	v_lshl_add_u64 v[220:221], s[56:57], 0, v[182:183]
	s_add_i32 m0, s58, 0x2000
	s_nop 0
	global_load_lds_dwordx4 v[220:221], off
	v_lshl_add_u64 v[220:221], s[36:37], 0, v[176:177]
	s_mov_b32 m0, s29
	s_nop 0
	global_load_lds_dwordx4 v[220:221], off
	s_mov_b32 m0, s41
	s_nop 0
	global_load_lds_dwordx4 v[222:223], off
	s_waitcnt vmcnt(8)
	s_waitcnt lgkmcnt(0)
	s_barrier
	s_setprio 1
	s_waitcnt lgkmcnt(0)
	v_mfma_f32_16x16x32_bf16 v[60:63], v[128:131], v[160:163], v[60:63]
	v_mfma_f32_16x16x32_bf16 v[56:59], v[136:139], v[160:163], v[56:59]
	v_mfma_f32_16x16x32_bf16 v[44:47], v[128:131], v[168:171], v[44:47]
	v_mfma_f32_16x16x32_bf16 v[40:43], v[136:139], v[168:171], v[40:43]
	v_mfma_f32_16x16x32_bf16 v[28:31], v[128:131], v[192:195], v[28:31]
	v_mfma_f32_16x16x32_bf16 v[24:27], v[136:139], v[192:195], v[24:27]
	v_mfma_f32_16x16x32_bf16 v[12:15], v[128:131], v[200:203], v[12:15]
	v_mfma_f32_16x16x32_bf16 v[8:11], v[136:139], v[200:203], v[8:11]
	v_mfma_f32_16x16x32_bf16 v[60:63], v[132:135], v[164:167], v[60:63]
	v_mfma_f32_16x16x32_bf16 v[56:59], v[140:143], v[164:167], v[56:59]
	v_mfma_f32_16x16x32_bf16 v[44:47], v[132:135], v[172:175], v[44:47]
	v_mfma_f32_16x16x32_bf16 v[40:43], v[140:143], v[172:175], v[40:43]
	v_mfma_f32_16x16x32_bf16 v[28:31], v[132:135], v[196:199], v[28:31]
	v_mfma_f32_16x16x32_bf16 v[24:27], v[140:143], v[196:199], v[24:27]
	v_mfma_f32_16x16x32_bf16 v[12:15], v[132:135], v[212:215], v[12:15]
	v_mfma_f32_16x16x32_bf16 v[8:11], v[140:143], v[212:215], v[8:11]
	s_setprio 0
	s_setprio 1
	v_mfma_f32_16x16x32_bf16 v[52:55], v[144:147], v[160:163], v[52:55]
	v_mfma_f32_16x16x32_bf16 v[48:51], v[152:155], v[160:163], v[48:51]
	v_mfma_f32_16x16x32_bf16 v[36:39], v[144:147], v[168:171], v[36:39]
	v_mfma_f32_16x16x32_bf16 v[32:35], v[152:155], v[168:171], v[32:35]
	v_mfma_f32_16x16x32_bf16 v[20:23], v[144:147], v[192:195], v[20:23]
	v_mfma_f32_16x16x32_bf16 v[16:19], v[152:155], v[192:195], v[16:19]
	v_mfma_f32_16x16x32_bf16 v[4:7], v[144:147], v[200:203], v[4:7]
	v_mfma_f32_16x16x32_bf16 v[0:3], v[152:155], v[200:203], v[0:3]
	v_mfma_f32_16x16x32_bf16 v[52:55], v[148:151], v[164:167], v[52:55]
	v_mfma_f32_16x16x32_bf16 v[48:51], v[156:159], v[164:167], v[48:51]
	v_mfma_f32_16x16x32_bf16 v[36:39], v[148:151], v[172:175], v[36:39]
	v_mfma_f32_16x16x32_bf16 v[32:35], v[156:159], v[172:175], v[32:35]
	v_mfma_f32_16x16x32_bf16 v[20:23], v[148:151], v[196:199], v[20:23]
	v_mfma_f32_16x16x32_bf16 v[16:19], v[156:159], v[196:199], v[16:19]
	v_mfma_f32_16x16x32_bf16 v[4:7], v[148:151], v[212:215], v[4:7]
	v_mfma_f32_16x16x32_bf16 v[0:3], v[156:159], v[212:215], v[0:3]
	s_setprio 0
	s_barrier
	s_add_i32 s56, 0, 0x18000
	s_add_i32 s57, 0, 0x1c000
	v_add_u32_e32 v140, s56, v205
	v_add_u32_e32 v156, s57, v205
	ds_read_b128 v[128:131], v140
	ds_read_b128 v[132:135], v140 offset:1024
	ds_read_b128 v[136:139], v140 offset:2048
	ds_read_b128 v[140:143], v140 offset:3072
	ds_read_b128 v[144:147], v156
	ds_read_b128 v[148:151], v156 offset:1024
	ds_read_b128 v[152:155], v156 offset:2048
	ds_read_b128 v[156:159], v156 offset:3072
	s_add_u32 s36, s36, 0x40000
	s_addc_u32 s37, s37, 0
	s_mov_b32 m0, s42
	v_lshl_add_u64 v[224:225], s[36:37], 0, v[176:177]
	ds_read_b128 v[160:163], v210 offset:32768
	ds_read_b128 v[164:167], v210 offset:33792
	ds_read_b128 v[168:171], v210 offset:34816
	ds_read_b128 v[172:175], v210 offset:35840
	ds_read_b128 v[192:195], v210 offset:36864
	ds_read_b128 v[196:199], v210 offset:37888
	ds_read_b128 v[200:203], v210 offset:38912
	ds_read_b128 v[212:215], v210 offset:39936
	global_load_lds_dwordx4 v[224:225], off
	v_lshl_add_u64 v[224:225], s[36:37], 0, v[180:181]
	s_mov_b32 m0, s43
	s_nop 0
	global_load_lds_dwordx4 v[224:225], off
	s_waitcnt vmcnt(8)
	s_waitcnt lgkmcnt(0)
	s_barrier
	s_setprio 1
	s_waitcnt lgkmcnt(0)
	v_mfma_f32_16x16x32_bf16 v[124:127], v[128:131], v[160:163], v[124:127]
	v_mfma_f32_16x16x32_bf16 v[120:123], v[136:139], v[160:163], v[120:123]
	v_mfma_f32_16x16x32_bf16 v[108:111], v[128:131], v[168:171], v[108:111]
	v_mfma_f32_16x16x32_bf16 v[104:107], v[136:139], v[168:171], v[104:107]
	v_mfma_f32_16x16x32_bf16 v[92:95], v[128:131], v[192:195], v[92:95]
	v_mfma_f32_16x16x32_bf16 v[88:91], v[136:139], v[192:195], v[88:91]
	v_mfma_f32_16x16x32_bf16 v[76:79], v[128:131], v[200:203], v[76:79]
	v_mfma_f32_16x16x32_bf16 v[72:75], v[136:139], v[200:203], v[72:75]
	v_mfma_f32_16x16x32_bf16 v[124:127], v[132:135], v[164:167], v[124:127]
	v_mfma_f32_16x16x32_bf16 v[120:123], v[140:143], v[164:167], v[120:123]
	v_mfma_f32_16x16x32_bf16 v[108:111], v[132:135], v[172:175], v[108:111]
	v_mfma_f32_16x16x32_bf16 v[104:107], v[140:143], v[172:175], v[104:107]
	v_mfma_f32_16x16x32_bf16 v[92:95], v[132:135], v[196:199], v[92:95]
	v_mfma_f32_16x16x32_bf16 v[88:91], v[140:143], v[196:199], v[88:91]
	v_mfma_f32_16x16x32_bf16 v[76:79], v[132:135], v[212:215], v[76:79]
	v_mfma_f32_16x16x32_bf16 v[72:75], v[140:143], v[212:215], v[72:75]
	s_setprio 0
	s_setprio 1
	v_mfma_f32_16x16x32_bf16 v[116:119], v[144:147], v[160:163], v[116:119]
	v_mfma_f32_16x16x32_bf16 v[112:115], v[152:155], v[160:163], v[112:115]
	v_mfma_f32_16x16x32_bf16 v[100:103], v[144:147], v[168:171], v[100:103]
	v_mfma_f32_16x16x32_bf16 v[96:99], v[152:155], v[168:171], v[96:99]
	v_mfma_f32_16x16x32_bf16 v[84:87], v[144:147], v[192:195], v[84:87]
	v_mfma_f32_16x16x32_bf16 v[80:83], v[152:155], v[192:195], v[80:83]
	v_mfma_f32_16x16x32_bf16 v[68:71], v[144:147], v[200:203], v[68:71]
	v_mfma_f32_16x16x32_bf16 v[64:67], v[152:155], v[200:203], v[64:67]
	v_mfma_f32_16x16x32_bf16 v[116:119], v[148:151], v[164:167], v[116:119]
	v_mfma_f32_16x16x32_bf16 v[112:115], v[156:159], v[164:167], v[112:115]
	v_mfma_f32_16x16x32_bf16 v[100:103], v[148:151], v[172:175], v[100:103]
	v_mfma_f32_16x16x32_bf16 v[96:99], v[156:159], v[172:175], v[96:99]
	v_mfma_f32_16x16x32_bf16 v[84:87], v[148:151], v[196:199], v[84:87]
	v_mfma_f32_16x16x32_bf16 v[80:83], v[156:159], v[196:199], v[80:83]
	v_mfma_f32_16x16x32_bf16 v[68:71], v[148:151], v[212:215], v[68:71]
	v_mfma_f32_16x16x32_bf16 v[64:67], v[156:159], v[212:215], v[64:67]
	s_setprio 0
	s_barrier
	s_add_i32 s36, s56, s40
	v_lshl_add_u64 v[216:217], v[216:217], 0, s[14:15]
	s_mov_b32 m0, s36
	ds_read_b128 v[160:163], v210 offset:49152
	ds_read_b128 v[164:167], v210 offset:50176
	ds_read_b128 v[168:171], v210 offset:51200
	ds_read_b128 v[172:175], v210 offset:52224
	ds_read_b128 v[192:195], v210 offset:53248
	ds_read_b128 v[196:199], v210 offset:54272
	ds_read_b128 v[200:203], v210 offset:55296
	ds_read_b128 v[212:215], v210 offset:56320
	global_load_lds_dwordx4 v[216:217], off
	s_add_i32 m0, s36, 0x2000
	s_add_u32 s34, s34, 0x40080
	v_lshl_add_u64 v[216:217], v[218:219], 0, s[14:15]
	s_addc_u32 s35, s35, 0
	s_add_i32 s36, s57, s40
	global_load_lds_dwordx4 v[216:217], off
	v_lshl_add_u64 v[216:217], s[34:35], 0, v[178:179]
	s_mov_b32 m0, s36
	s_nop 0
	global_load_lds_dwordx4 v[216:217], off
	v_lshl_add_u64 v[216:217], s[34:35], 0, v[182:183]
	s_add_i32 m0, s36, 0x2000
	s_nop 0
	global_load_lds_dwordx4 v[216:217], off
	v_lshl_add_u64 v[216:217], v[220:221], 0, s[14:15]
	s_mov_b32 m0, s45
	s_nop 0
	global_load_lds_dwordx4 v[216:217], off
	v_lshl_add_u64 v[216:217], v[222:223], 0, s[14:15]
	s_mov_b32 m0, s46
	s_nop 0
	global_load_lds_dwordx4 v[216:217], off
	s_waitcnt vmcnt(8)
	s_waitcnt lgkmcnt(0)
	s_barrier
	s_setprio 1
	s_waitcnt lgkmcnt(0)
	v_mfma_f32_16x16x32_bf16 v[60:63], v[128:131], v[160:163], v[60:63]
	v_mfma_f32_16x16x32_bf16 v[56:59], v[136:139], v[160:163], v[56:59]
	v_mfma_f32_16x16x32_bf16 v[44:47], v[128:131], v[168:171], v[44:47]
	v_mfma_f32_16x16x32_bf16 v[40:43], v[136:139], v[168:171], v[40:43]
	v_mfma_f32_16x16x32_bf16 v[28:31], v[128:131], v[192:195], v[28:31]
	v_mfma_f32_16x16x32_bf16 v[24:27], v[136:139], v[192:195], v[24:27]
	v_mfma_f32_16x16x32_bf16 v[12:15], v[128:131], v[200:203], v[12:15]
	v_mfma_f32_16x16x32_bf16 v[8:11], v[136:139], v[200:203], v[8:11]
	v_mfma_f32_16x16x32_bf16 v[60:63], v[132:135], v[164:167], v[60:63]
	v_mfma_f32_16x16x32_bf16 v[56:59], v[140:143], v[164:167], v[56:59]
	v_mfma_f32_16x16x32_bf16 v[44:47], v[132:135], v[172:175], v[44:47]
	v_mfma_f32_16x16x32_bf16 v[40:43], v[140:143], v[172:175], v[40:43]
	v_mfma_f32_16x16x32_bf16 v[28:31], v[132:135], v[196:199], v[28:31]
	v_mfma_f32_16x16x32_bf16 v[24:27], v[140:143], v[196:199], v[24:27]
	v_mfma_f32_16x16x32_bf16 v[12:15], v[132:135], v[212:215], v[12:15]
	v_mfma_f32_16x16x32_bf16 v[8:11], v[140:143], v[212:215], v[8:11]
	s_setprio 0
	s_setprio 1
	v_mfma_f32_16x16x32_bf16 v[52:55], v[144:147], v[160:163], v[52:55]
	v_mfma_f32_16x16x32_bf16 v[48:51], v[152:155], v[160:163], v[48:51]
	v_mfma_f32_16x16x32_bf16 v[36:39], v[144:147], v[168:171], v[36:39]
	v_mfma_f32_16x16x32_bf16 v[32:35], v[152:155], v[168:171], v[32:35]
	v_mfma_f32_16x16x32_bf16 v[20:23], v[144:147], v[192:195], v[20:23]
	v_mfma_f32_16x16x32_bf16 v[16:19], v[152:155], v[192:195], v[16:19]
	v_mfma_f32_16x16x32_bf16 v[4:7], v[144:147], v[200:203], v[4:7]
	v_mfma_f32_16x16x32_bf16 v[0:3], v[152:155], v[200:203], v[0:3]
	v_mfma_f32_16x16x32_bf16 v[52:55], v[148:151], v[164:167], v[52:55]
	v_mfma_f32_16x16x32_bf16 v[48:51], v[156:159], v[164:167], v[48:51]
	v_mfma_f32_16x16x32_bf16 v[36:39], v[148:151], v[172:175], v[36:39]
	v_mfma_f32_16x16x32_bf16 v[32:35], v[156:159], v[172:175], v[32:35]
	v_mfma_f32_16x16x32_bf16 v[20:23], v[148:151], v[196:199], v[20:23]
	v_mfma_f32_16x16x32_bf16 v[16:19], v[156:159], v[196:199], v[16:19]
	v_mfma_f32_16x16x32_bf16 v[4:7], v[148:151], v[212:215], v[4:7]
	v_mfma_f32_16x16x32_bf16 v[0:3], v[156:159], v[212:215], v[0:3]
	s_setprio 0
	s_barrier
	s_add_i32 s55, s55, 2
	s_add_u32 s30, s30, 0x100
	s_addc_u32 s31, s31, 0
	s_add_u32 s53, s53, 0x100
	s_addc_u32 s54, s54, 0
	s_cmp_gt_u32 s55, 13
	s_cbranch_scc0 .LBB0_1046
	s_mov_b32 s100, 1
	s_and_b64 vcc, exec, s[16:17]
	s_cbranch_vccz .LBB0_1049
	s_barrier

.LBB0_1123:
	s_add_u32 s10, s94, 0x1000
	s_addc_u32 s11, s95, 0
	s_add_u32 s12, s94, 0x1a800000
	s_addc_u32 s13, s95, 0
	s_lshl_b32 s5, s14, 5
	s_mov_b64 s[14:15], 0x80
	s_and_b32 s20, s5, 0x60
	s_add_i32 m0, s39, 0x18000
	v_lshl_add_u64 v[6:7], v[6:7], 0, s[14:15]
	s_lshl_b32 s17, s16, 13
	s_lshl_b32 s21, s20, 7
	s_waitcnt vmcnt(2)
	s_barrier
	global_load_lds_dwordx4 v[6:7], off
	v_lshl_add_u64 v[4:5], v[4:5], 0, s[14:15]
	s_add_i32 m0, s39, 0x1a000
	s_add_i32 s44, s39, 0x8000
	s_add_i32 s45, s39, 0xa000
	global_load_lds_dwordx4 v[4:5], off
	v_lshl_add_u64 v[0:1], v[0:1], 0, s[14:15]
	s_mov_b32 m0, s44
	s_add_u32 s18, s28, 0x40080
	global_load_lds_dwordx4 v[0:1], off
	v_lshl_add_u64 v[0:1], v[2:3], 0, s[14:15]
	s_mov_b32 m0, s45
	s_addc_u32 s19, s29, 0
	global_load_lds_dwordx4 v[0:1], off
	s_add_i32 m0, s39, 0x1c000
	v_lshl_add_u64 v[0:1], s[18:19], 0, v[132:133]
	global_load_lds_dwordx4 v[0:1], off
	v_lshl_add_u64 v[0:1], s[18:19], 0, v[128:129]
	s_add_i32 m0, s39, 0x1e000
	s_cmpk_lt_u32 s1, 0x100
	global_load_lds_dwordx4 v[0:1], off
	v_lshrrev_b32_e32 v1, 1, v9
	v_and_b32_e32 v1, 24, v1
	v_and_b32_e32 v0, 15, v9
	v_lshlrev_b32_e32 v2, 1, v1
	v_lshl_or_b32 v154, s16, 6, v0
	v_lshl_or_b32 v0, v0, 6, v2
	v_lshlrev_b32_e32 v2, 2, v9
	v_and_b32_e32 v2, 32, v2
	v_bitop3_b32 v3, v0, s17, v2 bitop3:0xde
	v_bitop3_b32 v155, v0, s21, v2 bitop3:0xde
	v_lshlrev_b32_e32 v0, 14, v13
	v_and_b32_e32 v0, 0xffff8000, v0
	v_or_b32_e32 v156, s20, v1
	v_lshl_add_u32 v0, v12, 11, v0
	v_and_b32_e32 v1, 1, v13
	v_lshl_or_b32 v0, v1, 6, v0
	v_lshl_add_u32 v136, v14, 1, v0
	v_lshlrev_b32_e32 v0, 14, v8
	v_and_b32_e32 v0, 0xffff8000, v0
	s_waitcnt vmcnt(6)
	v_lshl_add_u32 v0, v10, 11, v0
	v_and_b32_e32 v1, 1, v8
	s_cselect_b64 s[16:17], -1, 0
	v_lshl_or_b32 v0, v1, 6, v0
	s_add_i32 s48, 0, 0x10000
	s_add_i32 s49, 0, 0x14000
	s_sext_i32_i16 s5, s0
	s_ashr_i32 s46, s90, 31
	s_mov_b32 s47, s90
	v_mov_b32_e32 v137, v133
	v_lshl_add_u32 v138, v11, 1, v0
	v_mov_b32_e32 v139, v133
	v_mov_b64_e32 v[140:141], 0x1600
	v_mov_b64_e32 v[142:143], 0x15ff
	v_add_u32_e32 v157, s48, v155
	v_add_u32_e32 v158, s49, v155
	v_add_u32_e32 v159, 0, v3
	v_mov_b32_e32 v160, 0x358637bd
	s_mov_b32 s50, 0x800000
	s_movk_i32 s51, 0x1600
	s_barrier
	s_mov_b32 s100, 0
	s_branch .LBB0_1126

.LBB0_1128:
	s_ashr_i32 s21, s20, 31
	s_lshl_b64 s[22:23], s[20:21], 19
	s_add_u32 s22, s3, s22
	s_addc_u32 s23, s33, s23
	s_and_b64 s[24:25], s[0:1], exec
	s_cselect_b32 s21, s23, s27
	s_cselect_b32 s52, s22, s26
	s_ashr_i32 s19, s18, 31
	s_lshl_b64 s[24:25], s[18:19], 19
	s_add_u32 s24, s34, s24
	s_addc_u32 s25, s35, s25
	s_and_b64 s[30:31], s[0:1], exec
	s_cselect_b32 s19, s25, s29
	s_cselect_b32 s53, s24, s28
	s_add_u32 s26, s26, 0x40080
	s_addc_u32 s27, s27, 0
	s_add_u32 s54, s28, 0x100
	v_mov_b32_e32 v0, 0
	s_addc_u32 s55, s29, 0
	s_mov_b32 s56, -2
	v_mov_b32_e32 v1, v0
	v_mov_b32_e32 v2, v0
	v_mov_b32_e32 v3, v0
	v_mov_b32_e32 v4, v0
	v_mov_b32_e32 v5, v0
	v_mov_b32_e32 v6, v0
	v_mov_b32_e32 v7, v0
	v_mov_b32_e32 v16, v0
	v_mov_b32_e32 v17, v0
	v_mov_b32_e32 v18, v0
	v_mov_b32_e32 v19, v0
	v_mov_b32_e32 v20, v0
	v_mov_b32_e32 v21, v0
	v_mov_b32_e32 v22, v0
	v_mov_b32_e32 v23, v0
	v_mov_b32_e32 v32, v0
	v_mov_b32_e32 v33, v0
	v_mov_b32_e32 v34, v0
	v_mov_b32_e32 v35, v0
	v_mov_b32_e32 v36, v0
	v_mov_b32_e32 v37, v0
	v_mov_b32_e32 v38, v0
	v_mov_b32_e32 v39, v0
	v_mov_b32_e32 v48, v0
	v_mov_b32_e32 v49, v0
	v_mov_b32_e32 v50, v0
	v_mov_b32_e32 v51, v0
	v_mov_b32_e32 v52, v0
	v_mov_b32_e32 v53, v0
	v_mov_b32_e32 v54, v0
	v_mov_b32_e32 v55, v0
	v_mov_b32_e32 v8, v0
	v_mov_b32_e32 v9, v0
	v_mov_b32_e32 v10, v0
	v_mov_b32_e32 v11, v0
	v_mov_b32_e32 v12, v0
	v_mov_b32_e32 v13, v0
	v_mov_b32_e32 v14, v0
	v_mov_b32_e32 v15, v0
	v_mov_b32_e32 v24, v0
	v_mov_b32_e32 v25, v0
	v_mov_b32_e32 v26, v0
	v_mov_b32_e32 v27, v0
	v_mov_b32_e32 v28, v0
	v_mov_b32_e32 v29, v0
	v_mov_b32_e32 v30, v0
	v_mov_b32_e32 v31, v0
	v_mov_b32_e32 v40, v0
	v_mov_b32_e32 v41, v0
	v_mov_b32_e32 v42, v0
	v_mov_b32_e32 v43, v0
	v_mov_b32_e32 v44, v0
	v_mov_b32_e32 v45, v0
	v_mov_b32_e32 v46, v0
	v_mov_b32_e32 v47, v0
	v_mov_b32_e32 v56, v0
	v_mov_b32_e32 v57, v0
	v_mov_b32_e32 v58, v0
	v_mov_b32_e32 v59, v0
	v_mov_b32_e32 v60, v0
	v_mov_b32_e32 v61, v0
	v_mov_b32_e32 v62, v0
	v_mov_b32_e32 v63, v0
	v_mov_b32_e32 v64, v0
	v_mov_b32_e32 v65, v0
	v_mov_b32_e32 v66, v0
	v_mov_b32_e32 v67, v0
	v_mov_b32_e32 v68, v0
	v_mov_b32_e32 v69, v0
	v_mov_b32_e32 v70, v0
	v_mov_b32_e32 v71, v0
	v_mov_b32_e32 v80, v0
	v_mov_b32_e32 v81, v0
	v_mov_b32_e32 v82, v0
	v_mov_b32_e32 v83, v0
	v_mov_b32_e32 v84, v0
	v_mov_b32_e32 v85, v0
	v_mov_b32_e32 v86, v0
	v_mov_b32_e32 v87, v0
	v_mov_b32_e32 v96, v0
	v_mov_b32_e32 v97, v0
	v_mov_b32_e32 v98, v0
	v_mov_b32_e32 v99, v0
	v_mov_b32_e32 v100, v0
	v_mov_b32_e32 v101, v0
	v_mov_b32_e32 v102, v0
	v_mov_b32_e32 v103, v0
	v_mov_b32_e32 v112, v0
	v_mov_b32_e32 v113, v0
	v_mov_b32_e32 v114, v0
	v_mov_b32_e32 v115, v0
	v_mov_b32_e32 v116, v0
	v_mov_b32_e32 v117, v0
	v_mov_b32_e32 v118, v0
	v_mov_b32_e32 v119, v0
	v_mov_b32_e32 v72, v0
	v_mov_b32_e32 v73, v0
	v_mov_b32_e32 v74, v0
	v_mov_b32_e32 v75, v0
	v_mov_b32_e32 v76, v0
	v_mov_b32_e32 v77, v0
	v_mov_b32_e32 v78, v0
	v_mov_b32_e32 v79, v0
	v_mov_b32_e32 v88, v0
	v_mov_b32_e32 v89, v0
	v_mov_b32_e32 v90, v0
	v_mov_b32_e32 v91, v0
	v_mov_b32_e32 v92, v0
	v_mov_b32_e32 v93, v0
	v_mov_b32_e32 v94, v0
	v_mov_b32_e32 v95, v0
	v_mov_b32_e32 v104, v0
	v_mov_b32_e32 v105, v0
	v_mov_b32_e32 v106, v0
	v_mov_b32_e32 v107, v0
	v_mov_b32_e32 v108, v0
	v_mov_b32_e32 v109, v0
	v_mov_b32_e32 v110, v0
	v_mov_b32_e32 v111, v0
	v_mov_b32_e32 v120, v0
	v_mov_b32_e32 v121, v0
	v_mov_b32_e32 v122, v0
	v_mov_b32_e32 v123, v0
	v_mov_b32_e32 v124, v0
	v_mov_b32_e32 v125, v0
	v_mov_b32_e32 v126, v0
	v_mov_b32_e32 v127, v0
	s_cmp_eq_u32 s100, 0
	s_cbranch_scc1 .LBB0_1129
	ds_read_b128 v[144:147], v157
	ds_read_b128 v[148:151], v157 offset:1024
	ds_read_b128 v[162:165], v157 offset:2048
	ds_read_b128 v[166:169], v157 offset:3072
	ds_read_b128 v[170:173], v158
	ds_read_b128 v[174:177], v158 offset:1024
	ds_read_b128 v[178:181], v158 offset:2048
	ds_read_b128 v[182:185], v158 offset:3072
	s_add_u32 s28, s26, 0xfffc0080
	s_addc_u32 s29, s27, -1
	s_cmp_eq_u32 s56, 12
	s_cselect_b32 s31, s21, s29
	s_cselect_b32 s30, s52, s28
	s_cselect_b32 s29, s19, s55
	s_cselect_b32 s28, s53, s54
	v_lshl_add_u64 v[152:153], s[26:27], 0, v[136:137]
	s_add_i32 m0, s39, 0xc000
	ds_read_b128 v[186:189], v159
	ds_read_b128 v[190:193], v159 offset:1024
	ds_read_b128 v[194:197], v159 offset:2048
	ds_read_b128 v[198:201], v159 offset:3072
	ds_read_b128 v[202:205], v159 offset:4096
	ds_read_b128 v[210:213], v159 offset:5120
	ds_read_b128 v[214:217], v159 offset:6144
	ds_read_b128 v[218:221], v159 offset:7168
	global_load_lds_dwordx4 v[152:153], off
	v_lshl_add_u64 v[152:153], s[26:27], 0, v[138:139]
	s_add_i32 m0, s39, 0xe000
	s_nop 0
	global_load_lds_dwordx4 v[152:153], off
	s_waitcnt vmcnt(24)
	s_waitcnt lgkmcnt(0)
	s_barrier
	s_setprio 1
	s_waitcnt lgkmcnt(0)
	v_mfma_f32_16x16x32_bf16 v[124:127], v[144:147], v[186:189], v[124:127]
	v_mfma_f32_16x16x32_bf16 v[120:123], v[162:165], v[186:189], v[120:123]
	v_mfma_f32_16x16x32_bf16 v[108:111], v[144:147], v[194:197], v[108:111]
	v_mfma_f32_16x16x32_bf16 v[104:107], v[162:165], v[194:197], v[104:107]
	v_mfma_f32_16x16x32_bf16 v[92:95], v[144:147], v[202:205], v[92:95]
	v_mfma_f32_16x16x32_bf16 v[88:91], v[162:165], v[202:205], v[88:91]
	v_mfma_f32_16x16x32_bf16 v[76:79], v[144:147], v[214:217], v[76:79]
	v_mfma_f32_16x16x32_bf16 v[72:75], v[162:165], v[214:217], v[72:75]
	v_mfma_f32_16x16x32_bf16 v[124:127], v[148:151], v[190:193], v[124:127]
	v_mfma_f32_16x16x32_bf16 v[120:123], v[166:169], v[190:193], v[120:123]
	v_mfma_f32_16x16x32_bf16 v[108:111], v[148:151], v[198:201], v[108:111]
	v_mfma_f32_16x16x32_bf16 v[104:107], v[166:169], v[198:201], v[104:107]
	v_mfma_f32_16x16x32_bf16 v[92:95], v[148:151], v[210:213], v[92:95]
	v_mfma_f32_16x16x32_bf16 v[88:91], v[166:169], v[210:213], v[88:91]
	v_mfma_f32_16x16x32_bf16 v[76:79], v[148:151], v[218:221], v[76:79]
	v_mfma_f32_16x16x32_bf16 v[72:75], v[166:169], v[218:221], v[72:75]
	s_setprio 0
	s_setprio 1
	v_mfma_f32_16x16x32_bf16 v[116:119], v[170:173], v[186:189], v[116:119]
	v_mfma_f32_16x16x32_bf16 v[112:115], v[178:181], v[186:189], v[112:115]
	v_mfma_f32_16x16x32_bf16 v[100:103], v[170:173], v[194:197], v[100:103]
	v_mfma_f32_16x16x32_bf16 v[96:99], v[178:181], v[194:197], v[96:99]
	v_mfma_f32_16x16x32_bf16 v[84:87], v[170:173], v[202:205], v[84:87]
	v_mfma_f32_16x16x32_bf16 v[80:83], v[178:181], v[202:205], v[80:83]
	v_mfma_f32_16x16x32_bf16 v[68:71], v[170:173], v[214:217], v[68:71]
	v_mfma_f32_16x16x32_bf16 v[64:67], v[178:181], v[214:217], v[64:67]
	v_mfma_f32_16x16x32_bf16 v[116:119], v[174:177], v[190:193], v[116:119]
	v_mfma_f32_16x16x32_bf16 v[112:115], v[182:185], v[190:193], v[112:115]
	v_mfma_f32_16x16x32_bf16 v[100:103], v[174:177], v[198:201], v[100:103]
	v_mfma_f32_16x16x32_bf16 v[96:99], v[182:185], v[198:201], v[96:99]
	v_mfma_f32_16x16x32_bf16 v[84:87], v[174:177], v[210:213], v[84:87]
	v_mfma_f32_16x16x32_bf16 v[80:83], v[182:185], v[210:213], v[80:83]
	v_mfma_f32_16x16x32_bf16 v[68:71], v[174:177], v[218:221], v[68:71]
	v_mfma_f32_16x16x32_bf16 v[64:67], v[182:185], v[218:221], v[64:67]
	s_setprio 0
	s_barrier
	s_add_i32 s57, s48, s36
	v_lshl_add_u64 v[152:153], s[28:29], 0, v[132:133]
	s_mov_b32 m0, s57
	ds_read_b128 v[186:189], v159 offset:16384
	ds_read_b128 v[190:193], v159 offset:17408
	ds_read_b128 v[194:197], v159 offset:18432
	ds_read_b128 v[198:201], v159 offset:19456
	ds_read_b128 v[202:205], v159 offset:20480
	ds_read_b128 v[210:213], v159 offset:21504
	ds_read_b128 v[214:217], v159 offset:22528
	ds_read_b128 v[218:221], v159 offset:23552
	global_load_lds_dwordx4 v[152:153], off
	s_add_i32 m0, s57, 0x2000
	s_add_u32 s58, s28, 0x40000
	v_lshl_add_u64 v[206:207], s[28:29], 0, v[128:129]
	s_addc_u32 s59, s29, 0
	s_add_i32 s57, s49, s36
	global_load_lds_dwordx4 v[206:207], off
	v_lshl_add_u64 v[222:223], s[58:59], 0, v[132:133]
	s_mov_b32 m0, s57
	v_lshl_add_u64 v[224:225], s[30:31], 0, v[130:131]
	global_load_lds_dwordx4 v[222:223], off
	v_lshl_add_u64 v[222:223], s[58:59], 0, v[128:129]
	s_add_i32 m0, s57, 0x2000
	s_nop 0
	global_load_lds_dwordx4 v[222:223], off
	v_lshl_add_u64 v[222:223], s[30:31], 0, v[134:135]
	s_mov_b32 m0, s39
	s_nop 0
	global_load_lds_dwordx4 v[222:223], off
	s_mov_b32 m0, s40
	s_nop 0
	global_load_lds_dwordx4 v[224:225], off
	s_waitcnt vmcnt(24)
	s_waitcnt lgkmcnt(0)
	s_barrier
	s_setprio 1
	s_waitcnt lgkmcnt(0)
	v_mfma_f32_16x16x32_bf16 v[60:63], v[144:147], v[186:189], v[60:63]
	v_mfma_f32_16x16x32_bf16 v[56:59], v[162:165], v[186:189], v[56:59]
	v_mfma_f32_16x16x32_bf16 v[44:47], v[144:147], v[194:197], v[44:47]
	v_mfma_f32_16x16x32_bf16 v[40:43], v[162:165], v[194:197], v[40:43]
	v_mfma_f32_16x16x32_bf16 v[28:31], v[144:147], v[202:205], v[28:31]
	v_mfma_f32_16x16x32_bf16 v[24:27], v[162:165], v[202:205], v[24:27]
	v_mfma_f32_16x16x32_bf16 v[12:15], v[144:147], v[214:217], v[12:15]
	v_mfma_f32_16x16x32_bf16 v[8:11], v[162:165], v[214:217], v[8:11]
	v_mfma_f32_16x16x32_bf16 v[60:63], v[148:151], v[190:193], v[60:63]
	v_mfma_f32_16x16x32_bf16 v[56:59], v[166:169], v[190:193], v[56:59]
	v_mfma_f32_16x16x32_bf16 v[44:47], v[148:151], v[198:201], v[44:47]
	v_mfma_f32_16x16x32_bf16 v[40:43], v[166:169], v[198:201], v[40:43]
	v_mfma_f32_16x16x32_bf16 v[28:31], v[148:151], v[210:213], v[28:31]
	v_mfma_f32_16x16x32_bf16 v[24:27], v[166:169], v[210:213], v[24:27]
	v_mfma_f32_16x16x32_bf16 v[12:15], v[148:151], v[218:221], v[12:15]
	v_mfma_f32_16x16x32_bf16 v[8:11], v[166:169], v[218:221], v[8:11]
	s_setprio 0
	s_setprio 1
	v_mfma_f32_16x16x32_bf16 v[52:55], v[170:173], v[186:189], v[52:55]
	v_mfma_f32_16x16x32_bf16 v[48:51], v[178:181], v[186:189], v[48:51]
	v_mfma_f32_16x16x32_bf16 v[36:39], v[170:173], v[194:197], v[36:39]
	v_mfma_f32_16x16x32_bf16 v[32:35], v[178:181], v[194:197], v[32:35]
	v_mfma_f32_16x16x32_bf16 v[20:23], v[170:173], v[202:205], v[20:23]
	v_mfma_f32_16x16x32_bf16 v[16:19], v[178:181], v[202:205], v[16:19]
	v_mfma_f32_16x16x32_bf16 v[4:7], v[170:173], v[214:217], v[4:7]
	v_mfma_f32_16x16x32_bf16 v[0:3], v[178:181], v[214:217], v[0:3]
	v_mfma_f32_16x16x32_bf16 v[52:55], v[174:177], v[190:193], v[52:55]
	v_mfma_f32_16x16x32_bf16 v[48:51], v[182:185], v[190:193], v[48:51]
	v_mfma_f32_16x16x32_bf16 v[36:39], v[174:177], v[198:201], v[36:39]
	v_mfma_f32_16x16x32_bf16 v[32:35], v[182:185], v[198:201], v[32:35]
	v_mfma_f32_16x16x32_bf16 v[20:23], v[174:177], v[210:213], v[20:23]
	v_mfma_f32_16x16x32_bf16 v[16:19], v[182:185], v[210:213], v[16:19]
	v_mfma_f32_16x16x32_bf16 v[4:7], v[174:177], v[218:221], v[4:7]
	v_mfma_f32_16x16x32_bf16 v[0:3], v[182:185], v[218:221], v[0:3]
	s_setprio 0
	s_barrier
	s_add_i32 s57, 0, 0x18000
	v_add_u32_e32 v161, s57, v155
	s_add_i32 s58, 0, 0x1c000
	ds_read_b128 v[144:147], v161
	ds_read_b128 v[148:151], v161 offset:1024
	ds_read_b128 v[162:165], v161 offset:2048
	ds_read_b128 v[166:169], v161 offset:3072
	v_add_u32_e32 v161, s58, v155
	ds_read_b128 v[170:173], v161
	ds_read_b128 v[174:177], v161 offset:1024
	ds_read_b128 v[178:181], v161 offset:2048
	ds_read_b128 v[182:185], v161 offset:3072
	s_add_u32 s30, s30, 0x40000
	s_addc_u32 s31, s31, 0
	s_mov_b32 m0, s41
	v_lshl_add_u64 v[226:227], s[30:31], 0, v[134:135]
	ds_read_b128 v[186:189], v159 offset:32768
	ds_read_b128 v[190:193], v159 offset:33792
	ds_read_b128 v[194:197], v159 offset:34816
	ds_read_b128 v[198:201], v159 offset:35840
	ds_read_b128 v[202:205], v159 offset:36864
	ds_read_b128 v[210:213], v159 offset:37888
	ds_read_b128 v[214:217], v159 offset:38912
	ds_read_b128 v[218:221], v159 offset:39936
	global_load_lds_dwordx4 v[226:227], off
	v_lshl_add_u64 v[226:227], s[30:31], 0, v[130:131]
	s_mov_b32 m0, s42
	s_nop 0
	global_load_lds_dwordx4 v[226:227], off
	s_waitcnt vmcnt(8)
	s_waitcnt lgkmcnt(0)
	s_barrier
	s_setprio 1
	s_waitcnt lgkmcnt(0)
	v_mfma_f32_16x16x32_bf16 v[124:127], v[144:147], v[186:189], v[124:127]
	v_mfma_f32_16x16x32_bf16 v[120:123], v[162:165], v[186:189], v[120:123]
	v_mfma_f32_16x16x32_bf16 v[108:111], v[144:147], v[194:197], v[108:111]
	v_mfma_f32_16x16x32_bf16 v[104:107], v[162:165], v[194:197], v[104:107]
	v_mfma_f32_16x16x32_bf16 v[92:95], v[144:147], v[202:205], v[92:95]
	v_mfma_f32_16x16x32_bf16 v[88:91], v[162:165], v[202:205], v[88:91]
	v_mfma_f32_16x16x32_bf16 v[76:79], v[144:147], v[214:217], v[76:79]
	v_mfma_f32_16x16x32_bf16 v[72:75], v[162:165], v[214:217], v[72:75]
	v_mfma_f32_16x16x32_bf16 v[124:127], v[148:151], v[190:193], v[124:127]
	v_mfma_f32_16x16x32_bf16 v[120:123], v[166:169], v[190:193], v[120:123]
	v_mfma_f32_16x16x32_bf16 v[108:111], v[148:151], v[198:201], v[108:111]
	v_mfma_f32_16x16x32_bf16 v[104:107], v[166:169], v[198:201], v[104:107]
	v_mfma_f32_16x16x32_bf16 v[92:95], v[148:151], v[210:213], v[92:95]
	v_mfma_f32_16x16x32_bf16 v[88:91], v[166:169], v[210:213], v[88:91]
	v_mfma_f32_16x16x32_bf16 v[76:79], v[148:151], v[218:221], v[76:79]
	v_mfma_f32_16x16x32_bf16 v[72:75], v[166:169], v[218:221], v[72:75]
	s_setprio 0
	s_setprio 1
	v_mfma_f32_16x16x32_bf16 v[116:119], v[170:173], v[186:189], v[116:119]
	v_mfma_f32_16x16x32_bf16 v[112:115], v[178:181], v[186:189], v[112:115]
	v_mfma_f32_16x16x32_bf16 v[100:103], v[170:173], v[194:197], v[100:103]
	v_mfma_f32_16x16x32_bf16 v[96:99], v[178:181], v[194:197], v[96:99]
	v_mfma_f32_16x16x32_bf16 v[84:87], v[170:173], v[202:205], v[84:87]
	v_mfma_f32_16x16x32_bf16 v[80:83], v[178:181], v[202:205], v[80:83]
	v_mfma_f32_16x16x32_bf16 v[68:71], v[170:173], v[214:217], v[68:71]
	v_mfma_f32_16x16x32_bf16 v[64:67], v[178:181], v[214:217], v[64:67]
	v_mfma_f32_16x16x32_bf16 v[116:119], v[174:177], v[190:193], v[116:119]
	v_mfma_f32_16x16x32_bf16 v[112:115], v[182:185], v[190:193], v[112:115]
	v_mfma_f32_16x16x32_bf16 v[100:103], v[174:177], v[198:201], v[100:103]
	v_mfma_f32_16x16x32_bf16 v[96:99], v[182:185], v[198:201], v[96:99]
	v_mfma_f32_16x16x32_bf16 v[84:87], v[174:177], v[210:213], v[84:87]
	v_mfma_f32_16x16x32_bf16 v[80:83], v[182:185], v[210:213], v[80:83]
	v_mfma_f32_16x16x32_bf16 v[68:71], v[174:177], v[218:221], v[68:71]
	v_mfma_f32_16x16x32_bf16 v[64:67], v[182:185], v[218:221], v[64:67]
	s_setprio 0
	s_barrier
	s_add_i32 s30, s57, s36
	v_lshl_add_u64 v[152:153], v[152:153], 0, s[14:15]
	s_mov_b32 m0, s30
	ds_read_b128 v[186:189], v159 offset:49152
	ds_read_b128 v[190:193], v159 offset:50176
	ds_read_b128 v[194:197], v159 offset:51200
	ds_read_b128 v[198:201], v159 offset:52224
	ds_read_b128 v[202:205], v159 offset:53248
	ds_read_b128 v[210:213], v159 offset:54272
	ds_read_b128 v[214:217], v159 offset:55296
	ds_read_b128 v[218:221], v159 offset:56320
	global_load_lds_dwordx4 v[152:153], off
	s_add_i32 m0, s30, 0x2000
	s_add_u32 s28, s28, 0x40080
	v_lshl_add_u64 v[152:153], v[206:207], 0, s[14:15]
	s_addc_u32 s29, s29, 0
	s_add_i32 s30, s58, s36
	global_load_lds_dwordx4 v[152:153], off
	v_lshl_add_u64 v[152:153], s[28:29], 0, v[132:133]
	s_mov_b32 m0, s30
	s_nop 0
	global_load_lds_dwordx4 v[152:153], off
	v_lshl_add_u64 v[152:153], s[28:29], 0, v[128:129]
	s_add_i32 m0, s30, 0x2000
	s_nop 0
	global_load_lds_dwordx4 v[152:153], off
	v_lshl_add_u64 v[152:153], v[222:223], 0, s[14:15]
	s_mov_b32 m0, s44
	s_nop 0
	global_load_lds_dwordx4 v[152:153], off
	v_lshl_add_u64 v[152:153], v[224:225], 0, s[14:15]
	s_mov_b32 m0, s45
	s_nop 0
	global_load_lds_dwordx4 v[152:153], off
	s_waitcnt vmcnt(8)
	s_waitcnt lgkmcnt(0)
	s_barrier
	s_setprio 1
	s_waitcnt lgkmcnt(0)
	v_mfma_f32_16x16x32_bf16 v[60:63], v[144:147], v[186:189], v[60:63]
	v_mfma_f32_16x16x32_bf16 v[56:59], v[162:165], v[186:189], v[56:59]
	v_mfma_f32_16x16x32_bf16 v[44:47], v[144:147], v[194:197], v[44:47]
	v_mfma_f32_16x16x32_bf16 v[40:43], v[162:165], v[194:197], v[40:43]
	v_mfma_f32_16x16x32_bf16 v[28:31], v[144:147], v[202:205], v[28:31]
	v_mfma_f32_16x16x32_bf16 v[24:27], v[162:165], v[202:205], v[24:27]
	v_mfma_f32_16x16x32_bf16 v[12:15], v[144:147], v[214:217], v[12:15]
	v_mfma_f32_16x16x32_bf16 v[8:11], v[162:165], v[214:217], v[8:11]
	v_mfma_f32_16x16x32_bf16 v[60:63], v[148:151], v[190:193], v[60:63]
	v_mfma_f32_16x16x32_bf16 v[56:59], v[166:169], v[190:193], v[56:59]
	v_mfma_f32_16x16x32_bf16 v[44:47], v[148:151], v[198:201], v[44:47]
	v_mfma_f32_16x16x32_bf16 v[40:43], v[166:169], v[198:201], v[40:43]
	v_mfma_f32_16x16x32_bf16 v[28:31], v[148:151], v[210:213], v[28:31]
	v_mfma_f32_16x16x32_bf16 v[24:27], v[166:169], v[210:213], v[24:27]
	v_mfma_f32_16x16x32_bf16 v[12:15], v[148:151], v[218:221], v[12:15]
	v_mfma_f32_16x16x32_bf16 v[8:11], v[166:169], v[218:221], v[8:11]
	s_setprio 0
	s_setprio 1
	v_mfma_f32_16x16x32_bf16 v[52:55], v[170:173], v[186:189], v[52:55]
	v_mfma_f32_16x16x32_bf16 v[48:51], v[178:181], v[186:189], v[48:51]
	v_mfma_f32_16x16x32_bf16 v[36:39], v[170:173], v[194:197], v[36:39]
	v_mfma_f32_16x16x32_bf16 v[32:35], v[178:181], v[194:197], v[32:35]
	v_mfma_f32_16x16x32_bf16 v[20:23], v[170:173], v[202:205], v[20:23]
	v_mfma_f32_16x16x32_bf16 v[16:19], v[178:181], v[202:205], v[16:19]
	v_mfma_f32_16x16x32_bf16 v[4:7], v[170:173], v[214:217], v[4:7]
	v_mfma_f32_16x16x32_bf16 v[0:3], v[178:181], v[214:217], v[0:3]
	v_mfma_f32_16x16x32_bf16 v[52:55], v[174:177], v[190:193], v[52:55]
	v_mfma_f32_16x16x32_bf16 v[48:51], v[182:185], v[190:193], v[48:51]
	v_mfma_f32_16x16x32_bf16 v[36:39], v[174:177], v[198:201], v[36:39]
	v_mfma_f32_16x16x32_bf16 v[32:35], v[182:185], v[198:201], v[32:35]
	v_mfma_f32_16x16x32_bf16 v[20:23], v[174:177], v[210:213], v[20:23]
	v_mfma_f32_16x16x32_bf16 v[16:19], v[182:185], v[210:213], v[16:19]
	v_mfma_f32_16x16x32_bf16 v[4:7], v[174:177], v[218:221], v[4:7]
	v_mfma_f32_16x16x32_bf16 v[0:3], v[182:185], v[218:221], v[0:3]
	s_setprio 0
	s_barrier
	s_add_i32 s56, s56, 2
	s_add_u32 s26, s26, 0x100
	s_addc_u32 s27, s27, 0
	s_add_u32 s54, s54, 0x100
	s_addc_u32 s55, s55, 0
	s_cmp_gt_u32 s56, 13
	s_cbranch_scc0 .LBB0_1129
.LBB0_1129:
	ds_read_b128 v[144:147], v157
	ds_read_b128 v[148:151], v157 offset:1024
	ds_read_b128 v[162:165], v157 offset:2048
	ds_read_b128 v[166:169], v157 offset:3072
	ds_read_b128 v[170:173], v158
	ds_read_b128 v[174:177], v158 offset:1024
	ds_read_b128 v[178:181], v158 offset:2048
	ds_read_b128 v[182:185], v158 offset:3072
	s_add_u32 s28, s26, 0xfffc0080
	s_addc_u32 s29, s27, -1
	s_cmp_eq_u32 s56, 12
	s_cselect_b32 s31, s21, s29
	s_cselect_b32 s30, s52, s28
	s_cselect_b32 s29, s19, s55
	s_cselect_b32 s28, s53, s54
	v_lshl_add_u64 v[152:153], s[26:27], 0, v[136:137]
	s_add_i32 m0, s39, 0xc000
	ds_read_b128 v[186:189], v159
	ds_read_b128 v[190:193], v159 offset:1024
	ds_read_b128 v[194:197], v159 offset:2048
	ds_read_b128 v[198:201], v159 offset:3072
	ds_read_b128 v[202:205], v159 offset:4096
	ds_read_b128 v[210:213], v159 offset:5120
	ds_read_b128 v[214:217], v159 offset:6144
	ds_read_b128 v[218:221], v159 offset:7168
	global_load_lds_dwordx4 v[152:153], off
	v_lshl_add_u64 v[152:153], s[26:27], 0, v[138:139]
	s_add_i32 m0, s39, 0xe000
	s_nop 0
	global_load_lds_dwordx4 v[152:153], off
	s_waitcnt vmcnt(8)
	s_waitcnt lgkmcnt(0)
	s_barrier
	s_setprio 1
	s_waitcnt lgkmcnt(0)
	v_mfma_f32_16x16x32_bf16 v[124:127], v[144:147], v[186:189], v[124:127]
	v_mfma_f32_16x16x32_bf16 v[120:123], v[162:165], v[186:189], v[120:123]
	v_mfma_f32_16x16x32_bf16 v[108:111], v[144:147], v[194:197], v[108:111]
	v_mfma_f32_16x16x32_bf16 v[104:107], v[162:165], v[194:197], v[104:107]
	v_mfma_f32_16x16x32_bf16 v[92:95], v[144:147], v[202:205], v[92:95]
	v_mfma_f32_16x16x32_bf16 v[88:91], v[162:165], v[202:205], v[88:91]
	v_mfma_f32_16x16x32_bf16 v[76:79], v[144:147], v[214:217], v[76:79]
	v_mfma_f32_16x16x32_bf16 v[72:75], v[162:165], v[214:217], v[72:75]
	v_mfma_f32_16x16x32_bf16 v[124:127], v[148:151], v[190:193], v[124:127]
	v_mfma_f32_16x16x32_bf16 v[120:123], v[166:169], v[190:193], v[120:123]
	v_mfma_f32_16x16x32_bf16 v[108:111], v[148:151], v[198:201], v[108:111]
	v_mfma_f32_16x16x32_bf16 v[104:107], v[166:169], v[198:201], v[104:107]
	v_mfma_f32_16x16x32_bf16 v[92:95], v[148:151], v[210:213], v[92:95]
	v_mfma_f32_16x16x32_bf16 v[88:91], v[166:169], v[210:213], v[88:91]
	v_mfma_f32_16x16x32_bf16 v[76:79], v[148:151], v[218:221], v[76:79]
	v_mfma_f32_16x16x32_bf16 v[72:75], v[166:169], v[218:221], v[72:75]
	s_setprio 0
	s_setprio 1
	v_mfma_f32_16x16x32_bf16 v[116:119], v[170:173], v[186:189], v[116:119]
	v_mfma_f32_16x16x32_bf16 v[112:115], v[178:181], v[186:189], v[112:115]
	v_mfma_f32_16x16x32_bf16 v[100:103], v[170:173], v[194:197], v[100:103]
	v_mfma_f32_16x16x32_bf16 v[96:99], v[178:181], v[194:197], v[96:99]
	v_mfma_f32_16x16x32_bf16 v[84:87], v[170:173], v[202:205], v[84:87]
	v_mfma_f32_16x16x32_bf16 v[80:83], v[178:181], v[202:205], v[80:83]
	v_mfma_f32_16x16x32_bf16 v[68:71], v[170:173], v[214:217], v[68:71]
	v_mfma_f32_16x16x32_bf16 v[64:67], v[178:181], v[214:217], v[64:67]
	v_mfma_f32_16x16x32_bf16 v[116:119], v[174:177], v[190:193], v[116:119]
	v_mfma_f32_16x16x32_bf16 v[112:115], v[182:185], v[190:193], v[112:115]
	v_mfma_f32_16x16x32_bf16 v[100:103], v[174:177], v[198:201], v[100:103]
	v_mfma_f32_16x16x32_bf16 v[96:99], v[182:185], v[198:201], v[96:99]
	v_mfma_f32_16x16x32_bf16 v[84:87], v[174:177], v[210:213], v[84:87]
	v_mfma_f32_16x16x32_bf16 v[80:83], v[182:185], v[210:213], v[80:83]
	v_mfma_f32_16x16x32_bf16 v[68:71], v[174:177], v[218:221], v[68:71]
	v_mfma_f32_16x16x32_bf16 v[64:67], v[182:185], v[218:221], v[64:67]
	s_setprio 0
	s_barrier
	s_add_i32 s57, s48, s36
	v_lshl_add_u64 v[152:153], s[28:29], 0, v[132:133]
	s_mov_b32 m0, s57
	ds_read_b128 v[186:189], v159 offset:16384
	ds_read_b128 v[190:193], v159 offset:17408
	ds_read_b128 v[194:197], v159 offset:18432
	ds_read_b128 v[198:201], v159 offset:19456
	ds_read_b128 v[202:205], v159 offset:20480
	ds_read_b128 v[210:213], v159 offset:21504
	ds_read_b128 v[214:217], v159 offset:22528
	ds_read_b128 v[218:221], v159 offset:23552
	global_load_lds_dwordx4 v[152:153], off
	s_add_i32 m0, s57, 0x2000
	s_add_u32 s58, s28, 0x40000
	v_lshl_add_u64 v[206:207], s[28:29], 0, v[128:129]
	s_addc_u32 s59, s29, 0
	s_add_i32 s57, s49, s36
	global_load_lds_dwordx4 v[206:207], off
	v_lshl_add_u64 v[222:223], s[58:59], 0, v[132:133]
	s_mov_b32 m0, s57
	v_lshl_add_u64 v[224:225], s[30:31], 0, v[130:131]
	global_load_lds_dwordx4 v[222:223], off
	v_lshl_add_u64 v[222:223], s[58:59], 0, v[128:129]
	s_add_i32 m0, s57, 0x2000
	s_nop 0
	global_load_lds_dwordx4 v[222:223], off
	v_lshl_add_u64 v[222:223], s[30:31], 0, v[134:135]
	s_mov_b32 m0, s39
	s_nop 0
	global_load_lds_dwordx4 v[222:223], off
	s_mov_b32 m0, s40
	s_nop 0
	global_load_lds_dwordx4 v[224:225], off
	s_waitcnt vmcnt(8)
	s_waitcnt lgkmcnt(0)
	s_barrier
	s_setprio 1
	s_waitcnt lgkmcnt(0)
	v_mfma_f32_16x16x32_bf16 v[60:63], v[144:147], v[186:189], v[60:63]
	v_mfma_f32_16x16x32_bf16 v[56:59], v[162:165], v[186:189], v[56:59]
	v_mfma_f32_16x16x32_bf16 v[44:47], v[144:147], v[194:197], v[44:47]
	v_mfma_f32_16x16x32_bf16 v[40:43], v[162:165], v[194:197], v[40:43]
	v_mfma_f32_16x16x32_bf16 v[28:31], v[144:147], v[202:205], v[28:31]
	v_mfma_f32_16x16x32_bf16 v[24:27], v[162:165], v[202:205], v[24:27]
	v_mfma_f32_16x16x32_bf16 v[12:15], v[144:147], v[214:217], v[12:15]
	v_mfma_f32_16x16x32_bf16 v[8:11], v[162:165], v[214:217], v[8:11]
	v_mfma_f32_16x16x32_bf16 v[60:63], v[148:151], v[190:193], v[60:63]
	v_mfma_f32_16x16x32_bf16 v[56:59], v[166:169], v[190:193], v[56:59]
	v_mfma_f32_16x16x32_bf16 v[44:47], v[148:151], v[198:201], v[44:47]
	v_mfma_f32_16x16x32_bf16 v[40:43], v[166:169], v[198:201], v[40:43]
	v_mfma_f32_16x16x32_bf16 v[28:31], v[148:151], v[210:213], v[28:31]
	v_mfma_f32_16x16x32_bf16 v[24:27], v[166:169], v[210:213], v[24:27]
	v_mfma_f32_16x16x32_bf16 v[12:15], v[148:151], v[218:221], v[12:15]
	v_mfma_f32_16x16x32_bf16 v[8:11], v[166:169], v[218:221], v[8:11]
	s_setprio 0
	s_setprio 1
	v_mfma_f32_16x16x32_bf16 v[52:55], v[170:173], v[186:189], v[52:55]
	v_mfma_f32_16x16x32_bf16 v[48:51], v[178:181], v[186:189], v[48:51]
	v_mfma_f32_16x16x32_bf16 v[36:39], v[170:173], v[194:197], v[36:39]
	v_mfma_f32_16x16x32_bf16 v[32:35], v[178:181], v[194:197], v[32:35]
	v_mfma_f32_16x16x32_bf16 v[20:23], v[170:173], v[202:205], v[20:23]
	v_mfma_f32_16x16x32_bf16 v[16:19], v[178:181], v[202:205], v[16:19]
	v_mfma_f32_16x16x32_bf16 v[4:7], v[170:173], v[214:217], v[4:7]
	v_mfma_f32_16x16x32_bf16 v[0:3], v[178:181], v[214:217], v[0:3]
	v_mfma_f32_16x16x32_bf16 v[52:55], v[174:177], v[190:193], v[52:55]
	v_mfma_f32_16x16x32_bf16 v[48:51], v[182:185], v[190:193], v[48:51]
	v_mfma_f32_16x16x32_bf16 v[36:39], v[174:177], v[198:201], v[36:39]
	v_mfma_f32_16x16x32_bf16 v[32:35], v[182:185], v[198:201], v[32:35]
	v_mfma_f32_16x16x32_bf16 v[20:23], v[174:177], v[210:213], v[20:23]
	v_mfma_f32_16x16x32_bf16 v[16:19], v[182:185], v[210:213], v[16:19]
	v_mfma_f32_16x16x32_bf16 v[4:7], v[174:177], v[218:221], v[4:7]
	v_mfma_f32_16x16x32_bf16 v[0:3], v[182:185], v[218:221], v[0:3]
	s_setprio 0
	s_barrier
	s_add_i32 s57, 0, 0x18000
	v_add_u32_e32 v161, s57, v155
	s_add_i32 s58, 0, 0x1c000
	ds_read_b128 v[144:147], v161
	ds_read_b128 v[148:151], v161 offset:1024
	ds_read_b128 v[162:165], v161 offset:2048
	ds_read_b128 v[166:169], v161 offset:3072
	v_add_u32_e32 v161, s58, v155
	ds_read_b128 v[170:173], v161
	ds_read_b128 v[174:177], v161 offset:1024
	ds_read_b128 v[178:181], v161 offset:2048
	ds_read_b128 v[182:185], v161 offset:3072
	s_add_u32 s30, s30, 0x40000
	s_addc_u32 s31, s31, 0
	s_mov_b32 m0, s41
	v_lshl_add_u64 v[226:227], s[30:31], 0, v[134:135]
	ds_read_b128 v[186:189], v159 offset:32768
	ds_read_b128 v[190:193], v159 offset:33792
	ds_read_b128 v[194:197], v159 offset:34816
	ds_read_b128 v[198:201], v159 offset:35840
	ds_read_b128 v[202:205], v159 offset:36864
	ds_read_b128 v[210:213], v159 offset:37888
	ds_read_b128 v[214:217], v159 offset:38912
	ds_read_b128 v[218:221], v159 offset:39936
	global_load_lds_dwordx4 v[226:227], off
	v_lshl_add_u64 v[226:227], s[30:31], 0, v[130:131]
	s_mov_b32 m0, s42
	s_nop 0
	global_load_lds_dwordx4 v[226:227], off
	s_waitcnt vmcnt(8)
	s_waitcnt lgkmcnt(0)
	s_barrier
	s_setprio 1
	s_waitcnt lgkmcnt(0)
	v_mfma_f32_16x16x32_bf16 v[124:127], v[144:147], v[186:189], v[124:127]
	v_mfma_f32_16x16x32_bf16 v[120:123], v[162:165], v[186:189], v[120:123]
	v_mfma_f32_16x16x32_bf16 v[108:111], v[144:147], v[194:197], v[108:111]
	v_mfma_f32_16x16x32_bf16 v[104:107], v[162:165], v[194:197], v[104:107]
	v_mfma_f32_16x16x32_bf16 v[92:95], v[144:147], v[202:205], v[92:95]
	v_mfma_f32_16x16x32_bf16 v[88:91], v[162:165], v[202:205], v[88:91]
	v_mfma_f32_16x16x32_bf16 v[76:79], v[144:147], v[214:217], v[76:79]
	v_mfma_f32_16x16x32_bf16 v[72:75], v[162:165], v[214:217], v[72:75]
	v_mfma_f32_16x16x32_bf16 v[124:127], v[148:151], v[190:193], v[124:127]
	v_mfma_f32_16x16x32_bf16 v[120:123], v[166:169], v[190:193], v[120:123]
	v_mfma_f32_16x16x32_bf16 v[108:111], v[148:151], v[198:201], v[108:111]
	v_mfma_f32_16x16x32_bf16 v[104:107], v[166:169], v[198:201], v[104:107]
	v_mfma_f32_16x16x32_bf16 v[92:95], v[148:151], v[210:213], v[92:95]
	v_mfma_f32_16x16x32_bf16 v[88:91], v[166:169], v[210:213], v[88:91]
	v_mfma_f32_16x16x32_bf16 v[76:79], v[148:151], v[218:221], v[76:79]
	v_mfma_f32_16x16x32_bf16 v[72:75], v[166:169], v[218:221], v[72:75]
	s_setprio 0
	s_setprio 1
	v_mfma_f32_16x16x32_bf16 v[116:119], v[170:173], v[186:189], v[116:119]
	v_mfma_f32_16x16x32_bf16 v[112:115], v[178:181], v[186:189], v[112:115]
	v_mfma_f32_16x16x32_bf16 v[100:103], v[170:173], v[194:197], v[100:103]
	v_mfma_f32_16x16x32_bf16 v[96:99], v[178:181], v[194:197], v[96:99]
	v_mfma_f32_16x16x32_bf16 v[84:87], v[170:173], v[202:205], v[84:87]
	v_mfma_f32_16x16x32_bf16 v[80:83], v[178:181], v[202:205], v[80:83]
	v_mfma_f32_16x16x32_bf16 v[68:71], v[170:173], v[214:217], v[68:71]
	v_mfma_f32_16x16x32_bf16 v[64:67], v[178:181], v[214:217], v[64:67]
	v_mfma_f32_16x16x32_bf16 v[116:119], v[174:177], v[190:193], v[116:119]
	v_mfma_f32_16x16x32_bf16 v[112:115], v[182:185], v[190:193], v[112:115]
	v_mfma_f32_16x16x32_bf16 v[100:103], v[174:177], v[198:201], v[100:103]
	v_mfma_f32_16x16x32_bf16 v[96:99], v[182:185], v[198:201], v[96:99]
	v_mfma_f32_16x16x32_bf16 v[84:87], v[174:177], v[210:213], v[84:87]
	v_mfma_f32_16x16x32_bf16 v[80:83], v[182:185], v[210:213], v[80:83]
	v_mfma_f32_16x16x32_bf16 v[68:71], v[174:177], v[218:221], v[68:71]
	v_mfma_f32_16x16x32_bf16 v[64:67], v[182:185], v[218:221], v[64:67]
	s_setprio 0
	s_barrier
	s_add_i32 s30, s57, s36
	v_lshl_add_u64 v[152:153], v[152:153], 0, s[14:15]
	s_mov_b32 m0, s30
	ds_read_b128 v[186:189], v159 offset:49152
	ds_read_b128 v[190:193], v159 offset:50176
	ds_read_b128 v[194:197], v159 offset:51200
	ds_read_b128 v[198:201], v159 offset:52224
	ds_read_b128 v[202:205], v159 offset:53248
	ds_read_b128 v[210:213], v159 offset:54272
	ds_read_b128 v[214:217], v159 offset:55296
	ds_read_b128 v[218:221], v159 offset:56320
	global_load_lds_dwordx4 v[152:153], off
	s_add_i32 m0, s30, 0x2000
	s_add_u32 s28, s28, 0x40080
	v_lshl_add_u64 v[152:153], v[206:207], 0, s[14:15]
	s_addc_u32 s29, s29, 0
	s_add_i32 s30, s58, s36
	global_load_lds_dwordx4 v[152:153], off
	v_lshl_add_u64 v[152:153], s[28:29], 0, v[132:133]
	s_mov_b32 m0, s30
	s_nop 0
	global_load_lds_dwordx4 v[152:153], off
	v_lshl_add_u64 v[152:153], s[28:29], 0, v[128:129]
	s_add_i32 m0, s30, 0x2000
	s_nop 0
	global_load_lds_dwordx4 v[152:153], off
	v_lshl_add_u64 v[152:153], v[222:223], 0, s[14:15]
	s_mov_b32 m0, s44
	s_nop 0
	global_load_lds_dwordx4 v[152:153], off
	v_lshl_add_u64 v[152:153], v[224:225], 0, s[14:15]
	s_mov_b32 m0, s45
	s_nop 0
	global_load_lds_dwordx4 v[152:153], off
	s_waitcnt vmcnt(8)
	s_waitcnt lgkmcnt(0)
	s_barrier
	s_setprio 1
	s_waitcnt lgkmcnt(0)
	v_mfma_f32_16x16x32_bf16 v[60:63], v[144:147], v[186:189], v[60:63]
	v_mfma_f32_16x16x32_bf16 v[56:59], v[162:165], v[186:189], v[56:59]
	v_mfma_f32_16x16x32_bf16 v[44:47], v[144:147], v[194:197], v[44:47]
	v_mfma_f32_16x16x32_bf16 v[40:43], v[162:165], v[194:197], v[40:43]
	v_mfma_f32_16x16x32_bf16 v[28:31], v[144:147], v[202:205], v[28:31]
	v_mfma_f32_16x16x32_bf16 v[24:27], v[162:165], v[202:205], v[24:27]
	v_mfma_f32_16x16x32_bf16 v[12:15], v[144:147], v[214:217], v[12:15]
	v_mfma_f32_16x16x32_bf16 v[8:11], v[162:165], v[214:217], v[8:11]
	v_mfma_f32_16x16x32_bf16 v[60:63], v[148:151], v[190:193], v[60:63]
	v_mfma_f32_16x16x32_bf16 v[56:59], v[166:169], v[190:193], v[56:59]
	v_mfma_f32_16x16x32_bf16 v[44:47], v[148:151], v[198:201], v[44:47]
	v_mfma_f32_16x16x32_bf16 v[40:43], v[166:169], v[198:201], v[40:43]
	v_mfma_f32_16x16x32_bf16 v[28:31], v[148:151], v[210:213], v[28:31]
	v_mfma_f32_16x16x32_bf16 v[24:27], v[166:169], v[210:213], v[24:27]
	v_mfma_f32_16x16x32_bf16 v[12:15], v[148:151], v[218:221], v[12:15]
	v_mfma_f32_16x16x32_bf16 v[8:11], v[166:169], v[218:221], v[8:11]
	s_setprio 0
	s_setprio 1
	v_mfma_f32_16x16x32_bf16 v[52:55], v[170:173], v[186:189], v[52:55]
	v_mfma_f32_16x16x32_bf16 v[48:51], v[178:181], v[186:189], v[48:51]
	v_mfma_f32_16x16x32_bf16 v[36:39], v[170:173], v[194:197], v[36:39]
	v_mfma_f32_16x16x32_bf16 v[32:35], v[178:181], v[194:197], v[32:35]
	v_mfma_f32_16x16x32_bf16 v[20:23], v[170:173], v[202:205], v[20:23]
	v_mfma_f32_16x16x32_bf16 v[16:19], v[178:181], v[202:205], v[16:19]
	v_mfma_f32_16x16x32_bf16 v[4:7], v[170:173], v[214:217], v[4:7]
	v_mfma_f32_16x16x32_bf16 v[0:3], v[178:181], v[214:217], v[0:3]
	v_mfma_f32_16x16x32_bf16 v[52:55], v[174:177], v[190:193], v[52:55]
	v_mfma_f32_16x16x32_bf16 v[48:51], v[182:185], v[190:193], v[48:51]
	v_mfma_f32_16x16x32_bf16 v[36:39], v[174:177], v[198:201], v[36:39]
	v_mfma_f32_16x16x32_bf16 v[32:35], v[182:185], v[198:201], v[32:35]
	v_mfma_f32_16x16x32_bf16 v[20:23], v[174:177], v[210:213], v[20:23]
	v_mfma_f32_16x16x32_bf16 v[16:19], v[182:185], v[210:213], v[16:19]
	v_mfma_f32_16x16x32_bf16 v[4:7], v[174:177], v[218:221], v[4:7]
	v_mfma_f32_16x16x32_bf16 v[0:3], v[182:185], v[218:221], v[0:3]
	s_setprio 0
	s_barrier
	s_add_i32 s56, s56, 2
	s_add_u32 s26, s26, 0x100
	s_addc_u32 s27, s27, 0
	s_add_u32 s54, s54, 0x100
	s_addc_u32 s55, s55, 0
	s_cmp_gt_u32 s56, 13
	s_cbranch_scc0 .LBB0_1129
	s_mov_b32 s100, 1
	s_and_b64 vcc, exec, s[16:17]
	s_cbranch_vccz .LBB0_1132
	s_barrier

.LBB0_1196:
	s_add_u32 s12, s94, 0x12800000
	s_addc_u32 s13, s95, 0
	s_add_u32 s14, s94, 0x2800000
	s_addc_u32 s15, s95, 0
	s_add_u32 s16, s94, 0x41000
	s_addc_u32 s17, s95, 0
	s_lshl_b32 s1, s1, 5
	s_mov_b64 s[18:19], 0x80
	s_and_b32 s7, s1, 0x60
	s_add_i32 m0, s37, 0x18000
	v_lshl_add_u64 v[6:7], v[6:7], 0, s[18:19]
	s_lshl_b32 s5, s0, 13
	s_lshl_b32 s1, s7, 7
	s_waitcnt vmcnt(2)
	s_barrier
	global_load_lds_dwordx4 v[6:7], off
	v_lshl_add_u64 v[4:5], v[4:5], 0, s[18:19]
	s_add_i32 m0, s37, 0x1a000
	s_add_i32 s42, s37, 0x8000
	s_add_i32 s43, s37, 0xa000
	global_load_lds_dwordx4 v[4:5], off
	v_lshl_add_u64 v[0:1], v[0:1], 0, s[18:19]
	s_mov_b32 m0, s42
	s_add_u32 s20, s26, 0xb0080
	global_load_lds_dwordx4 v[0:1], off
	v_lshl_add_u64 v[0:1], v[2:3], 0, s[18:19]
	s_mov_b32 m0, s43
	s_addc_u32 s21, s27, 0
	global_load_lds_dwordx4 v[0:1], off
	s_add_i32 m0, s37, 0x1c000
	v_lshl_add_u64 v[0:1], s[20:21], 0, v[154:155]
	global_load_lds_dwordx4 v[0:1], off
	v_lshl_add_u64 v[0:1], s[20:21], 0, v[158:159]
	s_add_i32 m0, s37, 0x1e000
	s_cmpk_lt_u32 s6, 0x100
	global_load_lds_dwordx4 v[0:1], off
	v_bfe_u32 v1, v8, 4, 2
	v_and_b32_e32 v0, 15, v8
	v_lshlrev_b32_e32 v2, 4, v1
	v_lshl_or_b32 v186, s0, 6, v0
	v_lshl_or_b32 v0, v0, 6, v2
	v_lshlrev_b32_e32 v2, 2, v8
	v_and_b32_e32 v2, 32, v2
	v_bitop3_b32 v3, v0, s5, v2 bitop3:0xde
	v_bitop3_b32 v187, v0, s1, v2 bitop3:0xde
	v_cmp_eq_u32_e64 s[0:1], 0, v1
	v_lshl_or_b32 v188, v1, 3, s7
	v_lshrrev_b32_e32 v1, 1, v9
	v_mul_lo_u32 v0, v11, s4
	s_mov_b32 s5, 0xb000
	v_mad_u64_u32 v[0:1], s[6:7], v1, s5, v[0:1]
	v_or_b32_e32 v0, v0, v10
	s_mov_b64 s[22:23], 0xb0080
	v_add_lshl_u32 v0, v0, v12, 1
	v_mov_b32_e32 v1, v155
	v_lshl_add_u64 v[160:161], v[0:1], 0, s[22:23]
	v_lshrrev_b32_e32 v1, 1, v13
	v_mul_lo_u32 v0, v14, s4
	v_mad_u64_u32 v[0:1], s[4:5], v1, s5, v[0:1]
	v_or_b32_e32 v0, v0, v15
	s_waitcnt vmcnt(6)
	v_add_lshl_u32 v0, v0, v16, 1
	v_mov_b32_e32 v1, v155
	s_cselect_b64 s[20:21], -1, 0
	v_lshl_add_u64 v[162:163], v[0:1], 0, s[22:23]
	s_add_i32 s47, 0, 0x10000
	s_add_i32 s48, 0, 0x14000
	v_mbcnt_lo_u32_b32 v0, -1, 0
	s_ashr_i32 s44, s90, 31
	s_mov_b32 s45, s90
	s_ashr_i32 s46, s2, 31
	v_mov_b64_e32 v[164:165], 0x400
	v_mov_b64_e32 v[166:167], 0x3ff
	v_add_u32_e32 v189, s47, v187
	v_add_u32_e32 v190, s48, v187
	v_add_u32_e32 v191, 0, v3
	v_mbcnt_hi_u32_b32 v192, -1, v0
	s_barrier
	s_mov_b32 s100, 0
	s_branch .LBB0_1199

.LBB0_1209:
	s_add_u32 s53, s26, 0x100
	v_mov_b32_e32 v0, 0
	s_addc_u32 s54, s27, 0
	s_mov_b32 s55, -2
	s_waitcnt lgkmcnt(0)
	v_mov_b32_e32 v1, v0
	v_mov_b32_e32 v2, v0
	v_mov_b32_e32 v3, v0
	v_mov_b32_e32 v4, v0
	v_mov_b32_e32 v5, v0
	v_mov_b32_e32 v6, v0
	v_mov_b32_e32 v7, v0
	v_mov_b32_e32 v16, v0
	v_mov_b32_e32 v17, v0
	v_mov_b32_e32 v18, v0
	v_mov_b32_e32 v19, v0
	s_waitcnt vmcnt(0)
	v_mov_b32_e32 v20, v0
	v_mov_b32_e32 v21, v0
	v_mov_b32_e32 v22, v0
	v_mov_b32_e32 v23, v0
	v_mov_b32_e32 v32, v0
	v_mov_b32_e32 v33, v0
	v_mov_b32_e32 v34, v0
	v_mov_b32_e32 v35, v0
	v_mov_b32_e32 v36, v0
	v_mov_b32_e32 v37, v0
	v_mov_b32_e32 v38, v0
	v_mov_b32_e32 v39, v0
	v_mov_b32_e32 v48, v0
	v_mov_b32_e32 v49, v0
	v_mov_b32_e32 v50, v0
	v_mov_b32_e32 v51, v0
	v_mov_b32_e32 v52, v0
	v_mov_b32_e32 v53, v0
	v_mov_b32_e32 v54, v0
	v_mov_b32_e32 v55, v0
	v_mov_b32_e32 v8, v0
	v_mov_b32_e32 v9, v0
	v_mov_b32_e32 v10, v0
	v_mov_b32_e32 v11, v0
	v_mov_b32_e32 v12, v0
	v_mov_b32_e32 v13, v0
	v_mov_b32_e32 v14, v0
	v_mov_b32_e32 v15, v0
	v_mov_b32_e32 v24, v0
	v_mov_b32_e32 v25, v0
	v_mov_b32_e32 v26, v0
	v_mov_b32_e32 v27, v0
	v_mov_b32_e32 v28, v0
	v_mov_b32_e32 v29, v0
	v_mov_b32_e32 v30, v0
	v_mov_b32_e32 v31, v0
	v_mov_b32_e32 v40, v0
	v_mov_b32_e32 v41, v0
	v_mov_b32_e32 v42, v0
	v_mov_b32_e32 v43, v0
	v_mov_b32_e32 v44, v0
	v_mov_b32_e32 v45, v0
	v_mov_b32_e32 v46, v0
	v_mov_b32_e32 v47, v0
	v_mov_b32_e32 v56, v0
	v_mov_b32_e32 v57, v0
	v_mov_b32_e32 v58, v0
	v_mov_b32_e32 v59, v0
	v_mov_b32_e32 v60, v0
	v_mov_b32_e32 v61, v0
	v_mov_b32_e32 v62, v0
	v_mov_b32_e32 v63, v0
	v_mov_b32_e32 v64, v0
	v_mov_b32_e32 v65, v0
	v_mov_b32_e32 v66, v0
	v_mov_b32_e32 v67, v0
	v_mov_b32_e32 v68, v0
	v_mov_b32_e32 v69, v0
	v_mov_b32_e32 v70, v0
	v_mov_b32_e32 v71, v0
	v_mov_b32_e32 v80, v0
	v_mov_b32_e32 v81, v0
	v_mov_b32_e32 v82, v0
	v_mov_b32_e32 v83, v0
	v_mov_b32_e32 v84, v0
	v_mov_b32_e32 v85, v0
	v_mov_b32_e32 v86, v0
	v_mov_b32_e32 v87, v0
	v_mov_b32_e32 v96, v0
	v_mov_b32_e32 v97, v0
	v_mov_b32_e32 v98, v0
	v_mov_b32_e32 v99, v0
	v_mov_b32_e32 v100, v0
	v_mov_b32_e32 v101, v0
	v_mov_b32_e32 v102, v0
	v_mov_b32_e32 v103, v0
	v_mov_b32_e32 v112, v0
	v_mov_b32_e32 v113, v0
	v_mov_b32_e32 v114, v0
	v_mov_b32_e32 v115, v0
	v_mov_b32_e32 v116, v0
	v_mov_b32_e32 v117, v0
	v_mov_b32_e32 v118, v0
	v_mov_b32_e32 v119, v0
	v_mov_b32_e32 v72, v0
	v_mov_b32_e32 v73, v0
	v_mov_b32_e32 v74, v0
	v_mov_b32_e32 v75, v0
	v_mov_b32_e32 v76, v0
	v_mov_b32_e32 v77, v0
	v_mov_b32_e32 v78, v0
	v_mov_b32_e32 v79, v0
	v_mov_b32_e32 v88, v0
	v_mov_b32_e32 v89, v0
	v_mov_b32_e32 v90, v0
	v_mov_b32_e32 v91, v0
	v_mov_b32_e32 v92, v0
	v_mov_b32_e32 v93, v0
	v_mov_b32_e32 v94, v0
	v_mov_b32_e32 v95, v0
	v_mov_b32_e32 v104, v0
	v_mov_b32_e32 v105, v0
	v_mov_b32_e32 v106, v0
	v_mov_b32_e32 v107, v0
	v_mov_b32_e32 v108, v0
	v_mov_b32_e32 v109, v0
	v_mov_b32_e32 v110, v0
	v_mov_b32_e32 v111, v0
	v_mov_b32_e32 v120, v0
	v_mov_b32_e32 v121, v0
	v_mov_b32_e32 v122, v0
	v_mov_b32_e32 v123, v0
	v_mov_b32_e32 v124, v0
	v_mov_b32_e32 v125, v0
	v_mov_b32_e32 v126, v0
	v_mov_b32_e32 v127, v0
	s_cmp_eq_u32 s100, 0
	s_cbranch_scc1 .LBB0_1210
	ds_read_b128 v[128:131], v189
	ds_read_b128 v[132:135], v189 offset:1024
	ds_read_b128 v[136:139], v189 offset:2048
	ds_read_b128 v[140:143], v189 offset:3072
	ds_read_b128 v[144:147], v190
	ds_read_b128 v[148:151], v190 offset:1024
	ds_read_b128 v[168:171], v190 offset:2048
	ds_read_b128 v[172:175], v190 offset:3072
	s_add_u32 s26, s24, 0x100
	s_addc_u32 s27, s25, 0
	s_cmp_eq_u32 s55, 40
	s_cselect_b32 s31, s5, s27
	s_cselect_b32 s30, s4, s26
	s_cselect_b32 s29, s23, s54
	s_cselect_b32 s28, s22, s53
	v_lshl_add_u64 v[184:185], s[24:25], 0, v[160:161]
	s_add_i32 m0, s37, 0xc000
	ds_read_b128 v[176:179], v191
	ds_read_b128 v[180:183], v191 offset:1024
	ds_read_b128 v[194:197], v191 offset:2048
	ds_read_b128 v[198:201], v191 offset:3072
	ds_read_b128 v[202:205], v191 offset:4096
	ds_read_b128 v[210:213], v191 offset:5120
	ds_read_b128 v[214:217], v191 offset:6144
	ds_read_b128 v[218:221], v191 offset:7168
	global_load_lds_dwordx4 v[184:185], off
	v_lshl_add_u64 v[184:185], s[24:25], 0, v[162:163]
	s_add_i32 m0, s37, 0xe000
	s_nop 0
	global_load_lds_dwordx4 v[184:185], off
	s_waitcnt vmcnt(24)
	s_waitcnt lgkmcnt(0)
	s_barrier
	s_setprio 1
	s_waitcnt lgkmcnt(0)
	v_mfma_f32_16x16x32_bf16 v[124:127], v[128:131], v[176:179], v[124:127]
	v_mfma_f32_16x16x32_bf16 v[120:123], v[136:139], v[176:179], v[120:123]
	v_mfma_f32_16x16x32_bf16 v[108:111], v[128:131], v[194:197], v[108:111]
	v_mfma_f32_16x16x32_bf16 v[104:107], v[136:139], v[194:197], v[104:107]
	v_mfma_f32_16x16x32_bf16 v[92:95], v[128:131], v[202:205], v[92:95]
	v_mfma_f32_16x16x32_bf16 v[88:91], v[136:139], v[202:205], v[88:91]
	v_mfma_f32_16x16x32_bf16 v[76:79], v[128:131], v[214:217], v[76:79]
	v_mfma_f32_16x16x32_bf16 v[72:75], v[136:139], v[214:217], v[72:75]
	v_mfma_f32_16x16x32_bf16 v[124:127], v[132:135], v[180:183], v[124:127]
	v_mfma_f32_16x16x32_bf16 v[120:123], v[140:143], v[180:183], v[120:123]
	v_mfma_f32_16x16x32_bf16 v[108:111], v[132:135], v[198:201], v[108:111]
	v_mfma_f32_16x16x32_bf16 v[104:107], v[140:143], v[198:201], v[104:107]
	v_mfma_f32_16x16x32_bf16 v[92:95], v[132:135], v[210:213], v[92:95]
	v_mfma_f32_16x16x32_bf16 v[88:91], v[140:143], v[210:213], v[88:91]
	v_mfma_f32_16x16x32_bf16 v[76:79], v[132:135], v[218:221], v[76:79]
	v_mfma_f32_16x16x32_bf16 v[72:75], v[140:143], v[218:221], v[72:75]
	s_setprio 0
	s_setprio 1
	v_mfma_f32_16x16x32_bf16 v[116:119], v[144:147], v[176:179], v[116:119]
	v_mfma_f32_16x16x32_bf16 v[112:115], v[168:171], v[176:179], v[112:115]
	v_mfma_f32_16x16x32_bf16 v[100:103], v[144:147], v[194:197], v[100:103]
	v_mfma_f32_16x16x32_bf16 v[96:99], v[168:171], v[194:197], v[96:99]
	v_mfma_f32_16x16x32_bf16 v[84:87], v[144:147], v[202:205], v[84:87]
	v_mfma_f32_16x16x32_bf16 v[80:83], v[168:171], v[202:205], v[80:83]
	v_mfma_f32_16x16x32_bf16 v[68:71], v[144:147], v[214:217], v[68:71]
	v_mfma_f32_16x16x32_bf16 v[64:67], v[168:171], v[214:217], v[64:67]
	v_mfma_f32_16x16x32_bf16 v[116:119], v[148:151], v[180:183], v[116:119]
	v_mfma_f32_16x16x32_bf16 v[112:115], v[172:175], v[180:183], v[112:115]
	v_mfma_f32_16x16x32_bf16 v[100:103], v[148:151], v[198:201], v[100:103]
	v_mfma_f32_16x16x32_bf16 v[96:99], v[172:175], v[198:201], v[96:99]
	v_mfma_f32_16x16x32_bf16 v[84:87], v[148:151], v[210:213], v[84:87]
	v_mfma_f32_16x16x32_bf16 v[80:83], v[172:175], v[210:213], v[80:83]
	v_mfma_f32_16x16x32_bf16 v[68:71], v[148:151], v[218:221], v[68:71]
	v_mfma_f32_16x16x32_bf16 v[64:67], v[172:175], v[218:221], v[64:67]
	s_setprio 0
	s_barrier
	s_add_i32 s24, s47, s36
	v_lshl_add_u64 v[184:185], s[28:29], 0, v[154:155]
	s_mov_b32 m0, s24
	ds_read_b128 v[176:179], v191 offset:16384
	ds_read_b128 v[180:183], v191 offset:17408
	ds_read_b128 v[194:197], v191 offset:18432
	ds_read_b128 v[198:201], v191 offset:19456
	ds_read_b128 v[202:205], v191 offset:20480
	ds_read_b128 v[210:213], v191 offset:21504
	ds_read_b128 v[214:217], v191 offset:22528
	ds_read_b128 v[218:221], v191 offset:23552
	global_load_lds_dwordx4 v[184:185], off
	s_add_i32 m0, s24, 0x2000
	s_add_u32 s24, s28, 0xb0000
	v_lshl_add_u64 v[206:207], s[28:29], 0, v[158:159]
	s_addc_u32 s25, s29, 0
	s_add_i32 s56, s48, s36
	global_load_lds_dwordx4 v[206:207], off
	v_lshl_add_u64 v[222:223], s[24:25], 0, v[154:155]
	s_mov_b32 m0, s56
	v_lshl_add_u64 v[224:225], s[30:31], 0, v[156:157]
	global_load_lds_dwordx4 v[222:223], off
	v_lshl_add_u64 v[222:223], s[24:25], 0, v[158:159]
	s_add_i32 m0, s56, 0x2000
	s_nop 0
	global_load_lds_dwordx4 v[222:223], off
	v_lshl_add_u64 v[222:223], s[30:31], 0, v[152:153]
	s_mov_b32 m0, s37
	s_nop 0
	global_load_lds_dwordx4 v[222:223], off
	s_mov_b32 m0, s38
	s_nop 0
	global_load_lds_dwordx4 v[224:225], off
	s_waitcnt vmcnt(24)
	s_waitcnt lgkmcnt(0)
	s_barrier
	s_setprio 1
	s_waitcnt lgkmcnt(0)
	v_mfma_f32_16x16x32_bf16 v[60:63], v[128:131], v[176:179], v[60:63]
	v_mfma_f32_16x16x32_bf16 v[56:59], v[136:139], v[176:179], v[56:59]
	v_mfma_f32_16x16x32_bf16 v[44:47], v[128:131], v[194:197], v[44:47]
	v_mfma_f32_16x16x32_bf16 v[40:43], v[136:139], v[194:197], v[40:43]
	v_mfma_f32_16x16x32_bf16 v[28:31], v[128:131], v[202:205], v[28:31]
	v_mfma_f32_16x16x32_bf16 v[24:27], v[136:139], v[202:205], v[24:27]
	v_mfma_f32_16x16x32_bf16 v[12:15], v[128:131], v[214:217], v[12:15]
	v_mfma_f32_16x16x32_bf16 v[8:11], v[136:139], v[214:217], v[8:11]
	v_mfma_f32_16x16x32_bf16 v[60:63], v[132:135], v[180:183], v[60:63]
	v_mfma_f32_16x16x32_bf16 v[56:59], v[140:143], v[180:183], v[56:59]
	v_mfma_f32_16x16x32_bf16 v[44:47], v[132:135], v[198:201], v[44:47]
	v_mfma_f32_16x16x32_bf16 v[40:43], v[140:143], v[198:201], v[40:43]
	v_mfma_f32_16x16x32_bf16 v[28:31], v[132:135], v[210:213], v[28:31]
	v_mfma_f32_16x16x32_bf16 v[24:27], v[140:143], v[210:213], v[24:27]
	v_mfma_f32_16x16x32_bf16 v[12:15], v[132:135], v[218:221], v[12:15]
	v_mfma_f32_16x16x32_bf16 v[8:11], v[140:143], v[218:221], v[8:11]
	s_setprio 0
	s_setprio 1
	v_mfma_f32_16x16x32_bf16 v[52:55], v[144:147], v[176:179], v[52:55]
	v_mfma_f32_16x16x32_bf16 v[48:51], v[168:171], v[176:179], v[48:51]
	v_mfma_f32_16x16x32_bf16 v[36:39], v[144:147], v[194:197], v[36:39]
	v_mfma_f32_16x16x32_bf16 v[32:35], v[168:171], v[194:197], v[32:35]
	v_mfma_f32_16x16x32_bf16 v[20:23], v[144:147], v[202:205], v[20:23]
	v_mfma_f32_16x16x32_bf16 v[16:19], v[168:171], v[202:205], v[16:19]
	v_mfma_f32_16x16x32_bf16 v[4:7], v[144:147], v[214:217], v[4:7]
	v_mfma_f32_16x16x32_bf16 v[0:3], v[168:171], v[214:217], v[0:3]
	v_mfma_f32_16x16x32_bf16 v[52:55], v[148:151], v[180:183], v[52:55]
	v_mfma_f32_16x16x32_bf16 v[48:51], v[172:175], v[180:183], v[48:51]
	v_mfma_f32_16x16x32_bf16 v[36:39], v[148:151], v[198:201], v[36:39]
	v_mfma_f32_16x16x32_bf16 v[32:35], v[172:175], v[198:201], v[32:35]
	v_mfma_f32_16x16x32_bf16 v[20:23], v[148:151], v[210:213], v[20:23]
	v_mfma_f32_16x16x32_bf16 v[16:19], v[172:175], v[210:213], v[16:19]
	v_mfma_f32_16x16x32_bf16 v[4:7], v[148:151], v[218:221], v[4:7]
	v_mfma_f32_16x16x32_bf16 v[0:3], v[172:175], v[218:221], v[0:3]
	s_setprio 0
	s_barrier
	s_add_i32 s56, 0, 0x18000
	s_add_i32 s57, 0, 0x1c000
	v_add_u32_e32 v140, s56, v187
	v_add_u32_e32 v172, s57, v187
	ds_read_b128 v[128:131], v140
	ds_read_b128 v[132:135], v140 offset:1024
	ds_read_b128 v[136:139], v140 offset:2048
	ds_read_b128 v[140:143], v140 offset:3072
	ds_read_b128 v[144:147], v172
	ds_read_b128 v[148:151], v172 offset:1024
	ds_read_b128 v[168:171], v172 offset:2048
	ds_read_b128 v[172:175], v172 offset:3072
	s_add_u32 s24, s30, 0xb0000
	s_addc_u32 s25, s31, 0
	s_mov_b32 m0, s39
	v_lshl_add_u64 v[226:227], s[24:25], 0, v[152:153]
	ds_read_b128 v[176:179], v191 offset:32768
	ds_read_b128 v[180:183], v191 offset:33792
	ds_read_b128 v[194:197], v191 offset:34816
	ds_read_b128 v[198:201], v191 offset:35840
	ds_read_b128 v[202:205], v191 offset:36864
	ds_read_b128 v[210:213], v191 offset:37888
	ds_read_b128 v[214:217], v191 offset:38912
	ds_read_b128 v[218:221], v191 offset:39936
	global_load_lds_dwordx4 v[226:227], off
	v_lshl_add_u64 v[226:227], s[24:25], 0, v[156:157]
	s_mov_b32 m0, s40
	s_nop 0
	global_load_lds_dwordx4 v[226:227], off
	s_waitcnt vmcnt(8)
	s_waitcnt lgkmcnt(0)
	s_barrier
	s_setprio 1
	s_waitcnt lgkmcnt(0)
	v_mfma_f32_16x16x32_bf16 v[124:127], v[128:131], v[176:179], v[124:127]
	v_mfma_f32_16x16x32_bf16 v[120:123], v[136:139], v[176:179], v[120:123]
	v_mfma_f32_16x16x32_bf16 v[108:111], v[128:131], v[194:197], v[108:111]
	v_mfma_f32_16x16x32_bf16 v[104:107], v[136:139], v[194:197], v[104:107]
	v_mfma_f32_16x16x32_bf16 v[92:95], v[128:131], v[202:205], v[92:95]
	v_mfma_f32_16x16x32_bf16 v[88:91], v[136:139], v[202:205], v[88:91]
	v_mfma_f32_16x16x32_bf16 v[76:79], v[128:131], v[214:217], v[76:79]
	v_mfma_f32_16x16x32_bf16 v[72:75], v[136:139], v[214:217], v[72:75]
	v_mfma_f32_16x16x32_bf16 v[124:127], v[132:135], v[180:183], v[124:127]
	v_mfma_f32_16x16x32_bf16 v[120:123], v[140:143], v[180:183], v[120:123]
	v_mfma_f32_16x16x32_bf16 v[108:111], v[132:135], v[198:201], v[108:111]
	v_mfma_f32_16x16x32_bf16 v[104:107], v[140:143], v[198:201], v[104:107]
	v_mfma_f32_16x16x32_bf16 v[92:95], v[132:135], v[210:213], v[92:95]
	v_mfma_f32_16x16x32_bf16 v[88:91], v[140:143], v[210:213], v[88:91]
	v_mfma_f32_16x16x32_bf16 v[76:79], v[132:135], v[218:221], v[76:79]
	v_mfma_f32_16x16x32_bf16 v[72:75], v[140:143], v[218:221], v[72:75]
	s_setprio 0
	s_setprio 1
	v_mfma_f32_16x16x32_bf16 v[116:119], v[144:147], v[176:179], v[116:119]
	v_mfma_f32_16x16x32_bf16 v[112:115], v[168:171], v[176:179], v[112:115]
	v_mfma_f32_16x16x32_bf16 v[100:103], v[144:147], v[194:197], v[100:103]
	v_mfma_f32_16x16x32_bf16 v[96:99], v[168:171], v[194:197], v[96:99]
	v_mfma_f32_16x16x32_bf16 v[84:87], v[144:147], v[202:205], v[84:87]
	v_mfma_f32_16x16x32_bf16 v[80:83], v[168:171], v[202:205], v[80:83]
	v_mfma_f32_16x16x32_bf16 v[68:71], v[144:147], v[214:217], v[68:71]
	v_mfma_f32_16x16x32_bf16 v[64:67], v[168:171], v[214:217], v[64:67]
	v_mfma_f32_16x16x32_bf16 v[116:119], v[148:151], v[180:183], v[116:119]
	v_mfma_f32_16x16x32_bf16 v[112:115], v[172:175], v[180:183], v[112:115]
	v_mfma_f32_16x16x32_bf16 v[100:103], v[148:151], v[198:201], v[100:103]
	v_mfma_f32_16x16x32_bf16 v[96:99], v[172:175], v[198:201], v[96:99]
	v_mfma_f32_16x16x32_bf16 v[84:87], v[148:151], v[210:213], v[84:87]
	v_mfma_f32_16x16x32_bf16 v[80:83], v[172:175], v[210:213], v[80:83]
	v_mfma_f32_16x16x32_bf16 v[68:71], v[148:151], v[218:221], v[68:71]
	v_mfma_f32_16x16x32_bf16 v[64:67], v[172:175], v[218:221], v[64:67]
	s_setprio 0
	s_barrier
	s_add_i32 s24, s56, s36
	v_lshl_add_u64 v[184:185], v[184:185], 0, s[18:19]
	s_mov_b32 m0, s24
	ds_read_b128 v[176:179], v191 offset:49152
	ds_read_b128 v[180:183], v191 offset:50176
	ds_read_b128 v[194:197], v191 offset:51200
	ds_read_b128 v[198:201], v191 offset:52224
	ds_read_b128 v[202:205], v191 offset:53248
	ds_read_b128 v[210:213], v191 offset:54272
	ds_read_b128 v[214:217], v191 offset:55296
	ds_read_b128 v[218:221], v191 offset:56320
	global_load_lds_dwordx4 v[184:185], off
	s_add_i32 m0, s24, 0x2000
	s_add_u32 s24, s28, 0xb0080
	v_lshl_add_u64 v[184:185], v[206:207], 0, s[18:19]
	s_addc_u32 s25, s29, 0
	s_add_i32 s28, s57, s36
	global_load_lds_dwordx4 v[184:185], off
	v_lshl_add_u64 v[184:185], s[24:25], 0, v[154:155]
	s_mov_b32 m0, s28
	s_nop 0
	global_load_lds_dwordx4 v[184:185], off
	v_lshl_add_u64 v[184:185], s[24:25], 0, v[158:159]
	s_add_i32 m0, s28, 0x2000
	s_nop 0
	global_load_lds_dwordx4 v[184:185], off
	v_lshl_add_u64 v[184:185], v[222:223], 0, s[18:19]
	s_mov_b32 m0, s42
	s_nop 0
	global_load_lds_dwordx4 v[184:185], off
	v_lshl_add_u64 v[184:185], v[224:225], 0, s[18:19]
	s_mov_b32 m0, s43
	s_nop 0
	global_load_lds_dwordx4 v[184:185], off
	s_waitcnt vmcnt(8)
	s_waitcnt lgkmcnt(0)
	s_barrier
	s_setprio 1
	s_waitcnt lgkmcnt(0)
	v_mfma_f32_16x16x32_bf16 v[60:63], v[128:131], v[176:179], v[60:63]
	v_mfma_f32_16x16x32_bf16 v[56:59], v[136:139], v[176:179], v[56:59]
	v_mfma_f32_16x16x32_bf16 v[44:47], v[128:131], v[194:197], v[44:47]
	v_mfma_f32_16x16x32_bf16 v[40:43], v[136:139], v[194:197], v[40:43]
	v_mfma_f32_16x16x32_bf16 v[28:31], v[128:131], v[202:205], v[28:31]
	v_mfma_f32_16x16x32_bf16 v[24:27], v[136:139], v[202:205], v[24:27]
	v_mfma_f32_16x16x32_bf16 v[12:15], v[128:131], v[214:217], v[12:15]
	v_mfma_f32_16x16x32_bf16 v[8:11], v[136:139], v[214:217], v[8:11]
	v_mfma_f32_16x16x32_bf16 v[60:63], v[132:135], v[180:183], v[60:63]
	v_mfma_f32_16x16x32_bf16 v[56:59], v[140:143], v[180:183], v[56:59]
	v_mfma_f32_16x16x32_bf16 v[44:47], v[132:135], v[198:201], v[44:47]
	v_mfma_f32_16x16x32_bf16 v[40:43], v[140:143], v[198:201], v[40:43]
	v_mfma_f32_16x16x32_bf16 v[28:31], v[132:135], v[210:213], v[28:31]
	v_mfma_f32_16x16x32_bf16 v[24:27], v[140:143], v[210:213], v[24:27]
	v_mfma_f32_16x16x32_bf16 v[12:15], v[132:135], v[218:221], v[12:15]
	v_mfma_f32_16x16x32_bf16 v[8:11], v[140:143], v[218:221], v[8:11]
	s_setprio 0
	s_setprio 1
	v_mfma_f32_16x16x32_bf16 v[52:55], v[144:147], v[176:179], v[52:55]
	v_mfma_f32_16x16x32_bf16 v[48:51], v[168:171], v[176:179], v[48:51]
	v_mfma_f32_16x16x32_bf16 v[36:39], v[144:147], v[194:197], v[36:39]
	v_mfma_f32_16x16x32_bf16 v[32:35], v[168:171], v[194:197], v[32:35]
	v_mfma_f32_16x16x32_bf16 v[20:23], v[144:147], v[202:205], v[20:23]
	v_mfma_f32_16x16x32_bf16 v[16:19], v[168:171], v[202:205], v[16:19]
	v_mfma_f32_16x16x32_bf16 v[4:7], v[144:147], v[214:217], v[4:7]
	v_mfma_f32_16x16x32_bf16 v[0:3], v[168:171], v[214:217], v[0:3]
	v_mfma_f32_16x16x32_bf16 v[52:55], v[148:151], v[180:183], v[52:55]
	v_mfma_f32_16x16x32_bf16 v[48:51], v[172:175], v[180:183], v[48:51]
	v_mfma_f32_16x16x32_bf16 v[36:39], v[148:151], v[198:201], v[36:39]
	v_mfma_f32_16x16x32_bf16 v[32:35], v[172:175], v[198:201], v[32:35]
	v_mfma_f32_16x16x32_bf16 v[20:23], v[148:151], v[210:213], v[20:23]
	v_mfma_f32_16x16x32_bf16 v[16:19], v[172:175], v[210:213], v[16:19]
	v_mfma_f32_16x16x32_bf16 v[4:7], v[148:151], v[218:221], v[4:7]
	v_mfma_f32_16x16x32_bf16 v[0:3], v[172:175], v[218:221], v[0:3]
	s_setprio 0
	s_barrier
	s_add_i32 s55, s55, 2
	s_add_u32 s53, s53, 0x100
	s_addc_u32 s54, s54, 0
	s_cmp_gt_u32 s55, 41
	s_mov_b64 s[24:25], s[26:27]
	s_cbranch_scc0 .LBB0_1210
.LBB0_1210:
	ds_read_b128 v[128:131], v189
	ds_read_b128 v[132:135], v189 offset:1024
	ds_read_b128 v[136:139], v189 offset:2048
	ds_read_b128 v[140:143], v189 offset:3072
	ds_read_b128 v[144:147], v190
	ds_read_b128 v[148:151], v190 offset:1024
	ds_read_b128 v[168:171], v190 offset:2048
	ds_read_b128 v[172:175], v190 offset:3072
	s_add_u32 s26, s24, 0x100
	s_addc_u32 s27, s25, 0
	s_cmp_eq_u32 s55, 40
	s_cselect_b32 s31, s5, s27
	s_cselect_b32 s30, s4, s26
	s_cselect_b32 s29, s23, s54
	s_cselect_b32 s28, s22, s53
	v_lshl_add_u64 v[184:185], s[24:25], 0, v[160:161]
	s_add_i32 m0, s37, 0xc000
	ds_read_b128 v[176:179], v191
	ds_read_b128 v[180:183], v191 offset:1024
	ds_read_b128 v[194:197], v191 offset:2048
	ds_read_b128 v[198:201], v191 offset:3072
	ds_read_b128 v[202:205], v191 offset:4096
	ds_read_b128 v[210:213], v191 offset:5120
	ds_read_b128 v[214:217], v191 offset:6144
	ds_read_b128 v[218:221], v191 offset:7168
	global_load_lds_dwordx4 v[184:185], off
	v_lshl_add_u64 v[184:185], s[24:25], 0, v[162:163]
	s_add_i32 m0, s37, 0xe000
	s_nop 0
	global_load_lds_dwordx4 v[184:185], off
	s_waitcnt vmcnt(8)
	s_waitcnt lgkmcnt(0)
	s_barrier
	s_setprio 1
	s_waitcnt lgkmcnt(0)
	v_mfma_f32_16x16x32_bf16 v[124:127], v[128:131], v[176:179], v[124:127]
	v_mfma_f32_16x16x32_bf16 v[120:123], v[136:139], v[176:179], v[120:123]
	v_mfma_f32_16x16x32_bf16 v[108:111], v[128:131], v[194:197], v[108:111]
	v_mfma_f32_16x16x32_bf16 v[104:107], v[136:139], v[194:197], v[104:107]
	v_mfma_f32_16x16x32_bf16 v[92:95], v[128:131], v[202:205], v[92:95]
	v_mfma_f32_16x16x32_bf16 v[88:91], v[136:139], v[202:205], v[88:91]
	v_mfma_f32_16x16x32_bf16 v[76:79], v[128:131], v[214:217], v[76:79]
	v_mfma_f32_16x16x32_bf16 v[72:75], v[136:139], v[214:217], v[72:75]
	v_mfma_f32_16x16x32_bf16 v[124:127], v[132:135], v[180:183], v[124:127]
	v_mfma_f32_16x16x32_bf16 v[120:123], v[140:143], v[180:183], v[120:123]
	v_mfma_f32_16x16x32_bf16 v[108:111], v[132:135], v[198:201], v[108:111]
	v_mfma_f32_16x16x32_bf16 v[104:107], v[140:143], v[198:201], v[104:107]
	v_mfma_f32_16x16x32_bf16 v[92:95], v[132:135], v[210:213], v[92:95]
	v_mfma_f32_16x16x32_bf16 v[88:91], v[140:143], v[210:213], v[88:91]
	v_mfma_f32_16x16x32_bf16 v[76:79], v[132:135], v[218:221], v[76:79]
	v_mfma_f32_16x16x32_bf16 v[72:75], v[140:143], v[218:221], v[72:75]
	s_setprio 0
	s_setprio 1
	v_mfma_f32_16x16x32_bf16 v[116:119], v[144:147], v[176:179], v[116:119]
	v_mfma_f32_16x16x32_bf16 v[112:115], v[168:171], v[176:179], v[112:115]
	v_mfma_f32_16x16x32_bf16 v[100:103], v[144:147], v[194:197], v[100:103]
	v_mfma_f32_16x16x32_bf16 v[96:99], v[168:171], v[194:197], v[96:99]
	v_mfma_f32_16x16x32_bf16 v[84:87], v[144:147], v[202:205], v[84:87]
	v_mfma_f32_16x16x32_bf16 v[80:83], v[168:171], v[202:205], v[80:83]
	v_mfma_f32_16x16x32_bf16 v[68:71], v[144:147], v[214:217], v[68:71]
	v_mfma_f32_16x16x32_bf16 v[64:67], v[168:171], v[214:217], v[64:67]
	v_mfma_f32_16x16x32_bf16 v[116:119], v[148:151], v[180:183], v[116:119]
	v_mfma_f32_16x16x32_bf16 v[112:115], v[172:175], v[180:183], v[112:115]
	v_mfma_f32_16x16x32_bf16 v[100:103], v[148:151], v[198:201], v[100:103]
	v_mfma_f32_16x16x32_bf16 v[96:99], v[172:175], v[198:201], v[96:99]
	v_mfma_f32_16x16x32_bf16 v[84:87], v[148:151], v[210:213], v[84:87]
	v_mfma_f32_16x16x32_bf16 v[80:83], v[172:175], v[210:213], v[80:83]
	v_mfma_f32_16x16x32_bf16 v[68:71], v[148:151], v[218:221], v[68:71]
	v_mfma_f32_16x16x32_bf16 v[64:67], v[172:175], v[218:221], v[64:67]
	s_setprio 0
	s_barrier
	s_add_i32 s24, s47, s36
	v_lshl_add_u64 v[184:185], s[28:29], 0, v[154:155]
	s_mov_b32 m0, s24
	ds_read_b128 v[176:179], v191 offset:16384
	ds_read_b128 v[180:183], v191 offset:17408
	ds_read_b128 v[194:197], v191 offset:18432
	ds_read_b128 v[198:201], v191 offset:19456
	ds_read_b128 v[202:205], v191 offset:20480
	ds_read_b128 v[210:213], v191 offset:21504
	ds_read_b128 v[214:217], v191 offset:22528
	ds_read_b128 v[218:221], v191 offset:23552
	global_load_lds_dwordx4 v[184:185], off
	s_add_i32 m0, s24, 0x2000
	s_add_u32 s24, s28, 0xb0000
	v_lshl_add_u64 v[206:207], s[28:29], 0, v[158:159]
	s_addc_u32 s25, s29, 0
	s_add_i32 s56, s48, s36
	global_load_lds_dwordx4 v[206:207], off
	v_lshl_add_u64 v[222:223], s[24:25], 0, v[154:155]
	s_mov_b32 m0, s56
	v_lshl_add_u64 v[224:225], s[30:31], 0, v[156:157]
	global_load_lds_dwordx4 v[222:223], off
	v_lshl_add_u64 v[222:223], s[24:25], 0, v[158:159]
	s_add_i32 m0, s56, 0x2000
	s_nop 0
	global_load_lds_dwordx4 v[222:223], off
	v_lshl_add_u64 v[222:223], s[30:31], 0, v[152:153]
	s_mov_b32 m0, s37
	s_nop 0
	global_load_lds_dwordx4 v[222:223], off
	s_mov_b32 m0, s38
	s_nop 0
	global_load_lds_dwordx4 v[224:225], off
	s_waitcnt vmcnt(8)
	s_waitcnt lgkmcnt(0)
	s_barrier
	s_setprio 1
	s_waitcnt lgkmcnt(0)
	v_mfma_f32_16x16x32_bf16 v[60:63], v[128:131], v[176:179], v[60:63]
	v_mfma_f32_16x16x32_bf16 v[56:59], v[136:139], v[176:179], v[56:59]
	v_mfma_f32_16x16x32_bf16 v[44:47], v[128:131], v[194:197], v[44:47]
	v_mfma_f32_16x16x32_bf16 v[40:43], v[136:139], v[194:197], v[40:43]
	v_mfma_f32_16x16x32_bf16 v[28:31], v[128:131], v[202:205], v[28:31]
	v_mfma_f32_16x16x32_bf16 v[24:27], v[136:139], v[202:205], v[24:27]
	v_mfma_f32_16x16x32_bf16 v[12:15], v[128:131], v[214:217], v[12:15]
	v_mfma_f32_16x16x32_bf16 v[8:11], v[136:139], v[214:217], v[8:11]
	v_mfma_f32_16x16x32_bf16 v[60:63], v[132:135], v[180:183], v[60:63]
	v_mfma_f32_16x16x32_bf16 v[56:59], v[140:143], v[180:183], v[56:59]
	v_mfma_f32_16x16x32_bf16 v[44:47], v[132:135], v[198:201], v[44:47]
	v_mfma_f32_16x16x32_bf16 v[40:43], v[140:143], v[198:201], v[40:43]
	v_mfma_f32_16x16x32_bf16 v[28:31], v[132:135], v[210:213], v[28:31]
	v_mfma_f32_16x16x32_bf16 v[24:27], v[140:143], v[210:213], v[24:27]
	v_mfma_f32_16x16x32_bf16 v[12:15], v[132:135], v[218:221], v[12:15]
	v_mfma_f32_16x16x32_bf16 v[8:11], v[140:143], v[218:221], v[8:11]
	s_setprio 0
	s_setprio 1
	v_mfma_f32_16x16x32_bf16 v[52:55], v[144:147], v[176:179], v[52:55]
	v_mfma_f32_16x16x32_bf16 v[48:51], v[168:171], v[176:179], v[48:51]
	v_mfma_f32_16x16x32_bf16 v[36:39], v[144:147], v[194:197], v[36:39]
	v_mfma_f32_16x16x32_bf16 v[32:35], v[168:171], v[194:197], v[32:35]
	v_mfma_f32_16x16x32_bf16 v[20:23], v[144:147], v[202:205], v[20:23]
	v_mfma_f32_16x16x32_bf16 v[16:19], v[168:171], v[202:205], v[16:19]
	v_mfma_f32_16x16x32_bf16 v[4:7], v[144:147], v[214:217], v[4:7]
	v_mfma_f32_16x16x32_bf16 v[0:3], v[168:171], v[214:217], v[0:3]
	v_mfma_f32_16x16x32_bf16 v[52:55], v[148:151], v[180:183], v[52:55]
	v_mfma_f32_16x16x32_bf16 v[48:51], v[172:175], v[180:183], v[48:51]
	v_mfma_f32_16x16x32_bf16 v[36:39], v[148:151], v[198:201], v[36:39]
	v_mfma_f32_16x16x32_bf16 v[32:35], v[172:175], v[198:201], v[32:35]
	v_mfma_f32_16x16x32_bf16 v[20:23], v[148:151], v[210:213], v[20:23]
	v_mfma_f32_16x16x32_bf16 v[16:19], v[172:175], v[210:213], v[16:19]
	v_mfma_f32_16x16x32_bf16 v[4:7], v[148:151], v[218:221], v[4:7]
	v_mfma_f32_16x16x32_bf16 v[0:3], v[172:175], v[218:221], v[0:3]
	s_setprio 0
	s_barrier
	s_add_i32 s56, 0, 0x18000
	s_add_i32 s57, 0, 0x1c000
	v_add_u32_e32 v140, s56, v187
	v_add_u32_e32 v172, s57, v187
	ds_read_b128 v[128:131], v140
	ds_read_b128 v[132:135], v140 offset:1024
	ds_read_b128 v[136:139], v140 offset:2048
	ds_read_b128 v[140:143], v140 offset:3072
	ds_read_b128 v[144:147], v172
	ds_read_b128 v[148:151], v172 offset:1024
	ds_read_b128 v[168:171], v172 offset:2048
	ds_read_b128 v[172:175], v172 offset:3072
	s_add_u32 s24, s30, 0xb0000
	s_addc_u32 s25, s31, 0
	s_mov_b32 m0, s39
	v_lshl_add_u64 v[226:227], s[24:25], 0, v[152:153]
	ds_read_b128 v[176:179], v191 offset:32768
	ds_read_b128 v[180:183], v191 offset:33792
	ds_read_b128 v[194:197], v191 offset:34816
	ds_read_b128 v[198:201], v191 offset:35840
	ds_read_b128 v[202:205], v191 offset:36864
	ds_read_b128 v[210:213], v191 offset:37888
	ds_read_b128 v[214:217], v191 offset:38912
	ds_read_b128 v[218:221], v191 offset:39936
	global_load_lds_dwordx4 v[226:227], off
	v_lshl_add_u64 v[226:227], s[24:25], 0, v[156:157]
	s_mov_b32 m0, s40
	s_nop 0
	global_load_lds_dwordx4 v[226:227], off
	s_waitcnt vmcnt(8)
	s_waitcnt lgkmcnt(0)
	s_barrier
	s_setprio 1
	s_waitcnt lgkmcnt(0)
	v_mfma_f32_16x16x32_bf16 v[124:127], v[128:131], v[176:179], v[124:127]
	v_mfma_f32_16x16x32_bf16 v[120:123], v[136:139], v[176:179], v[120:123]
	v_mfma_f32_16x16x32_bf16 v[108:111], v[128:131], v[194:197], v[108:111]
	v_mfma_f32_16x16x32_bf16 v[104:107], v[136:139], v[194:197], v[104:107]
	v_mfma_f32_16x16x32_bf16 v[92:95], v[128:131], v[202:205], v[92:95]
	v_mfma_f32_16x16x32_bf16 v[88:91], v[136:139], v[202:205], v[88:91]
	v_mfma_f32_16x16x32_bf16 v[76:79], v[128:131], v[214:217], v[76:79]
	v_mfma_f32_16x16x32_bf16 v[72:75], v[136:139], v[214:217], v[72:75]
	v_mfma_f32_16x16x32_bf16 v[124:127], v[132:135], v[180:183], v[124:127]
	v_mfma_f32_16x16x32_bf16 v[120:123], v[140:143], v[180:183], v[120:123]
	v_mfma_f32_16x16x32_bf16 v[108:111], v[132:135], v[198:201], v[108:111]
	v_mfma_f32_16x16x32_bf16 v[104:107], v[140:143], v[198:201], v[104:107]
	v_mfma_f32_16x16x32_bf16 v[92:95], v[132:135], v[210:213], v[92:95]
	v_mfma_f32_16x16x32_bf16 v[88:91], v[140:143], v[210:213], v[88:91]
	v_mfma_f32_16x16x32_bf16 v[76:79], v[132:135], v[218:221], v[76:79]
	v_mfma_f32_16x16x32_bf16 v[72:75], v[140:143], v[218:221], v[72:75]
	s_setprio 0
	s_setprio 1
	v_mfma_f32_16x16x32_bf16 v[116:119], v[144:147], v[176:179], v[116:119]
	v_mfma_f32_16x16x32_bf16 v[112:115], v[168:171], v[176:179], v[112:115]
	v_mfma_f32_16x16x32_bf16 v[100:103], v[144:147], v[194:197], v[100:103]
	v_mfma_f32_16x16x32_bf16 v[96:99], v[168:171], v[194:197], v[96:99]
	v_mfma_f32_16x16x32_bf16 v[84:87], v[144:147], v[202:205], v[84:87]
	v_mfma_f32_16x16x32_bf16 v[80:83], v[168:171], v[202:205], v[80:83]
	v_mfma_f32_16x16x32_bf16 v[68:71], v[144:147], v[214:217], v[68:71]
	v_mfma_f32_16x16x32_bf16 v[64:67], v[168:171], v[214:217], v[64:67]
	v_mfma_f32_16x16x32_bf16 v[116:119], v[148:151], v[180:183], v[116:119]
	v_mfma_f32_16x16x32_bf16 v[112:115], v[172:175], v[180:183], v[112:115]
	v_mfma_f32_16x16x32_bf16 v[100:103], v[148:151], v[198:201], v[100:103]
	v_mfma_f32_16x16x32_bf16 v[96:99], v[172:175], v[198:201], v[96:99]
	v_mfma_f32_16x16x32_bf16 v[84:87], v[148:151], v[210:213], v[84:87]
	v_mfma_f32_16x16x32_bf16 v[80:83], v[172:175], v[210:213], v[80:83]
	v_mfma_f32_16x16x32_bf16 v[68:71], v[148:151], v[218:221], v[68:71]
	v_mfma_f32_16x16x32_bf16 v[64:67], v[172:175], v[218:221], v[64:67]
	s_setprio 0
	s_barrier
	s_add_i32 s24, s56, s36
	v_lshl_add_u64 v[184:185], v[184:185], 0, s[18:19]
	s_mov_b32 m0, s24
	ds_read_b128 v[176:179], v191 offset:49152
	ds_read_b128 v[180:183], v191 offset:50176
	ds_read_b128 v[194:197], v191 offset:51200
	ds_read_b128 v[198:201], v191 offset:52224
	ds_read_b128 v[202:205], v191 offset:53248
	ds_read_b128 v[210:213], v191 offset:54272
	ds_read_b128 v[214:217], v191 offset:55296
	ds_read_b128 v[218:221], v191 offset:56320
	global_load_lds_dwordx4 v[184:185], off
	s_add_i32 m0, s24, 0x2000
	s_add_u32 s24, s28, 0xb0080
	v_lshl_add_u64 v[184:185], v[206:207], 0, s[18:19]
	s_addc_u32 s25, s29, 0
	s_add_i32 s28, s57, s36
	global_load_lds_dwordx4 v[184:185], off
	v_lshl_add_u64 v[184:185], s[24:25], 0, v[154:155]
	s_mov_b32 m0, s28
	s_nop 0
	global_load_lds_dwordx4 v[184:185], off
	v_lshl_add_u64 v[184:185], s[24:25], 0, v[158:159]
	s_add_i32 m0, s28, 0x2000
	s_nop 0
	global_load_lds_dwordx4 v[184:185], off
	v_lshl_add_u64 v[184:185], v[222:223], 0, s[18:19]
	s_mov_b32 m0, s42
	s_nop 0
	global_load_lds_dwordx4 v[184:185], off
	v_lshl_add_u64 v[184:185], v[224:225], 0, s[18:19]
	s_mov_b32 m0, s43
	s_nop 0
	global_load_lds_dwordx4 v[184:185], off
	s_waitcnt vmcnt(8)
	s_waitcnt lgkmcnt(0)
	s_barrier
	s_setprio 1
	s_waitcnt lgkmcnt(0)
	v_mfma_f32_16x16x32_bf16 v[60:63], v[128:131], v[176:179], v[60:63]
	v_mfma_f32_16x16x32_bf16 v[56:59], v[136:139], v[176:179], v[56:59]
	v_mfma_f32_16x16x32_bf16 v[44:47], v[128:131], v[194:197], v[44:47]
	v_mfma_f32_16x16x32_bf16 v[40:43], v[136:139], v[194:197], v[40:43]
	v_mfma_f32_16x16x32_bf16 v[28:31], v[128:131], v[202:205], v[28:31]
	v_mfma_f32_16x16x32_bf16 v[24:27], v[136:139], v[202:205], v[24:27]
	v_mfma_f32_16x16x32_bf16 v[12:15], v[128:131], v[214:217], v[12:15]
	v_mfma_f32_16x16x32_bf16 v[8:11], v[136:139], v[214:217], v[8:11]
	v_mfma_f32_16x16x32_bf16 v[60:63], v[132:135], v[180:183], v[60:63]
	v_mfma_f32_16x16x32_bf16 v[56:59], v[140:143], v[180:183], v[56:59]
	v_mfma_f32_16x16x32_bf16 v[44:47], v[132:135], v[198:201], v[44:47]
	v_mfma_f32_16x16x32_bf16 v[40:43], v[140:143], v[198:201], v[40:43]
	v_mfma_f32_16x16x32_bf16 v[28:31], v[132:135], v[210:213], v[28:31]
	v_mfma_f32_16x16x32_bf16 v[24:27], v[140:143], v[210:213], v[24:27]
	v_mfma_f32_16x16x32_bf16 v[12:15], v[132:135], v[218:221], v[12:15]
	v_mfma_f32_16x16x32_bf16 v[8:11], v[140:143], v[218:221], v[8:11]
	s_setprio 0
	s_setprio 1
	v_mfma_f32_16x16x32_bf16 v[52:55], v[144:147], v[176:179], v[52:55]
	v_mfma_f32_16x16x32_bf16 v[48:51], v[168:171], v[176:179], v[48:51]
	v_mfma_f32_16x16x32_bf16 v[36:39], v[144:147], v[194:197], v[36:39]
	v_mfma_f32_16x16x32_bf16 v[32:35], v[168:171], v[194:197], v[32:35]
	v_mfma_f32_16x16x32_bf16 v[20:23], v[144:147], v[202:205], v[20:23]
	v_mfma_f32_16x16x32_bf16 v[16:19], v[168:171], v[202:205], v[16:19]
	v_mfma_f32_16x16x32_bf16 v[4:7], v[144:147], v[214:217], v[4:7]
	v_mfma_f32_16x16x32_bf16 v[0:3], v[168:171], v[214:217], v[0:3]
	v_mfma_f32_16x16x32_bf16 v[52:55], v[148:151], v[180:183], v[52:55]
	v_mfma_f32_16x16x32_bf16 v[48:51], v[172:175], v[180:183], v[48:51]
	v_mfma_f32_16x16x32_bf16 v[36:39], v[148:151], v[198:201], v[36:39]
	v_mfma_f32_16x16x32_bf16 v[32:35], v[172:175], v[198:201], v[32:35]
	v_mfma_f32_16x16x32_bf16 v[20:23], v[148:151], v[210:213], v[20:23]
	v_mfma_f32_16x16x32_bf16 v[16:19], v[172:175], v[210:213], v[16:19]
	v_mfma_f32_16x16x32_bf16 v[4:7], v[148:151], v[218:221], v[4:7]
	v_mfma_f32_16x16x32_bf16 v[0:3], v[172:175], v[218:221], v[0:3]
	s_setprio 0
	s_barrier
	s_add_i32 s55, s55, 2
	s_add_u32 s53, s53, 0x100
	s_addc_u32 s54, s54, 0
	s_cmp_gt_u32 s55, 41
	s_mov_b64 s[24:25], s[26:27]
	s_cbranch_scc0 .LBB0_1210
	s_mov_b32 s100, 1
	s_and_b64 vcc, exec, s[20:21]
	s_cbranch_vccz .LBB0_1213
	s_barrier
